# v52 with the 16 exp2 of each softmax block issued back to back ahead of the row-sum adds
# baseline (speedup 1.0000x reference)
; #define LAS __attribute__((address_space(3)))
; DI void expsum(f32x16& p, float& l_reg, bf16x8& pa0, bf16x8& pa1) {
; #pragma unroll
;     for (int r = 0; r < 16; ++r) p[r] = __builtin_amdgcn_exp2f(p[r]);
;     float ps = 0.f;
; #pragma unroll
;     for (int r = 0; r < 16; ++r) ps += p[r];
;     l_reg += ps; asm volatile("" : "+v"(l_reg));
;     ...
;     ATT_PK4(p, 0, pa0); ATT_PK4(p, 8, pa1);
;     ...
; }
; DI int v_rd_base(int lane) { return ((lane & 3) << 3) | (((lane >> 2) & 3) << 6) | (((lane >> 4) & 1) << 5) | (((lane >> 5) & 1) << 8); }
; template <int OFF> DI s16x4 tr_read(int vb) { s16x4 r; asm volatile("ds_read_b64_tr_b16 %0, %1 offset:%2" : "=&v"(r) : "v"(vb), "i"(OFF) : "memory"); return r; }
; template <int H> DI void v_reads(s16x4* vf, int vb) {
;     vf[0] = tr_read<v_rd_off(0, 2 * H, 0)>(vb); vf[1] = tr_read<v_rd_off(0, 2 * H, 1)>(vb); vf[2] = tr_read<v_rd_off(0, 2 * H + 1, 0)>(vb); vf[3] = tr_read<v_rd_off(0, 2 * H + 1, 1)>(vb);
;     vf[4] = tr_read<v_rd_off(1, 2 * H, 0)>(vb); vf[5] = tr_read<v_rd_off(1, 2 * H, 1)>(vb); vf[6] = tr_read<v_rd_off(1, 2 * H + 1, 0)>(vb); vf[7] = tr_read<v_rd_off(1, 2 * H + 1, 1)>(vb);
;     vf[8] = tr_read<v_rd_off(2, 2 * H, 0)>(vb); vf[9] = tr_read<v_rd_off(2, 2 * H, 1)>(vb); vf[10] = tr_read<v_rd_off(2, 2 * H + 1, 0)>(vb); vf[11] = tr_read<v_rd_off(2, 2 * H + 1, 1)>(vb);
;     vf[12] = tr_read<v_rd_off(3, 2 * H, 0)>(vb); vf[13] = tr_read<v_rd_off(3, 2 * H, 1)>(vb); vf[14] = tr_read<v_rd_off(3, 2 * H + 1, 0)>(vb); vf[15] = tr_read<v_rd_off(3, 2 * H + 1, 1)>(vb);
; }
; DI void pv_mma(f32x16* o, const s16x4* vf, bf16x8 pa0, bf16x8 pa1) {
;     ...
; #pragma unroll
;     for (int d0 = 0; d0 < 4; ++d0) {
;         o[d0] = __builtin_amdgcn_mfma_f32_32x32x16_bf16(pa0, ATT_PK(vf[4 * d0], vf[4 * d0 + 1]), o[d0], 0, 0, 0);
;         o[d0] = __builtin_amdgcn_mfma_f32_32x32x16_bf16(pa1, ATT_PK(vf[4 * d0 + 2], vf[4 * d0 + 3]), o[d0], 0, 0, 0); }
;     ...
; }
; template <int DQK, int D0A, int D0B> DI void k_reads(bf16x8* kf, const LAS unsigned char* Ks, int half, int r32, int hi) {
; #pragma unroll
;     for (int d0 = D0A; d0 < D0B; ++d0) kf[d0 - D0A] = *(const LAS bf16x8*)(Ks + half * (32 * DQK * 2) + kswz<DQK>(r32, (d0 * 16 + hi * 8) * 2));
; }
; template <int D0A, int D0B> DI void qk_mma(f32x16& p, const bf16x8* kf, const bf16x8* qr) {
; #pragma unroll
;     for (int d0 = D0A; d0 < D0B; ++d0) {
.LBB0_1922:
	s_add_i32 s3, s0, -1
	s_add_i32 s2, s22, 0xffffa000
	s_and_b32 s2, s2, 0x6000
	v_add_u32_e32 v121, s2, v114
	v_add_u32_e32 v122, v121, v115
	v_add_u32_e32 v126, v121, v116
	ds_read_b128 v[122:125], v122 offset:4096
	ds_read_b128 v[132:135], v126 offset:4096
	v_add_u32_e32 v126, v121, v117
	v_add_u32_e32 v121, v121, v118
	s_lshl_b32 s2, s1, 14
	ds_read_b128 v[136:139], v126 offset:4096
	ds_read_b128 v[140:143], v121 offset:4096
	v_add_u32_e32 v121, s2, v106
	ds_read_b64_tr_b16 v[144:145], v121 offset:0
	ds_read_b64_tr_b16 v[146:147], v121 offset:0x800
	ds_read_b64_tr_b16 v[148:149], v121 offset:0x1000
	ds_read_b64_tr_b16 v[150:151], v121 offset:0x1800
	ds_read_b64_tr_b16 v[152:153], v121 offset:0x200
	ds_read_b64_tr_b16 v[154:155], v121 offset:0xa00
	ds_read_b64_tr_b16 v[156:157], v121 offset:0x1200
	ds_read_b64_tr_b16 v[158:159], v121 offset:0x1a00
	ds_read_b64_tr_b16 v[162:163], v121 offset:0x400
	ds_read_b64_tr_b16 v[164:165], v121 offset:0xc00
	ds_read_b64_tr_b16 v[166:167], v121 offset:0x1400
	ds_read_b64_tr_b16 v[168:169], v121 offset:0x1c00
	ds_read_b64_tr_b16 v[170:171], v121 offset:0x600
	ds_read_b64_tr_b16 v[172:173], v121 offset:0xe00
	ds_read_b64_tr_b16 v[174:175], v121 offset:0x1600
	ds_read_b64_tr_b16 v[176:177], v121 offset:0x1e00
	s_setprio 2
	v_exp_f32_e32 v64, v64
	v_exp_f32_e32 v65, v65
	v_exp_f32_e32 v66, v66
	v_exp_f32_e32 v67, v67
	v_exp_f32_e32 v68, v68
	v_exp_f32_e32 v69, v69
	v_exp_f32_e32 v70, v70
	v_exp_f32_e32 v71, v71
	v_exp_f32_e32 v72, v72
	v_exp_f32_e32 v73, v73
	v_exp_f32_e32 v74, v74
	v_exp_f32_e32 v75, v75
	v_exp_f32_e32 v76, v76
	v_exp_f32_e32 v77, v77
	v_exp_f32_e32 v78, v78
	v_exp_f32_e32 v79, v79
	v_add_f32_e32 v126, v65, v64
	v_add_f32_e32 v126, v66, v126
	v_add_f32_e32 v126, v67, v126
	v_add_f32_e32 v126, v68, v126
	v_add_f32_e32 v126, v69, v126
	v_add_f32_e32 v126, v70, v126
	v_add_f32_e32 v126, v71, v126
	v_add_f32_e32 v126, v72, v126
	v_add_f32_e32 v126, v73, v126
	v_add_f32_e32 v126, v74, v126
	v_add_f32_e32 v126, v75, v126
	v_add_f32_e32 v126, v76, v126
	v_add_f32_e32 v126, v77, v126
	v_add_f32_e32 v126, v78, v126
	v_add_f32_e32 v126, v79, v126
	v_add_f32_e32 v120, v126, v120
	v_cvt_pk_bf16_f32 v64, v64, v65
	v_cvt_pk_bf16_f32 v65, v66, v67
	v_cvt_pk_bf16_f32 v66, v68, v69
	v_cvt_pk_bf16_f32 v67, v70, v71
	v_cvt_pk_bf16_f32 v68, v72, v73
	v_cvt_pk_bf16_f32 v69, v74, v75
	v_cvt_pk_bf16_f32 v70, v76, v77
	v_cvt_pk_bf16_f32 v71, v78, v79
	s_nop 0
	v_permlane32_swap_b32_e32 v64, v66
	v_permlane32_swap_b32_e32 v65, v67
	v_permlane32_swap_b32_e32 v68, v70
	v_permlane32_swap_b32_e32 v69, v71
	s_waitcnt lgkmcnt(0)
	s_setprio 1
	v_mfma_f32_32x32x16_bf16 v[0:15], v[64:67], v[144:147], v[0:15]
	s_cmp_lt_i32 s3, s55
	s_cselect_b64 vcc, -1, 0
	s_cmp_ge_i32 s3, s97
	s_cselect_b64 s[74:75], -1, 0
	s_or_b64 s[74:75], vcc, s[74:75]
	s_and_b64 vcc, exec, s[74:75]
	v_mfma_f32_32x32x16_bf16 v[48:63], v[64:67], v[152:155], v[48:63]
	v_mfma_f32_32x32x16_bf16 v[32:47], v[64:67], v[162:165], v[32:47]
	v_mfma_f32_32x32x16_bf16 v[16:31], v[64:67], v[170:173], v[16:31]
	v_mfma_f32_32x32x16_bf16 v[0:15], v[68:71], v[148:151], v[0:15]
	v_mfma_f32_32x32x16_bf16 v[48:63], v[68:71], v[156:159], v[48:63]
	v_mfma_f32_32x32x16_bf16 v[32:47], v[68:71], v[166:169], v[32:47]
	v_mfma_f32_32x32x16_bf16 v[16:31], v[68:71], v[174:177], v[16:31]
	v_mfma_f32_32x32x16_bf16 v[64:79], v[122:125], v[92:95], 0
	v_mfma_f32_32x32x16_bf16 v[64:79], v[132:135], v[88:91], v[64:79]
	v_mfma_f32_32x32x16_bf16 v[64:79], v[136:139], v[84:87], v[64:79]
	v_mfma_f32_32x32x16_bf16 v[64:79], v[140:143], v[80:83], v[64:79]
	s_setprio 0
	v_add_u32_e32 v122, s7, v119
	s_cbranch_vccnz .LBB0_1924
	v_add_u32_e32 v138, 0x28908, v122
	v_add_u32_e32 v140, 0x28920, v122
	v_add_u32_e32 v142, 0x28928, v122
	v_add_u32_e32 v124, 0x28940, v122
	v_add_u32_e32 v126, 0x28948, v122
	v_add_u32_e32 v132, 0x28960, v122
	v_add_u32_e32 v134, 0x28968, v122
	v_add_u32_e32 v123, 0x28900, v122
	ds_read2_b32 v[124:125], v124 offset1:1
	ds_read2_b32 v[126:127], v126 offset1:1
	ds_read2_b32 v[132:133], v132 offset1:1
	ds_read2_b32 v[134:135], v134 offset1:1
	ds_read2_b32 v[136:137], v123 offset1:1
	ds_read2_b32 v[138:139], v138 offset1:1
	ds_read2_b32 v[140:141], v140 offset1:1
	ds_read2_b32 v[142:143], v142 offset1:1
	s_waitcnt lgkmcnt(0)
	v_pk_add_f32 v[78:79], v[78:79], v[134:135]
	v_pk_add_f32 v[76:77], v[76:77], v[132:133]
	v_pk_add_f32 v[74:75], v[74:75], v[126:127]
	v_pk_add_f32 v[72:73], v[72:73], v[124:125]
	v_pk_add_f32 v[70:71], v[70:71], v[142:143]
	v_pk_add_f32 v[68:69], v[68:69], v[140:141]
	v_pk_add_f32 v[66:67], v[66:67], v[138:139]
	v_pk_add_f32 v[64:65], v[64:65], v[136:137]
; DI void expsum(f32x16& p, float& l_reg, bf16x8& pa0, bf16x8& pa1) {
; #pragma unroll
;     for (int r = 0; r < 16; ++r) p[r] = __builtin_amdgcn_exp2f(p[r]);
;     float ps = 0.f;
; #pragma unroll
;     for (int r = 0; r < 16; ++r) ps += p[r];
;     l_reg += ps; asm volatile("" : "+v"(l_reg));
;     ...
;     ATT_PK4(p, 0, pa0); ATT_PK4(p, 8, pa1);
;     ...
; }
; DI int v_rd_base(int lane) { return ((lane & 3) << 3) | (((lane >> 2) & 3) << 6) | (((lane >> 4) & 1) << 5) | (((lane >> 5) & 1) << 8); }
; template <int OFF> DI s16x4 tr_read(int vb) { s16x4 r; asm volatile("ds_read_b64_tr_b16 %0, %1 offset:%2" : "=&v"(r) : "v"(vb), "i"(OFF) : "memory"); return r; }
; template <int H> DI void v_reads(s16x4* vf, int vb) {
;     vf[0] = tr_read<v_rd_off(0, 2 * H, 0)>(vb); vf[1] = tr_read<v_rd_off(0, 2 * H, 1)>(vb); vf[2] = tr_read<v_rd_off(0, 2 * H + 1, 0)>(vb); vf[3] = tr_read<v_rd_off(0, 2 * H + 1, 1)>(vb);
;     vf[4] = tr_read<v_rd_off(1, 2 * H, 0)>(vb); vf[5] = tr_read<v_rd_off(1, 2 * H, 1)>(vb); vf[6] = tr_read<v_rd_off(1, 2 * H + 1, 0)>(vb); vf[7] = tr_read<v_rd_off(1, 2 * H + 1, 1)>(vb);
;     vf[8] = tr_read<v_rd_off(2, 2 * H, 0)>(vb); vf[9] = tr_read<v_rd_off(2, 2 * H, 1)>(vb); vf[10] = tr_read<v_rd_off(2, 2 * H + 1, 0)>(vb); vf[11] = tr_read<v_rd_off(2, 2 * H + 1, 1)>(vb);
;     vf[12] = tr_read<v_rd_off(3, 2 * H, 0)>(vb); vf[13] = tr_read<v_rd_off(3, 2 * H, 1)>(vb); vf[14] = tr_read<v_rd_off(3, 2 * H + 1, 0)>(vb); vf[15] = tr_read<v_rd_off(3, 2 * H + 1, 1)>(vb);
; }
; DI void pv_mma(f32x16* o, const s16x4* vf, bf16x8 pa0, bf16x8 pa1) {
;     ...
; #pragma unroll
;     for (int d0 = 0; d0 < 4; ++d0) {
;         o[d0] = __builtin_amdgcn_mfma_f32_32x32x16_bf16(pa0, ATT_PK(vf[4 * d0], vf[4 * d0 + 1]), o[d0], 0, 0, 0);
;         o[d0] = __builtin_amdgcn_mfma_f32_32x32x16_bf16(pa1, ATT_PK(vf[4 * d0 + 2], vf[4 * d0 + 3]), o[d0], 0, 0, 0); }
;     ...
; }
; template <int DQK, int MODE, int LDQ, int LDK, int LDV> ...
;     ...
;     f32x16 pA, pB; bf16x8 pa0, pa1;
;     int v0 = 0, v1 = 1, v2 = 2;
;     ATT_TOP(NKP + 2);
;     { bf16x8 kf[NDA]; k_reads<DQK, 0, NDA>(kf, lds, 0, r32, hi); ATT_LGKM0(); qk_mma<0, NDA>(pA, kf, qr);
;       if constexpr (ND0 > NDA) { bf16x8 kg[ND0 - NDA]; k_reads<DQK, NDA, ND0>(kg, lds, 0, r32, hi); ATT_LGKM0(); qk_mma<NDA, ND0>(pA, kg, qr); }
;       ATT_BIAS(pA, 0, 0); }
;     if (wid >= 4) __builtin_amdgcn_s_setprio(1);
;     for (int j = 0; j < NT; ++j) {
.LBB0_1924:
	s_add_i32 s3, s22, 0xffffc000
	s_and_b32 s3, s3, 0x6000
	v_add_u32_e32 v123, s3, v114
	v_add_u32_e32 v140, v123, v118
	v_add_u32_e32 v136, v123, v117
	v_add_u32_e32 v132, v123, v116
	v_add_u32_e32 v123, v123, v115
	ds_read_b128 v[124:127], v123
	ds_read_b128 v[132:135], v132
	ds_read_b128 v[136:139], v136
	ds_read_b128 v[140:143], v140
	ds_read_b64_tr_b16 v[144:145], v121 offset:0x2000
	ds_read_b64_tr_b16 v[146:147], v121 offset:0x2800
	ds_read_b64_tr_b16 v[148:149], v121 offset:0x3000
	ds_read_b64_tr_b16 v[150:151], v121 offset:0x3800
	ds_read_b64_tr_b16 v[152:153], v121 offset:0x2200
	ds_read_b64_tr_b16 v[154:155], v121 offset:0x2a00
	ds_read_b64_tr_b16 v[156:157], v121 offset:0x3200
	ds_read_b64_tr_b16 v[158:159], v121 offset:0x3a00
	ds_read_b64_tr_b16 v[162:163], v121 offset:0x2400
	ds_read_b64_tr_b16 v[164:165], v121 offset:0x2c00
	ds_read_b64_tr_b16 v[166:167], v121 offset:0x3400
	ds_read_b64_tr_b16 v[168:169], v121 offset:0x3c00
	ds_read_b64_tr_b16 v[170:171], v121 offset:0x2600
	ds_read_b64_tr_b16 v[172:173], v121 offset:0x2e00
	ds_read_b64_tr_b16 v[174:175], v121 offset:0x3600
	ds_read_b64_tr_b16 v[176:177], v121 offset:0x3e00
	s_setprio 2
	v_exp_f32_e32 v64, v64
	v_exp_f32_e32 v65, v65
	v_exp_f32_e32 v66, v66
	v_exp_f32_e32 v67, v67
	v_exp_f32_e32 v68, v68
	v_exp_f32_e32 v69, v69
	v_exp_f32_e32 v70, v70
	v_exp_f32_e32 v71, v71
	v_exp_f32_e32 v72, v72
	v_exp_f32_e32 v73, v73
	v_exp_f32_e32 v74, v74
	v_exp_f32_e32 v75, v75
	v_exp_f32_e32 v76, v76
	v_exp_f32_e32 v77, v77
	v_exp_f32_e32 v78, v78
	v_exp_f32_e32 v79, v79
	v_add_f32_e32 v121, v65, v64
	v_add_f32_e32 v121, v66, v121
	v_add_f32_e32 v121, v67, v121
	v_add_f32_e32 v121, v68, v121
	v_add_f32_e32 v121, v69, v121
	v_add_f32_e32 v121, v70, v121
	v_add_f32_e32 v121, v71, v121
	v_add_f32_e32 v121, v72, v121
	v_add_f32_e32 v121, v73, v121
	v_add_f32_e32 v121, v74, v121
	v_add_f32_e32 v121, v75, v121
	v_add_f32_e32 v121, v76, v121
	v_add_f32_e32 v121, v77, v121
	v_add_f32_e32 v121, v78, v121
	v_add_f32_e32 v121, v79, v121
	v_add_f32_e32 v120, v120, v121
	v_cvt_pk_bf16_f32 v64, v64, v65
	v_cvt_pk_bf16_f32 v65, v66, v67
	v_cvt_pk_bf16_f32 v66, v68, v69
	v_cvt_pk_bf16_f32 v67, v70, v71
	v_cvt_pk_bf16_f32 v68, v72, v73
	v_cvt_pk_bf16_f32 v69, v74, v75
	v_cvt_pk_bf16_f32 v70, v76, v77
	v_cvt_pk_bf16_f32 v71, v78, v79
	s_nop 0
	v_permlane32_swap_b32_e32 v64, v66
	v_permlane32_swap_b32_e32 v65, v67
	v_permlane32_swap_b32_e32 v68, v70
	v_permlane32_swap_b32_e32 v69, v71
	s_waitcnt lgkmcnt(0)
	s_setprio 1
	s_cmp_lt_u32 s33, 0x100
	s_cbranch_scc1 .Lstg_d0_mid_11
	s_waitcnt vmcnt(3)
	s_barrier

; #define LAS __attribute__((address_space(3)))
; DI void expsum(f32x16& p, float& l_reg, bf16x8& pa0, bf16x8& pa1) {
; #pragma unroll
;     for (int r = 0; r < 16; ++r) p[r] = __builtin_amdgcn_exp2f(p[r]);
;     float ps = 0.f;
; #pragma unroll
;     for (int r = 0; r < 16; ++r) ps += p[r];
;     l_reg += ps; asm volatile("" : "+v"(l_reg));
;     ...
;     ATT_PK4(p, 0, pa0); ATT_PK4(p, 8, pa1);
;     ...
; }
; DI int v_rd_base(int lane) { return ((lane & 3) << 3) | (((lane >> 2) & 3) << 6) | (((lane >> 4) & 1) << 5) | (((lane >> 5) & 1) << 8); }
; template <int OFF> DI s16x4 tr_read(int vb) { s16x4 r; asm volatile("ds_read_b64_tr_b16 %0, %1 offset:%2" : "=&v"(r) : "v"(vb), "i"(OFF) : "memory"); return r; }
; template <int H> DI void v_reads(s16x4* vf, int vb) {
;     vf[0] = tr_read<v_rd_off(0, 2 * H, 0)>(vb); vf[1] = tr_read<v_rd_off(0, 2 * H, 1)>(vb); vf[2] = tr_read<v_rd_off(0, 2 * H + 1, 0)>(vb); vf[3] = tr_read<v_rd_off(0, 2 * H + 1, 1)>(vb);
;     vf[4] = tr_read<v_rd_off(1, 2 * H, 0)>(vb); vf[5] = tr_read<v_rd_off(1, 2 * H, 1)>(vb); vf[6] = tr_read<v_rd_off(1, 2 * H + 1, 0)>(vb); vf[7] = tr_read<v_rd_off(1, 2 * H + 1, 1)>(vb);
;     vf[8] = tr_read<v_rd_off(2, 2 * H, 0)>(vb); vf[9] = tr_read<v_rd_off(2, 2 * H, 1)>(vb); vf[10] = tr_read<v_rd_off(2, 2 * H + 1, 0)>(vb); vf[11] = tr_read<v_rd_off(2, 2 * H + 1, 1)>(vb);
;     vf[12] = tr_read<v_rd_off(3, 2 * H, 0)>(vb); vf[13] = tr_read<v_rd_off(3, 2 * H, 1)>(vb); vf[14] = tr_read<v_rd_off(3, 2 * H + 1, 0)>(vb); vf[15] = tr_read<v_rd_off(3, 2 * H + 1, 1)>(vb);
; }
; DI void pv_mma(f32x16* o, const s16x4* vf, bf16x8 pa0, bf16x8 pa1) {
;     ...
; #pragma unroll
;     for (int d0 = 0; d0 < 4; ++d0) {
;         o[d0] = __builtin_amdgcn_mfma_f32_32x32x16_bf16(pa0, ATT_PK(vf[4 * d0], vf[4 * d0 + 1]), o[d0], 0, 0, 0);
;         o[d0] = __builtin_amdgcn_mfma_f32_32x32x16_bf16(pa1, ATT_PK(vf[4 * d0 + 2], vf[4 * d0 + 3]), o[d0], 0, 0, 0); }
;     ...
; }
; template <int DQK, int D0A, int D0B> DI void k_reads(bf16x8* kf, const LAS unsigned char* Ks, int half, int r32, int hi) {
; #pragma unroll
;     for (int d0 = D0A; d0 < D0B; ++d0) kf[d0 - D0A] = *(const LAS bf16x8*)(Ks + half * (32 * DQK * 2) + kswz<DQK>(r32, (d0 * 16 + hi * 8) * 2));
; }
; template <int D0A, int D0B> DI void qk_mma(f32x16& p, const bf16x8* kf, const bf16x8* qr) {
; #pragma unroll
;     for (int d0 = D0A; d0 < D0B; ++d0) {
.LBB0_1930:
	s_mov_b64 s[96:97], 0xc00
	ds_read_b128 v[98:101], v107 offset:12288
	ds_read_b128 v[102:105], v108 offset:12288
	ds_read_b128 v[114:117], v109 offset:12288
	ds_read_b128 v[122:125], v110 offset:12288
	v_lshl_add_u32 v96, s64, 14, v106
	ds_read_b64_tr_b16 v[132:133], v96 offset:0
	ds_read_b64_tr_b16 v[134:135], v96 offset:0x800
	ds_read_b64_tr_b16 v[136:137], v96 offset:0x1000
	ds_read_b64_tr_b16 v[138:139], v96 offset:0x1800
	ds_read_b64_tr_b16 v[140:141], v96 offset:0x200
	ds_read_b64_tr_b16 v[142:143], v96 offset:0xa00
	ds_read_b64_tr_b16 v[144:145], v96 offset:0x1200
	ds_read_b64_tr_b16 v[146:147], v96 offset:0x1a00
	ds_read_b64_tr_b16 v[148:149], v96 offset:0x400
	ds_read_b64_tr_b16 v[150:151], v96 offset:0xc00
	ds_read_b64_tr_b16 v[152:153], v96 offset:0x1400
	ds_read_b64_tr_b16 v[154:155], v96 offset:0x1c00
	ds_read_b64_tr_b16 v[156:157], v96 offset:0x600
	ds_read_b64_tr_b16 v[158:159], v96 offset:0xe00
	ds_read_b64_tr_b16 v[162:163], v96 offset:0x1600
	ds_read_b64_tr_b16 v[164:165], v96 offset:0x1e00
	s_setprio 2
	v_exp_f32_e32 v64, v64
	v_exp_f32_e32 v65, v65
	v_exp_f32_e32 v66, v66
	v_exp_f32_e32 v67, v67
	v_exp_f32_e32 v68, v68
	v_exp_f32_e32 v69, v69
	v_exp_f32_e32 v70, v70
	v_exp_f32_e32 v71, v71
	v_exp_f32_e32 v72, v72
	v_exp_f32_e32 v73, v73
	v_exp_f32_e32 v74, v74
	v_exp_f32_e32 v75, v75
	v_exp_f32_e32 v76, v76
	v_exp_f32_e32 v77, v77
	v_exp_f32_e32 v78, v78
	v_exp_f32_e32 v79, v79
	v_add_f32_e32 v97, v65, v64
	v_add_f32_e32 v97, v66, v97
	v_add_f32_e32 v97, v67, v97
	v_add_f32_e32 v97, v68, v97
	v_add_f32_e32 v97, v69, v97
	v_add_f32_e32 v97, v70, v97
	v_add_f32_e32 v97, v71, v97
	v_add_f32_e32 v97, v72, v97
	v_add_f32_e32 v97, v73, v97
	v_add_f32_e32 v97, v74, v97
	v_add_f32_e32 v97, v75, v97
	v_add_f32_e32 v97, v76, v97
	v_add_f32_e32 v97, v77, v97
	v_add_f32_e32 v97, v78, v97
	v_add_f32_e32 v97, v79, v97
	v_add_f32_e32 v97, v97, v120
	v_cvt_pk_bf16_f32 v64, v64, v65
	v_cvt_pk_bf16_f32 v65, v66, v67
	v_cvt_pk_bf16_f32 v66, v68, v69
	v_cvt_pk_bf16_f32 v67, v70, v71
	v_cvt_pk_bf16_f32 v68, v72, v73
	v_cvt_pk_bf16_f32 v69, v74, v75
	v_cvt_pk_bf16_f32 v70, v76, v77
	v_cvt_pk_bf16_f32 v71, v78, v79
	s_nop 0
	v_permlane32_swap_b32_e32 v64, v66
	v_permlane32_swap_b32_e32 v65, v67
	v_permlane32_swap_b32_e32 v68, v70
	v_permlane32_swap_b32_e32 v69, v71
	s_waitcnt lgkmcnt(0)
	s_setprio 1
	v_mfma_f32_32x32x16_bf16 v[0:15], v[64:67], v[132:135], v[0:15]
	s_cmp_gt_i32 s55, 61
	s_cselect_b64 s[0:1], -1, 0
	s_cmp_lt_i32 s58, 62
	s_cselect_b64 s[2:3], -1, 0
	s_or_b64 s[0:1], s[0:1], s[2:3]
	s_and_b64 vcc, exec, s[0:1]
	v_mfma_f32_32x32x16_bf16 v[48:63], v[64:67], v[140:143], v[48:63]
	v_mfma_f32_32x32x16_bf16 v[32:47], v[64:67], v[148:151], v[32:47]
	v_mfma_f32_32x32x16_bf16 v[16:31], v[64:67], v[156:159], v[16:31]
	v_mfma_f32_32x32x16_bf16 v[0:15], v[68:71], v[136:139], v[0:15]
	v_mfma_f32_32x32x16_bf16 v[48:63], v[68:71], v[144:147], v[48:63]
	v_mfma_f32_32x32x16_bf16 v[32:47], v[68:71], v[152:155], v[32:47]
	v_mfma_f32_32x32x16_bf16 v[16:31], v[68:71], v[162:165], v[16:31]
	s_waitcnt lgkmcnt(0)
	v_mfma_f32_32x32x16_bf16 v[64:79], v[98:101], v[92:95], 0
	v_mfma_f32_32x32x16_bf16 v[64:79], v[102:105], v[88:91], v[64:79]
	v_mfma_f32_32x32x16_bf16 v[64:79], v[114:117], v[84:87], v[64:79]
	v_mfma_f32_32x32x16_bf16 v[64:79], v[122:125], v[80:83], v[64:79]
	s_setprio 0
	s_cbranch_vccnz .LBB0_1932
	v_sub_u32_e32 v98, 0xf40, v111
	v_lshlrev_b32_e32 v98, 2, v98
	v_add3_u32 v98, s88, v98, v130
	v_add_u32_e32 v114, 0x400, v98
	v_add_u32_e32 v116, 0x408, v98
	v_add_u32_e32 v118, 0x420, v98
	v_add_u32_e32 v120, 0x428, v98
	v_add_u32_e32 v99, 0x440, v98
	v_add_u32_e32 v100, 0x448, v98
	v_add_u32_e32 v102, 0x460, v98
	v_add_u32_e32 v104, 0x468, v98
	ds_read2_b32 v[98:99], v99 offset1:1
	ds_read2_b32 v[100:101], v100 offset1:1
	ds_read2_b32 v[102:103], v102 offset1:1
	ds_read2_b32 v[104:105], v104 offset1:1
	ds_read2_b32 v[114:115], v114 offset1:1
	ds_read2_b32 v[116:117], v116 offset1:1
	ds_read2_b32 v[118:119], v118 offset1:1
	ds_read2_b32 v[120:121], v120 offset1:1
	s_waitcnt lgkmcnt(0)
	v_pk_add_f32 v[78:79], v[78:79], v[104:105]
	v_pk_add_f32 v[76:77], v[76:77], v[102:103]
	v_pk_add_f32 v[74:75], v[74:75], v[100:101]
	v_pk_add_f32 v[72:73], v[72:73], v[98:99]
	v_pk_add_f32 v[70:71], v[70:71], v[120:121]
	v_pk_add_f32 v[68:69], v[68:69], v[118:119]
	v_pk_add_f32 v[66:67], v[66:67], v[116:117]
	v_pk_add_f32 v[64:65], v[64:65], v[114:115]
.LBB0_1932:
	s_movk_i32 s64, 0x70
	ds_read_b128 v[98:101], v107 offset:16384
	ds_read_b128 v[102:105], v108 offset:16384
	ds_read_b128 v[114:117], v109 offset:16384
	ds_read_b128 v[118:121], v110 offset:16384
	ds_read_b64_tr_b16 v[122:123], v96 offset:0x2000
	ds_read_b64_tr_b16 v[124:125], v96 offset:0x2800
	ds_read_b64_tr_b16 v[132:133], v96 offset:0x3000
	ds_read_b64_tr_b16 v[134:135], v96 offset:0x3800
	ds_read_b64_tr_b16 v[136:137], v96 offset:0x2200
	ds_read_b64_tr_b16 v[138:139], v96 offset:0x2a00
	ds_read_b64_tr_b16 v[140:141], v96 offset:0x3200
	ds_read_b64_tr_b16 v[142:143], v96 offset:0x3a00
	ds_read_b64_tr_b16 v[144:145], v96 offset:0x2400
	ds_read_b64_tr_b16 v[146:147], v96 offset:0x2c00
	ds_read_b64_tr_b16 v[148:149], v96 offset:0x3400
	ds_read_b64_tr_b16 v[150:151], v96 offset:0x3c00
	ds_read_b64_tr_b16 v[152:153], v96 offset:0x2600
	ds_read_b64_tr_b16 v[154:155], v96 offset:0x2e00
	ds_read_b64_tr_b16 v[156:157], v96 offset:0x3600
	ds_read_b64_tr_b16 v[158:159], v96 offset:0x3e00
	s_nop 5
	s_setprio 2
	v_exp_f32_e32 v64, v64
	v_exp_f32_e32 v65, v65
	v_exp_f32_e32 v66, v66
	v_exp_f32_e32 v67, v67
	v_exp_f32_e32 v68, v68
	v_exp_f32_e32 v69, v69
	v_exp_f32_e32 v70, v70
	v_exp_f32_e32 v71, v71
	v_exp_f32_e32 v72, v72
	v_exp_f32_e32 v73, v73
	v_exp_f32_e32 v74, v74
	v_exp_f32_e32 v75, v75
	v_exp_f32_e32 v76, v76
	v_exp_f32_e32 v77, v77
	v_exp_f32_e32 v78, v78
	v_exp_f32_e32 v79, v79
	v_add_f32_e32 v96, v65, v64
	v_add_f32_e32 v96, v66, v96
	v_add_f32_e32 v96, v67, v96
	v_add_f32_e32 v96, v68, v96
	v_add_f32_e32 v96, v69, v96
	v_add_f32_e32 v96, v70, v96
	v_add_f32_e32 v96, v71, v96
	v_add_f32_e32 v96, v72, v96
	v_add_f32_e32 v96, v73, v96
	v_add_f32_e32 v96, v74, v96
	v_add_f32_e32 v96, v75, v96
	v_add_f32_e32 v96, v76, v96
	v_add_f32_e32 v96, v77, v96
	v_add_f32_e32 v96, v78, v96
	v_add_f32_e32 v96, v79, v96
	v_add_f32_e32 v96, v97, v96
	v_cvt_pk_bf16_f32 v64, v64, v65
	v_cvt_pk_bf16_f32 v65, v66, v67
	v_cvt_pk_bf16_f32 v66, v68, v69
	v_cvt_pk_bf16_f32 v67, v70, v71
	v_cvt_pk_bf16_f32 v68, v72, v73
	v_cvt_pk_bf16_f32 v69, v74, v75
	v_cvt_pk_bf16_f32 v70, v76, v77
	v_cvt_pk_bf16_f32 v71, v78, v79
	s_nop 0
	v_permlane32_swap_b32_e32 v64, v66
	v_permlane32_swap_b32_e32 v65, v67
	v_permlane32_swap_b32_e32 v68, v70
	v_permlane32_swap_b32_e32 v69, v71
	s_waitcnt lgkmcnt(0)
	s_setprio 1
	s_cmp_lt_u32 s33, 0x100
	s_cbranch_scc1 .Lstg_d0_m61_13
	s_waitcnt vmcnt(0)
	s_barrier

; #define LAS __attribute__((address_space(3)))
; DI void expsum(f32x16& p, float& l_reg, bf16x8& pa0, bf16x8& pa1) {
; #pragma unroll
;     for (int r = 0; r < 16; ++r) p[r] = __builtin_amdgcn_exp2f(p[r]);
;     float ps = 0.f;
; #pragma unroll
;     for (int r = 0; r < 16; ++r) ps += p[r];
;     l_reg += ps; asm volatile("" : "+v"(l_reg));
;     ...
;     ATT_PK4(p, 0, pa0); ATT_PK4(p, 8, pa1);
;     ...
; }
; DI int v_rd_base(int lane) { return ((lane & 3) << 3) | (((lane >> 2) & 3) << 6) | (((lane >> 4) & 1) << 5) | (((lane >> 5) & 1) << 8); }
; template <int OFF> DI s16x4 tr_read(int vb) { s16x4 r; asm volatile("ds_read_b64_tr_b16 %0, %1 offset:%2" : "=&v"(r) : "v"(vb), "i"(OFF) : "memory"); return r; }
; template <int H> DI void v_reads(s16x4* vf, int vb) {
;     vf[0] = tr_read<v_rd_off(0, 2 * H, 0)>(vb); vf[1] = tr_read<v_rd_off(0, 2 * H, 1)>(vb); vf[2] = tr_read<v_rd_off(0, 2 * H + 1, 0)>(vb); vf[3] = tr_read<v_rd_off(0, 2 * H + 1, 1)>(vb);
;     vf[4] = tr_read<v_rd_off(1, 2 * H, 0)>(vb); vf[5] = tr_read<v_rd_off(1, 2 * H, 1)>(vb); vf[6] = tr_read<v_rd_off(1, 2 * H + 1, 0)>(vb); vf[7] = tr_read<v_rd_off(1, 2 * H + 1, 1)>(vb);
;     vf[8] = tr_read<v_rd_off(2, 2 * H, 0)>(vb); vf[9] = tr_read<v_rd_off(2, 2 * H, 1)>(vb); vf[10] = tr_read<v_rd_off(2, 2 * H + 1, 0)>(vb); vf[11] = tr_read<v_rd_off(2, 2 * H + 1, 1)>(vb);
;     vf[12] = tr_read<v_rd_off(3, 2 * H, 0)>(vb); vf[13] = tr_read<v_rd_off(3, 2 * H, 1)>(vb); vf[14] = tr_read<v_rd_off(3, 2 * H + 1, 0)>(vb); vf[15] = tr_read<v_rd_off(3, 2 * H + 1, 1)>(vb);
; }
; DI void pv_mma(f32x16* o, const s16x4* vf, bf16x8 pa0, bf16x8 pa1) {
;     ...
; #pragma unroll
;     for (int d0 = 0; d0 < 4; ++d0) {
;         o[d0] = __builtin_amdgcn_mfma_f32_32x32x16_bf16(pa0, ATT_PK(vf[4 * d0], vf[4 * d0 + 1]), o[d0], 0, 0, 0);
;         o[d0] = __builtin_amdgcn_mfma_f32_32x32x16_bf16(pa1, ATT_PK(vf[4 * d0 + 2], vf[4 * d0 + 3]), o[d0], 0, 0, 0); }
;     ...
; }
; template <int DQK, int D0A, int D0B> DI void k_reads(bf16x8* kf, const LAS unsigned char* Ks, int half, int r32, int hi) {
; #pragma unroll
;     for (int d0 = D0A; d0 < D0B; ++d0) kf[d0 - D0A] = *(const LAS bf16x8*)(Ks + half * (32 * DQK * 2) + kswz<DQK>(r32, (d0 * 16 + hi * 8) * 2));
; }
; template <int D0A, int D0B> DI void qk_mma(f32x16& p, const bf16x8* kf, const bf16x8* qr) {
; #pragma unroll
;     for (int d0 = D0A; d0 < D0B; ++d0) {
.LBB0_1936:
	ds_read_b128 v[100:103], v107 offset:20480
	ds_read_b128 v[114:117], v108 offset:20480
	ds_read_b128 v[118:121], v109 offset:20480
	ds_read_b128 v[122:125], v110 offset:20480
	v_add_u32_e32 v98, 0x8000, v106
	ds_read_b64_tr_b16 v[132:133], v98 offset:0
	ds_read_b64_tr_b16 v[134:135], v98 offset:0x800
	ds_read_b64_tr_b16 v[136:137], v98 offset:0x1000
	ds_read_b64_tr_b16 v[138:139], v98 offset:0x1800
	ds_read_b64_tr_b16 v[140:141], v98 offset:0x200
	ds_read_b64_tr_b16 v[142:143], v98 offset:0xa00
	ds_read_b64_tr_b16 v[144:145], v98 offset:0x1200
	ds_read_b64_tr_b16 v[146:147], v98 offset:0x1a00
	ds_read_b64_tr_b16 v[148:149], v98 offset:0x400
	ds_read_b64_tr_b16 v[150:151], v98 offset:0xc00
	ds_read_b64_tr_b16 v[152:153], v98 offset:0x1400
	ds_read_b64_tr_b16 v[154:155], v98 offset:0x1c00
	ds_read_b64_tr_b16 v[156:157], v98 offset:0x600
	ds_read_b64_tr_b16 v[158:159], v98 offset:0xe00
	ds_read_b64_tr_b16 v[162:163], v98 offset:0x1600
	ds_read_b64_tr_b16 v[164:165], v98 offset:0x1e00
	s_setprio 2
	v_exp_f32_e32 v64, v64
	v_exp_f32_e32 v65, v65
	v_exp_f32_e32 v66, v66
	v_exp_f32_e32 v67, v67
	v_exp_f32_e32 v68, v68
	v_exp_f32_e32 v69, v69
	v_exp_f32_e32 v70, v70
	v_exp_f32_e32 v71, v71
	v_exp_f32_e32 v72, v72
	v_exp_f32_e32 v73, v73
	v_exp_f32_e32 v74, v74
	v_exp_f32_e32 v75, v75
	v_exp_f32_e32 v76, v76
	v_exp_f32_e32 v77, v77
	v_exp_f32_e32 v78, v78
	v_exp_f32_e32 v79, v79
	v_add_f32_e32 v99, v65, v64
	v_add_f32_e32 v99, v66, v99
	v_add_f32_e32 v99, v67, v99
	v_add_f32_e32 v99, v68, v99
	v_add_f32_e32 v99, v69, v99
	v_add_f32_e32 v99, v70, v99
	v_add_f32_e32 v99, v71, v99
	v_add_f32_e32 v99, v72, v99
	v_add_f32_e32 v99, v73, v99
	v_add_f32_e32 v99, v74, v99
	v_add_f32_e32 v99, v75, v99
	v_add_f32_e32 v99, v76, v99
	v_add_f32_e32 v99, v77, v99
	v_add_f32_e32 v99, v78, v99
	v_add_f32_e32 v99, v79, v99
	v_add_f32_e32 v96, v99, v96
	v_cvt_pk_bf16_f32 v64, v64, v65
	v_cvt_pk_bf16_f32 v65, v66, v67
	v_cvt_pk_bf16_f32 v66, v68, v69
	v_cvt_pk_bf16_f32 v67, v70, v71
	v_cvt_pk_bf16_f32 v68, v72, v73
	v_cvt_pk_bf16_f32 v69, v74, v75
	v_cvt_pk_bf16_f32 v70, v76, v77
	v_cvt_pk_bf16_f32 v71, v78, v79
	s_nop 0
	v_permlane32_swap_b32_e32 v64, v66
	v_permlane32_swap_b32_e32 v65, v67
	v_permlane32_swap_b32_e32 v68, v70
	v_permlane32_swap_b32_e32 v69, v71
	s_waitcnt lgkmcnt(0)
	s_setprio 1
	v_mfma_f32_32x32x16_bf16 v[0:15], v[64:67], v[132:135], v[0:15]
	s_and_b64 vcc, exec, s[2:3]
	v_mfma_f32_32x32x16_bf16 v[48:63], v[64:67], v[140:143], v[48:63]
	v_mfma_f32_32x32x16_bf16 v[32:47], v[64:67], v[148:151], v[32:47]
	v_mfma_f32_32x32x16_bf16 v[16:31], v[64:67], v[156:159], v[16:31]
	v_mfma_f32_32x32x16_bf16 v[0:15], v[68:71], v[136:139], v[0:15]
	v_mfma_f32_32x32x16_bf16 v[48:63], v[68:71], v[144:147], v[48:63]
	v_mfma_f32_32x32x16_bf16 v[32:47], v[68:71], v[152:155], v[32:47]
	v_mfma_f32_32x32x16_bf16 v[16:31], v[68:71], v[162:165], v[16:31]
	s_waitcnt lgkmcnt(0)
	v_mfma_f32_32x32x16_bf16 v[64:79], v[100:103], v[92:95], 0
	v_mfma_f32_32x32x16_bf16 v[64:79], v[114:117], v[88:91], v[64:79]
	v_mfma_f32_32x32x16_bf16 v[64:79], v[118:121], v[84:87], v[64:79]
	v_mfma_f32_32x32x16_bf16 v[64:79], v[122:125], v[80:83], v[64:79]
	s_setprio 0
	s_cbranch_vccnz .LBB0_1938
	v_add3_u32 v97, s88, v97, v130
	v_add_u32_e32 v118, 0x408, v97
	v_add_u32_e32 v120, 0x420, v97
	v_add_u32_e32 v122, 0x428, v97
	v_add_u32_e32 v100, 0x440, v97
	v_add_u32_e32 v102, 0x448, v97
	v_add_u32_e32 v104, 0x460, v97
	v_add_u32_e32 v99, 0x400, v97
	v_add_u32_e32 v97, 0x468, v97
	ds_read2_b32 v[100:101], v100 offset1:1
	ds_read2_b32 v[102:103], v102 offset1:1
	ds_read2_b32 v[104:105], v104 offset1:1
	ds_read2_b32 v[114:115], v97 offset1:1
	ds_read2_b32 v[116:117], v99 offset1:1
	ds_read2_b32 v[118:119], v118 offset1:1
	ds_read2_b32 v[120:121], v120 offset1:1
	ds_read2_b32 v[122:123], v122 offset1:1
	s_waitcnt lgkmcnt(0)
	v_pk_add_f32 v[78:79], v[78:79], v[114:115]
	v_pk_add_f32 v[76:77], v[76:77], v[104:105]
	v_pk_add_f32 v[74:75], v[74:75], v[102:103]
	v_pk_add_f32 v[72:73], v[72:73], v[100:101]
	v_pk_add_f32 v[70:71], v[70:71], v[122:123]
	v_pk_add_f32 v[68:69], v[68:69], v[120:121]
	v_pk_add_f32 v[66:67], v[66:67], v[118:119]
	v_pk_add_f32 v[64:65], v[64:65], v[116:117]
.LBB0_1938:
	ds_read_b128 v[100:103], v107 offset:24576
	ds_read_b128 v[114:117], v108 offset:24576
	ds_read_b128 v[118:121], v109 offset:24576
	ds_read_b128 v[122:125], v110 offset:24576
	ds_read_b64_tr_b16 v[132:133], v98 offset:0x2000
	ds_read_b64_tr_b16 v[134:135], v98 offset:0x2800
	ds_read_b64_tr_b16 v[136:137], v98 offset:0x3000
	ds_read_b64_tr_b16 v[138:139], v98 offset:0x3800
	ds_read_b64_tr_b16 v[140:141], v98 offset:0x2200
	ds_read_b64_tr_b16 v[142:143], v98 offset:0x2a00
	ds_read_b64_tr_b16 v[144:145], v98 offset:0x3200
	ds_read_b64_tr_b16 v[146:147], v98 offset:0x3a00
	ds_read_b64_tr_b16 v[148:149], v98 offset:0x2400
	ds_read_b64_tr_b16 v[150:151], v98 offset:0x2c00
	ds_read_b64_tr_b16 v[152:153], v98 offset:0x3400
	ds_read_b64_tr_b16 v[154:155], v98 offset:0x3c00
	ds_read_b64_tr_b16 v[156:157], v98 offset:0x2600
	ds_read_b64_tr_b16 v[158:159], v98 offset:0x2e00
	ds_read_b64_tr_b16 v[162:163], v98 offset:0x3600
	ds_read_b64_tr_b16 v[164:165], v98 offset:0x3e00
	s_nop 6
	s_setprio 2
	v_exp_f32_e32 v64, v64
	v_exp_f32_e32 v65, v65
	v_exp_f32_e32 v66, v66
	v_exp_f32_e32 v67, v67
	v_exp_f32_e32 v68, v68
	v_exp_f32_e32 v69, v69
	v_exp_f32_e32 v70, v70
	v_exp_f32_e32 v71, v71
	v_exp_f32_e32 v72, v72
	v_exp_f32_e32 v73, v73
	v_exp_f32_e32 v74, v74
	v_exp_f32_e32 v75, v75
	v_exp_f32_e32 v76, v76
	v_exp_f32_e32 v77, v77
	v_exp_f32_e32 v78, v78
	v_exp_f32_e32 v79, v79
	v_add_f32_e32 v97, v65, v64
	v_add_f32_e32 v97, v66, v97
	v_add_f32_e32 v97, v67, v97
	v_add_f32_e32 v97, v68, v97
	v_add_f32_e32 v97, v69, v97
	v_add_f32_e32 v97, v70, v97
	v_add_f32_e32 v97, v71, v97
	v_add_f32_e32 v97, v72, v97
	v_add_f32_e32 v97, v73, v97
	v_add_f32_e32 v97, v74, v97
	v_add_f32_e32 v97, v75, v97
	v_add_f32_e32 v97, v76, v97
	v_add_f32_e32 v97, v77, v97
	v_add_f32_e32 v97, v78, v97
	v_add_f32_e32 v97, v79, v97
	v_add_f32_e32 v96, v96, v97
	v_cvt_pk_bf16_f32 v64, v64, v65
	v_cvt_pk_bf16_f32 v65, v66, v67
	v_cvt_pk_bf16_f32 v66, v68, v69
	v_cvt_pk_bf16_f32 v67, v70, v71
	v_cvt_pk_bf16_f32 v68, v72, v73
	v_cvt_pk_bf16_f32 v69, v74, v75
	v_cvt_pk_bf16_f32 v70, v76, v77
	v_cvt_pk_bf16_f32 v71, v78, v79
	s_nop 0
	v_permlane32_swap_b32_e32 v64, v66
	v_permlane32_swap_b32_e32 v65, v67
	v_permlane32_swap_b32_e32 v68, v70
	v_permlane32_swap_b32_e32 v69, v71
	s_waitcnt lgkmcnt(0)
	s_setprio 1
	s_cmp_lt_u32 s33, 0x100
	s_cbranch_scc1 .Lstg_d0_m62_15
	s_waitcnt vmcnt(0)
	s_barrier

; #define LAS __attribute__((address_space(3)))
; DI void expsum(f32x16& p, float& l_reg, bf16x8& pa0, bf16x8& pa1) {
; #pragma unroll
;     for (int r = 0; r < 16; ++r) p[r] = __builtin_amdgcn_exp2f(p[r]);
;     float ps = 0.f;
; #pragma unroll
;     for (int r = 0; r < 16; ++r) ps += p[r];
;     l_reg += ps; asm volatile("" : "+v"(l_reg));
;     ...
;     ATT_PK4(p, 0, pa0); ATT_PK4(p, 8, pa1);
;     ...
; }
; DI int v_rd_base(int lane) { return ((lane & 3) << 3) | (((lane >> 2) & 3) << 6) | (((lane >> 4) & 1) << 5) | (((lane >> 5) & 1) << 8); }
; template <int OFF> DI s16x4 tr_read(int vb) { s16x4 r; asm volatile("ds_read_b64_tr_b16 %0, %1 offset:%2" : "=&v"(r) : "v"(vb), "i"(OFF) : "memory"); return r; }
; template <int H> DI void v_reads(s16x4* vf, int vb) {
;     vf[0] = tr_read<v_rd_off(0, 2 * H, 0)>(vb); vf[1] = tr_read<v_rd_off(0, 2 * H, 1)>(vb); vf[2] = tr_read<v_rd_off(0, 2 * H + 1, 0)>(vb); vf[3] = tr_read<v_rd_off(0, 2 * H + 1, 1)>(vb);
;     vf[4] = tr_read<v_rd_off(1, 2 * H, 0)>(vb); vf[5] = tr_read<v_rd_off(1, 2 * H, 1)>(vb); vf[6] = tr_read<v_rd_off(1, 2 * H + 1, 0)>(vb); vf[7] = tr_read<v_rd_off(1, 2 * H + 1, 1)>(vb);
;     vf[8] = tr_read<v_rd_off(2, 2 * H, 0)>(vb); vf[9] = tr_read<v_rd_off(2, 2 * H, 1)>(vb); vf[10] = tr_read<v_rd_off(2, 2 * H + 1, 0)>(vb); vf[11] = tr_read<v_rd_off(2, 2 * H + 1, 1)>(vb);
;     vf[12] = tr_read<v_rd_off(3, 2 * H, 0)>(vb); vf[13] = tr_read<v_rd_off(3, 2 * H, 1)>(vb); vf[14] = tr_read<v_rd_off(3, 2 * H + 1, 0)>(vb); vf[15] = tr_read<v_rd_off(3, 2 * H + 1, 1)>(vb);
; }
; DI void pv_mma(f32x16* o, const s16x4* vf, bf16x8 pa0, bf16x8 pa1) {
;     ...
; #pragma unroll
;     for (int d0 = 0; d0 < 4; ++d0) {
;         o[d0] = __builtin_amdgcn_mfma_f32_32x32x16_bf16(pa0, ATT_PK(vf[4 * d0], vf[4 * d0 + 1]), o[d0], 0, 0, 0);
;         o[d0] = __builtin_amdgcn_mfma_f32_32x32x16_bf16(pa1, ATT_PK(vf[4 * d0 + 2], vf[4 * d0 + 3]), o[d0], 0, 0, 0); }
;     ...
; }
; template <int DQK, int D0A, int D0B> DI void k_reads(bf16x8* kf, const LAS unsigned char* Ks, int half, int r32, int hi) {
; #pragma unroll
;     for (int d0 = D0A; d0 < D0B; ++d0) kf[d0 - D0A] = *(const LAS bf16x8*)(Ks + half * (32 * DQK * 2) + kswz<DQK>(r32, (d0 * 16 + hi * 8) * 2));
; }
; template <int D0A, int D0B> DI void qk_mma(f32x16& p, const bf16x8* kf, const bf16x8* qr) {
; #pragma unroll
;     for (int d0 = D0A; d0 < D0B; ++d0) {
.LBB0_1942:
	ds_read_b128 v[98:101], v107 offset:28672
	ds_read_b128 v[102:105], v108 offset:28672
	ds_read_b128 v[112:115], v109 offset:28672
	ds_read_b128 v[108:111], v110 offset:28672
	ds_read_b64_tr_b16 v[116:117], v106 offset:0
	ds_read_b64_tr_b16 v[118:119], v106 offset:0x800
	ds_read_b64_tr_b16 v[120:121], v106 offset:0x1000
	ds_read_b64_tr_b16 v[122:123], v106 offset:0x1800
	ds_read_b64_tr_b16 v[124:125], v106 offset:0x200
	ds_read_b64_tr_b16 v[126:127], v106 offset:0xa00
	ds_read_b64_tr_b16 v[132:133], v106 offset:0x1200
	ds_read_b64_tr_b16 v[134:135], v106 offset:0x1a00
	ds_read_b64_tr_b16 v[136:137], v106 offset:0x400
	ds_read_b64_tr_b16 v[138:139], v106 offset:0xc00
	ds_read_b64_tr_b16 v[140:141], v106 offset:0x1400
	ds_read_b64_tr_b16 v[142:143], v106 offset:0x1c00
	ds_read_b64_tr_b16 v[144:145], v106 offset:0x600
	ds_read_b64_tr_b16 v[146:147], v106 offset:0xe00
	ds_read_b64_tr_b16 v[148:149], v106 offset:0x1600
	ds_read_b64_tr_b16 v[150:151], v106 offset:0x1e00
	s_setprio 2
	v_exp_f32_e32 v64, v64
	v_exp_f32_e32 v65, v65
	v_exp_f32_e32 v66, v66
	v_exp_f32_e32 v67, v67
	v_exp_f32_e32 v68, v68
	v_exp_f32_e32 v69, v69
	v_exp_f32_e32 v70, v70
	v_exp_f32_e32 v71, v71
	v_exp_f32_e32 v72, v72
	v_exp_f32_e32 v73, v73
	v_exp_f32_e32 v74, v74
	v_exp_f32_e32 v75, v75
	v_exp_f32_e32 v76, v76
	v_exp_f32_e32 v77, v77
	v_exp_f32_e32 v78, v78
	v_exp_f32_e32 v79, v79
	v_add_f32_e32 v107, v65, v64
	v_add_f32_e32 v107, v66, v107
	v_add_f32_e32 v107, v67, v107
	v_add_f32_e32 v107, v68, v107
	v_add_f32_e32 v107, v69, v107
	v_add_f32_e32 v107, v70, v107
	v_add_f32_e32 v107, v71, v107
	v_add_f32_e32 v107, v72, v107
	v_add_f32_e32 v107, v73, v107
	v_add_f32_e32 v107, v74, v107
	v_add_f32_e32 v107, v75, v107
	v_add_f32_e32 v107, v76, v107
	v_add_f32_e32 v107, v77, v107
	v_add_f32_e32 v107, v78, v107
	v_add_f32_e32 v107, v79, v107
	v_add_f32_e32 v96, v107, v96
	v_cvt_pk_bf16_f32 v64, v64, v65
	v_cvt_pk_bf16_f32 v65, v66, v67
	v_cvt_pk_bf16_f32 v66, v68, v69
	v_cvt_pk_bf16_f32 v67, v70, v71
	v_cvt_pk_bf16_f32 v68, v72, v73
	v_cvt_pk_bf16_f32 v69, v74, v75
	v_cvt_pk_bf16_f32 v70, v76, v77
	v_cvt_pk_bf16_f32 v71, v78, v79
	s_nop 0
	v_permlane32_swap_b32_e32 v64, v66
	v_permlane32_swap_b32_e32 v65, v67
	v_permlane32_swap_b32_e32 v68, v70
	v_permlane32_swap_b32_e32 v69, v71
	s_waitcnt lgkmcnt(0)
	s_setprio 1
	v_mfma_f32_32x32x16_bf16 v[0:15], v[64:67], v[116:119], v[0:15]
	s_and_b64 vcc, exec, s[2:3]
	v_mfma_f32_32x32x16_bf16 v[48:63], v[64:67], v[124:127], v[48:63]
	v_mfma_f32_32x32x16_bf16 v[32:47], v[64:67], v[136:139], v[32:47]
	v_mfma_f32_32x32x16_bf16 v[16:31], v[64:67], v[144:147], v[16:31]
	v_mfma_f32_32x32x16_bf16 v[0:15], v[68:71], v[120:123], v[0:15]
	v_mfma_f32_32x32x16_bf16 v[48:63], v[68:71], v[132:135], v[48:63]
	v_mfma_f32_32x32x16_bf16 v[32:47], v[68:71], v[140:143], v[32:47]
	v_mfma_f32_32x32x16_bf16 v[16:31], v[68:71], v[148:151], v[16:31]
	s_waitcnt lgkmcnt(0)
	v_mfma_f32_32x32x16_bf16 v[64:79], v[98:101], v[92:95], 0
	v_mfma_f32_32x32x16_bf16 v[64:79], v[102:105], v[88:91], v[64:79]
	v_mfma_f32_32x32x16_bf16 v[64:79], v[112:115], v[84:87], v[64:79]
	v_mfma_f32_32x32x16_bf16 v[64:79], v[108:111], v[80:83], v[64:79]
	s_setprio 0
	s_cbranch_vccnz .LBB0_1944
	v_add3_u32 v80, s88, v97, v130
	v_add_u32_e32 v88, 0x400, v80
	v_add_u32_e32 v90, 0x408, v80
	v_add_u32_e32 v92, 0x420, v80
	v_add_u32_e32 v94, 0x428, v80
	v_add_u32_e32 v81, 0x440, v80
	v_add_u32_e32 v82, 0x448, v80
	v_add_u32_e32 v84, 0x460, v80
	v_add_u32_e32 v86, 0x468, v80
	ds_read2_b32 v[80:81], v81 offset1:1
	ds_read2_b32 v[82:83], v82 offset1:1
	ds_read2_b32 v[84:85], v84 offset1:1
	ds_read2_b32 v[86:87], v86 offset1:1
	ds_read2_b32 v[88:89], v88 offset1:1
	ds_read2_b32 v[90:91], v90 offset1:1
	ds_read2_b32 v[92:93], v92 offset1:1
	ds_read2_b32 v[94:95], v94 offset1:1
	s_waitcnt lgkmcnt(0)
	v_pk_add_f32 v[78:79], v[78:79], v[86:87]
	v_pk_add_f32 v[76:77], v[76:77], v[84:85]
	v_pk_add_f32 v[74:75], v[74:75], v[82:83]
	v_pk_add_f32 v[72:73], v[72:73], v[80:81]
	v_pk_add_f32 v[70:71], v[70:71], v[94:95]
	v_pk_add_f32 v[68:69], v[68:69], v[92:93]
	v_pk_add_f32 v[66:67], v[66:67], v[90:91]
	v_pk_add_f32 v[64:65], v[64:65], v[88:89]
.LBB0_1944:
	s_lshl_b32 s0, s54, 2
	s_add_i32 s0, s0, 0
	s_add_i32 s0, s0, 0x24000
	ds_read_b64_tr_b16 v[80:81], v106 offset:0x2000
	ds_read_b64_tr_b16 v[82:83], v106 offset:0x2800
	ds_read_b64_tr_b16 v[84:85], v106 offset:0x3000
	ds_read_b64_tr_b16 v[86:87], v106 offset:0x3800
	ds_read_b64_tr_b16 v[88:89], v106 offset:0x2200
	ds_read_b64_tr_b16 v[90:91], v106 offset:0x2a00
	ds_read_b64_tr_b16 v[92:93], v106 offset:0x3200
	ds_read_b64_tr_b16 v[94:95], v106 offset:0x3a00
	ds_read_b64_tr_b16 v[98:99], v106 offset:0x2400
	ds_read_b64_tr_b16 v[100:101], v106 offset:0x2c00
	ds_read_b64_tr_b16 v[102:103], v106 offset:0x3400
	ds_read_b64_tr_b16 v[104:105], v106 offset:0x3c00
	ds_read_b64_tr_b16 v[108:109], v106 offset:0x2600
	ds_read_b64_tr_b16 v[110:111], v106 offset:0x2e00
	ds_read_b64_tr_b16 v[112:113], v106 offset:0x3600
	ds_read_b64_tr_b16 v[114:115], v106 offset:0x3e00
	s_nop 7
	s_setprio 2
	v_exp_f32_e32 v97, v64
	v_exp_f32_e32 v65, v65
	v_exp_f32_e32 v106, v66
	v_exp_f32_e32 v67, v67
	v_exp_f32_e32 v68, v68
	v_exp_f32_e32 v69, v69
	v_exp_f32_e32 v70, v70
	v_exp_f32_e32 v71, v71
	v_exp_f32_e32 v72, v72
	v_exp_f32_e32 v73, v73
	v_exp_f32_e32 v74, v74
	v_exp_f32_e32 v75, v75
	v_exp_f32_e32 v76, v76
	v_exp_f32_e32 v77, v77
	v_exp_f32_e32 v78, v78
	v_exp_f32_e32 v79, v79
	v_add_f32_e32 v64, v65, v97
	v_add_f32_e32 v64, v106, v64
	v_add_f32_e32 v64, v67, v64
	v_add_f32_e32 v64, v68, v64
	v_add_f32_e32 v64, v69, v64
	v_add_f32_e32 v64, v70, v64
	v_add_f32_e32 v64, v71, v64
	v_add_f32_e32 v64, v72, v64
	v_add_f32_e32 v64, v73, v64
	v_add_f32_e32 v64, v74, v64
	v_add_f32_e32 v64, v75, v64
	v_add_f32_e32 v64, v76, v64
	v_add_f32_e32 v64, v77, v64
	v_add_f32_e32 v64, v78, v64
	v_add_f32_e32 v64, v79, v64
	v_add_f32_e32 v64, v96, v64
	v_cvt_pk_bf16_f32 v66, v97, v65
	v_cvt_pk_bf16_f32 v67, v106, v67
	v_cvt_pk_bf16_f32 v68, v68, v69
	v_cvt_pk_bf16_f32 v69, v70, v71
	v_cvt_pk_bf16_f32 v70, v72, v73
	v_cvt_pk_bf16_f32 v71, v74, v75
	v_cvt_pk_bf16_f32 v72, v76, v77
	v_cvt_pk_bf16_f32 v73, v78, v79
	s_nop 0
	v_permlane32_swap_b32_e32 v66, v68
	v_permlane32_swap_b32_e32 v67, v69
	v_permlane32_swap_b32_e32 v70, v72
	v_permlane32_swap_b32_e32 v71, v73
	s_waitcnt lgkmcnt(0)
; template <int TAG = 0> DI int fresh_tid(int wv) { int l; asm volatile("v_mbcnt_lo_u32_b32 %0, -1, 0\n\tv_mbcnt_hi_u32_b32 %0, -1, %0 ; site %1" : "=v"(l) : "n"(TAG)); return wv * 64 + l; }
; DI unsigned short f2bf(float x) { unsigned u = __float_as_uint(x); u += 0x7fffu + ((u >> 16) & 1u); return (unsigned short)(u >> 16); }
; DI int crow(int r, int hi) { return (r & 3) + 8 * (r >> 2) + 4 * hi; }
; DI float swap_sum(float v) { auto rr = __builtin_amdgcn_permlane32_swap(__float_as_uint(v), __float_as_uint(v), false, false); return __uint_as_float(rr[0]) + __uint_as_float(rr[1]); }
; template <int DQK, int MODE, int LDQ, int LDK, int LDV> ...
;     ...
;     __builtin_amdgcn_s_setprio(0);
;     ...
;     l_reg = swap_sum(l_reg);
;     { const int lane2 = fresh_tid<110 + MODE>(wv) & 63, r32 = lane2 & 31, hi = lane2 >> 5;
;     if (hi == 0) li_l[r32] = l_reg;
;     asm volatile("s_waitcnt lgkmcnt(0)" ::: "memory");
;     float s0v[MODE == 2 ? 16 : 1][4];
;     if constexpr (MODE == 2) {
; #pragma unroll
;         for (int r = 0; r < 16; ++r)
; #pragma unroll
;             for (int d0 = 0; d0 < 4; ++d0) s0v[r][d0] = S0[(size_t)(wid * 32 + crow(r, hi)) * 512 + d0 * 32 + r32];
;     }
; #pragma unroll
;     for (int r = 0; r < 16; ++r) { const int orow = wid * 32 + crow(r, hi); const float rl = __builtin_amdgcn_rcpf(li_l[crow(r, hi)]);
;         if constexpr (MODE == 0) {
; #pragma unroll
;             for (int d0 = 0; d0 < 4; ++d0) AOb[(size_t)orow * 1024 + d0 * 32 + r32] = f2bf(o[d0][r] * rl);
;         } else if constexpr (MODE == 1) {
; #pragma unroll
;             for (int d0 = 0; d0 < 4; ++d0) S0[(size_t)orow * 512 + d0 * 32 + r32] = o[d0][r] * rl;
	s_setprio 1
	v_mfma_f32_32x32x16_bf16 v[0:15], v[66:69], v[80:83], v[0:15]
	v_mfma_f32_32x32x16_bf16 v[48:63], v[66:69], v[88:91], v[48:63]
	v_mfma_f32_32x32x16_bf16 v[32:47], v[66:69], v[98:101], v[32:47]
	v_mfma_f32_32x32x16_bf16 v[16:31], v[66:69], v[108:111], v[16:31]
	v_mfma_f32_32x32x16_bf16 v[0:15], v[70:73], v[84:87], v[0:15]
	v_mfma_f32_32x32x16_bf16 v[48:63], v[70:73], v[92:95], v[48:63]
	v_mfma_f32_32x32x16_bf16 v[32:47], v[70:73], v[102:105], v[32:47]
	v_mfma_f32_32x32x16_bf16 v[16:31], v[70:73], v[112:115], v[16:31]
	s_setprio 0
	v_mbcnt_lo_u32_b32 v66, -1, 0
	v_mbcnt_hi_u32_b32 v66, -1, v66
	v_mov_b32_e32 v67, v64
	v_and_b32_e32 v65, 31, v66
	v_bfe_u32 v66, v66, 5, 1
	v_permlane32_swap_b32_e32 v64, v67
	v_cmp_eq_u32_e32 vcc, 0, v66
	s_and_saveexec_b64 s[2:3], vcc
	v_lshl_add_u32 v68, v65, 2, s0
	v_add_f32_e32 v64, v64, v67
	ds_write_b32 v68, v64
	s_or_b64 exec, exec, s[2:3]
	s_waitcnt lgkmcnt(0)
	v_lshl_add_u32 v68, v66, 4, s0
	ds_read_b128 v[70:73], v68
	ds_read_b128 v[74:77], v68 offset:32
	s_lshl_b64 s[58:59], s[40:41], 11
	v_readlane_b32 s1, v255, 2
	s_add_u32 s1, s1, s58
	v_readlane_b32 s2, v255, 0
	s_addc_u32 s2, s2, s59
	s_lshl_b32 s3, s87, 2
	s_waitcnt lgkmcnt(0)
	v_rcp_f32_e32 v69, v70
	s_add_u32 s54, s1, s3
	v_lshl_or_b32 v66, v66, 2, s94
	s_addc_u32 s55, s2, 0
	v_lshlrev_b32_e32 v130, 2, v65
	v_ashrrev_i32_e32 v67, 31, v66
	v_lshl_add_u64 v[64:65], s[54:55], 0, v[130:131]
	v_lshlrev_b64 v[78:79], 11, v[66:67]
	v_lshl_add_u64 v[78:79], v[64:65], 0, v[78:79]
	v_mul_f32_e32 v0, v0, v69
	global_store_dword v[78:79], v0, off
	v_mul_f32_e32 v0, v48, v69
	global_store_dword v[78:79], v0, off offset:128
	v_mul_f32_e32 v0, v32, v69
	global_store_dword v[78:79], v0, off offset:256
	v_mul_f32_e32 v0, v16, v69
	global_store_dword v[78:79], v0, off offset:384
	v_rcp_f32_e32 v0, v71
	v_or_b32_e32 v70, 1, v66
	v_ashrrev_i32_e32 v71, 31, v70
	v_lshlrev_b64 v[70:71], 11, v[70:71]
	v_lshl_add_u64 v[70:71], v[64:65], 0, v[70:71]
	v_mul_f32_e32 v1, v1, v0
	global_store_dword v[70:71], v1, off
	v_mul_f32_e32 v1, v49, v0
	global_store_dword v[70:71], v1, off offset:128
	v_mul_f32_e32 v1, v33, v0
	v_mul_f32_e32 v0, v17, v0
	v_rcp_f32_e32 v16, v72
	global_store_dword v[70:71], v0, off offset:384
	v_or_b32_e32 v0, 2, v66
	global_store_dword v[70:71], v1, off offset:256
	v_ashrrev_i32_e32 v1, 31, v0
	v_lshlrev_b64 v[0:1], 11, v[0:1]
	v_lshl_add_u64 v[0:1], v[64:65], 0, v[0:1]
	v_mul_f32_e32 v2, v2, v16
	global_store_dword v[0:1], v2, off
	v_mul_f32_e32 v2, v50, v16
	global_store_dword v[0:1], v2, off offset:128
	v_mul_f32_e32 v2, v34, v16
	global_store_dword v[0:1], v2, off offset:256
	v_mul_f32_e32 v2, v18, v16
	global_store_dword v[0:1], v2, off offset:384
	v_rcp_f32_e32 v2, v73
	v_or_b32_e32 v0, 3, v66
	v_ashrrev_i32_e32 v1, 31, v0
	v_lshlrev_b64 v[0:1], 11, v[0:1]
	v_lshl_add_u64 v[0:1], v[64:65], 0, v[0:1]
	v_mul_f32_e32 v3, v3, v2
	global_store_dword v[0:1], v3, off
	v_mul_f32_e32 v3, v51, v2
	global_store_dword v[0:1], v3, off offset:128
	v_mul_f32_e32 v3, v35, v2
	v_mul_f32_e32 v2, v19, v2
	global_store_dword v[0:1], v2, off offset:384
	v_rcp_f32_e32 v2, v74
	global_store_dword v[0:1], v3, off offset:256
	v_or_b32_e32 v0, 8, v66
	v_ashrrev_i32_e32 v1, 31, v0
	v_lshlrev_b64 v[0:1], 11, v[0:1]
	v_lshl_add_u64 v[0:1], v[64:65], 0, v[0:1]
	v_mul_f32_e32 v3, v4, v2
	global_store_dword v[0:1], v3, off
	v_mul_f32_e32 v3, v52, v2
	global_store_dword v[0:1], v3, off offset:128
	v_mul_f32_e32 v3, v36, v2
	v_mul_f32_e32 v2, v20, v2
	global_store_dword v[0:1], v2, off offset:384
	v_rcp_f32_e32 v2, v75
	global_store_dword v[0:1], v3, off offset:256
	v_or_b32_e32 v0, 9, v66
	v_ashrrev_i32_e32 v1, 31, v0
	v_lshlrev_b64 v[0:1], 11, v[0:1]
	v_lshl_add_u64 v[0:1], v[64:65], 0, v[0:1]
	v_mul_f32_e32 v3, v5, v2
	global_store_dword v[0:1], v3, off
	v_mul_f32_e32 v3, v53, v2
	global_store_dword v[0:1], v3, off offset:128
	v_mul_f32_e32 v3, v37, v2
	v_mul_f32_e32 v2, v21, v2
	global_store_dword v[0:1], v2, off offset:384
	v_rcp_f32_e32 v2, v76
	global_store_dword v[0:1], v3, off offset:256
	v_or_b32_e32 v0, 10, v66
	v_ashrrev_i32_e32 v1, 31, v0
	v_lshlrev_b64 v[0:1], 11, v[0:1]
	v_lshl_add_u64 v[0:1], v[64:65], 0, v[0:1]
	v_mul_f32_e32 v3, v6, v2
	global_store_dword v[0:1], v3, off
	v_mul_f32_e32 v3, v54, v2
	global_store_dword v[0:1], v3, off offset:128
	v_mul_f32_e32 v3, v38, v2
	v_mul_f32_e32 v2, v22, v2
	v_rcp_f32_e32 v6, v77
	global_store_dword v[0:1], v3, off offset:256
	global_store_dword v[0:1], v2, off offset:384
	v_or_b32_e32 v0, 11, v66
	v_ashrrev_i32_e32 v1, 31, v0
	v_lshlrev_b64 v[0:1], 11, v[0:1]
	v_lshl_add_u64 v[4:5], v[64:65], 0, v[0:1]
	v_mul_f32_e32 v0, v7, v6
	global_store_dword v[4:5], v0, off
	v_mul_f32_e32 v0, v55, v6
	global_store_dword v[4:5], v0, off offset:128
	v_mul_f32_e32 v0, v39, v6
	global_store_dword v[4:5], v0, off offset:256
	ds_read_b128 v[0:3], v68 offset:64
	v_mul_f32_e32 v6, v23, v6
	global_store_dword v[4:5], v6, off offset:384
	ds_read_b128 v[4:7], v68 offset:96
	v_or_b32_e32 v16, 16, v66
	s_waitcnt lgkmcnt(0)
; DI unsigned short f2bf(float x) { unsigned u = __float_as_uint(x); u += 0x7fffu + ((u >> 16) & 1u); return (unsigned short)(u >> 16); }
; DI int crow(int r, int hi) { return (r & 3) + 8 * (r >> 2) + 4 * hi; }
; template <int DQK, int MODE, int LDQ, int LDK, int LDV> ...
;     ...
;     for (int r = 0; r < 16; ++r) { const int orow = wid * 32 + crow(r, hi); const float rl = __builtin_amdgcn_rcpf(li_l[crow(r, hi)]);
;         if constexpr (MODE == 0) {
; #pragma unroll
;             for (int d0 = 0; d0 < 4; ++d0) AOb[(size_t)orow * 1024 + d0 * 32 + r32] = f2bf(o[d0][r] * rl);
;         } else if constexpr (MODE == 1) {
; #pragma unroll
;             for (int d0 = 0; d0 < 4; ++d0) S0[(size_t)orow * 512 + d0 * 32 + r32] = o[d0][r] * rl;
; DI void phase4(const Params& p, LAS unsigned char* lds, int wv) {
;     ...
;             att::attn_body<64, 1, 2048, 2048, 2048>(P + qrow * 2048 + 512 + h * 128, P + rowbase * 2048 + 1024 + h * 128, P + rowbase * 2048 + 1536 + h * 128, qb * 256, 0.f,
;                                                    nullptr, S0 + qrow * 512 + h * 128, nullptr, 0.f, nullptr, lds, wv);
;             __syncthreads();
;             att::attn_body<64, 2, 2048, 2048, 2048>(P + qrow * 2048 + 512 + h * 128 + 64, P + rowbase * 2048 + 1024 + h * 128 + 64, P + rowbase * 2048 + 1536 + h * 128, qb * 256, 0.f,
	v_rcp_f32_e32 v0, v0
	v_ashrrev_i32_e32 v17, 31, v16
	v_lshlrev_b64 v[16:17], 11, v[16:17]
	v_lshl_add_u64 v[16:17], v[64:65], 0, v[16:17]
	v_mul_f32_e32 v8, v8, v0
	global_store_dword v[16:17], v8, off
	v_mul_f32_e32 v8, v56, v0
	global_store_dword v[16:17], v8, off offset:128
	v_mul_f32_e32 v8, v40, v0
	global_store_dword v[16:17], v8, off offset:256
	v_mul_f32_e32 v0, v24, v0
	v_rcp_f32_e32 v8, v1
	global_store_dword v[16:17], v0, off offset:384
	v_or_b32_e32 v0, 17, v66
	v_ashrrev_i32_e32 v1, 31, v0
	v_lshlrev_b64 v[0:1], 11, v[0:1]
	v_lshl_add_u64 v[0:1], v[64:65], 0, v[0:1]
	v_mul_f32_e32 v9, v9, v8
	global_store_dword v[0:1], v9, off
	v_mul_f32_e32 v9, v57, v8
	global_store_dword v[0:1], v9, off offset:128
	v_mul_f32_e32 v9, v41, v8
	v_mul_f32_e32 v8, v25, v8
	v_rcp_f32_e32 v2, v2
	global_store_dword v[0:1], v9, off offset:256
	global_store_dword v[0:1], v8, off offset:384
	v_or_b32_e32 v0, 18, v66
	v_ashrrev_i32_e32 v1, 31, v0
	v_lshlrev_b64 v[0:1], 11, v[0:1]
	v_lshl_add_u64 v[0:1], v[64:65], 0, v[0:1]
	v_mul_f32_e32 v8, v10, v2
	global_store_dword v[0:1], v8, off
	v_mul_f32_e32 v8, v58, v2
	global_store_dword v[0:1], v8, off offset:128
	v_mul_f32_e32 v8, v42, v2
	v_mul_f32_e32 v2, v26, v2
	global_store_dword v[0:1], v2, off offset:384
	v_rcp_f32_e32 v2, v3
	global_store_dword v[0:1], v8, off offset:256
	v_or_b32_e32 v0, 19, v66
	v_ashrrev_i32_e32 v1, 31, v0
	v_lshlrev_b64 v[0:1], 11, v[0:1]
	v_lshl_add_u64 v[0:1], v[64:65], 0, v[0:1]
	v_mul_f32_e32 v3, v11, v2
	global_store_dword v[0:1], v3, off
	v_mul_f32_e32 v3, v59, v2
	global_store_dword v[0:1], v3, off offset:128
	v_mul_f32_e32 v3, v43, v2
	v_mul_f32_e32 v2, v27, v2
	global_store_dword v[0:1], v2, off offset:384
	v_rcp_f32_e32 v2, v4
	global_store_dword v[0:1], v3, off offset:256
	v_or_b32_e32 v0, 24, v66
	v_ashrrev_i32_e32 v1, 31, v0
	v_lshlrev_b64 v[0:1], 11, v[0:1]
	v_lshl_add_u64 v[0:1], v[64:65], 0, v[0:1]
	v_mul_f32_e32 v3, v12, v2
	global_store_dword v[0:1], v3, off
	v_mul_f32_e32 v3, v60, v2
	global_store_dword v[0:1], v3, off offset:128
	v_mul_f32_e32 v3, v44, v2
	v_mul_f32_e32 v2, v28, v2
	global_store_dword v[0:1], v2, off offset:384
	v_rcp_f32_e32 v2, v5
	global_store_dword v[0:1], v3, off offset:256
	v_or_b32_e32 v0, 25, v66
	v_ashrrev_i32_e32 v1, 31, v0
	v_lshlrev_b64 v[0:1], 11, v[0:1]
	v_lshl_add_u64 v[0:1], v[64:65], 0, v[0:1]
	v_mul_f32_e32 v3, v13, v2
	global_store_dword v[0:1], v3, off
	v_mul_f32_e32 v3, v61, v2
	global_store_dword v[0:1], v3, off offset:128
	v_mul_f32_e32 v3, v45, v2
	v_mul_f32_e32 v2, v29, v2
	global_store_dword v[0:1], v2, off offset:384
	v_rcp_f32_e32 v2, v6
	global_store_dword v[0:1], v3, off offset:256
	v_or_b32_e32 v0, 26, v66
	v_ashrrev_i32_e32 v1, 31, v0
	v_lshlrev_b64 v[0:1], 11, v[0:1]
	v_lshl_add_u64 v[0:1], v[64:65], 0, v[0:1]
	v_mul_f32_e32 v3, v14, v2
	global_store_dword v[0:1], v3, off
	v_mul_f32_e32 v3, v62, v2
	global_store_dword v[0:1], v3, off offset:128
	v_mul_f32_e32 v3, v46, v2
	v_mul_f32_e32 v2, v30, v2
	global_store_dword v[0:1], v2, off offset:384
	v_rcp_f32_e32 v2, v7
	global_store_dword v[0:1], v3, off offset:256
	v_or_b32_e32 v0, 27, v66
	v_ashrrev_i32_e32 v1, 31, v0
	v_lshlrev_b64 v[0:1], 11, v[0:1]
	v_lshl_add_u64 v[0:1], v[64:65], 0, v[0:1]
	v_mul_f32_e32 v3, v15, v2
	global_store_dword v[0:1], v3, off
	v_mul_f32_e32 v3, v63, v2
	global_store_dword v[0:1], v3, off offset:128
	v_mul_f32_e32 v3, v47, v2
	v_mul_f32_e32 v2, v31, v2
	global_store_dword v[0:1], v3, off offset:256
	global_store_dword v[0:1], v2, off offset:384
	s_waitcnt vmcnt(0)
	s_barrier
; #define LAS __attribute__((address_space(3)))
; template <int DQK, int MODE, int LDQ, int LDK, int LDV> ...
;     ...
;     int tid_ = fresh_tid<100 + MODE>(wv); const int tid = tid_, wid = __builtin_amdgcn_readfirstlane(tid >> 6), lane = tid & 63, r32 = lane & 31, hi = lane >> 5;
;     LAS float* ws = (LAS float*)(lds + WS_OFF) + wid * 64; LAS float* li_l = ws;
;     const LAS float* bt = (const LAS float*)(lds + BT_OFF);
;     float l_reg = 0.f; f32x16 o[4];
; #pragma unroll
;     for (int d = 0; d < 4; ++d)
; #pragma unroll
;         for (int r = 0; r < 16; ++r) o[d][r] = 0.f;
;     int kgo[NKP], vgo[2];
; #pragma unroll
;     for (int i = 0; i < NKP; ++i) { const int L = (wid + 8 * i) * 64 + lane, row = L / CPR, slot = L % CPR, cc = (slot & ~7) | ((slot & 7) ^ ((row >> 1) & 7)); kgo[i] = row * LDK + cc * 8; }
; #pragma unroll
;     for (int i = 0; i < 2; ++i) { const int L = (2 * wid + i) * 64 + lane, st = L >> 5, w5 = L & 31, kk = (st >> 2) * 8 + (w5 >> 2), c = (st & 3) * 32 + (w5 & 3) * 8;
;         const int k = (kk & ~0xC) | ((kk & 4) << 1) | ((kk & 8) >> 1); vgo[i] = k * LDV + c; }
;     ...
;     ATT_DMA_K(0); ATT_DMA_K(1); ATT_DMA_V(0, 0); ATT_DMA_K(2); ATT_DMA_V(1, 1);
;     bf16x8 qr[ND0];
;     { const bf16_t* Qw = Qb + (size_t)(wid * 32 + r32) * LDQ + hi * 8;
; #pragma unroll
;       for (int d0 = 0; d0 < ND0; ++d0) qr[d0] = *(const bf16x8*)(Qw + d0 * 16);
;       if constexpr (MODE == 0) {
;           float ss = 0.f;
; #pragma unroll
;           for (int d0 = 0; d0 < ND0; ++d0)
; #pragma unroll
;               for (int j = 0; j < 8; ++j) { const float f = bf2f((unsigned short)qr[d0][j]); ss += f * f; }
;           ss = swap_sum(ss);
;           const float rstd = rsqrtf(ss * (1.f / DQK) + EPS) * C;
; #pragma unroll
;           for (int d0 = 0; d0 < ND0; ++d0) { const float* g = gq + d0 * 16 + hi * 8;
;               { float f[8]; _Pragma("unroll") for (int j = 0; j < 8; ++j) f[j] = bf2f((unsigned short)qr[d0][j]) * rstd * g[j];
;                 u32x4 w = {cvtpk(f[0], f[1]), cvtpk(f[2], f[3]), cvtpk(f[4], f[5]), cvtpk(f[6], f[7])}; qr[d0] = __builtin_bit_cast(bf16x8, w); asm volatile("" ::: "memory"); } }
;       } }
;     const int qlo = q0 + wid * 32, qpos = qlo + r32;
;     const int tL = MODE == 0 ? 0 : (qlo >= 191 ? (qlo - 127) >> 6 : 0), tR = MODE == 0 ? NT : min(NT, (qlo + 222) >> 6);
	v_mbcnt_lo_u32_b32 v7, -1, 0
	v_mbcnt_hi_u32_b32 v7, -1, v7
	s_mov_b64 s[4:5], 0x880
	v_add_u32_e32 v0, s33, v7
	v_bfe_u32 v4, v0, 2, 2
	v_readfirstlane_b32 s0, v0
	s_ashr_i32 s2, s0, 31
	s_ashr_i32 s1, s0, 6
	v_mov_b32_e32 v1, s0
	v_bfi_b32 v1, s63, v1, v7
	s_lshr_b32 s2, s2, 29
	v_add_u32_e32 v3, s2, v1
	s_lshl_b32 s2, s1, 7
	v_ashrrev_i32_e32 v9, 3, v3
	v_and_b32_e32 v3, 0x1ffffff8, v3
	s_ashr_i32 s3, s2, 4
	v_lshrrev_b32_e32 v0, 1, v0
	v_sub_u32_e32 v1, v1, v3
	v_lshrrev_b32_e32 v3, 1, v9
	v_lshlrev_b32_e32 v18, 3, v7
	s_and_b32 s2, s3, -16
	v_and_b32_e32 v6, 8, v0
	s_lshr_b32 s3, s3, 1
	v_bitop3_b32 v1, v3, v1, 7 bitop3:0x6c
	v_and_b32_e32 v3, 32, v7
	v_and_b32_e32 v5, 24, v18
	s_and_b32 s3, s3, 4
	v_or3_b32 v0, v6, v4, s2
	v_or_b32_e32 v10, v3, v5
	v_or_b32_e32 v0, s3, v0
	v_lshl_or_b32 v96, v0, 11, v10
	v_lshlrev_b32_e32 v0, 11, v9
	v_lshl_add_u32 v0, v1, 3, v0
	v_ashrrev_i32_e32 v1, 31, v0
	v_lshlrev_b64 v[10:11], 1, v[0:1]
	v_lshl_add_u64 v[12:13], s[46:47], 0, v[10:11]
	v_lshl_add_u64 v[12:13], v[12:13], 0, s[4:5]
	s_lshl_b32 s4, s1, 10
	s_add_i32 s94, s4, 0
	s_mov_b32 m0, s94
	v_lshl_add_u64 v[10:11], s[48:49], 0, v[10:11]
	s_mov_b64 s[4:5], 0x40080
	global_load_lds_dwordx4 v[12:13], off
	v_lshl_add_u64 v[12:13], v[10:11], 0, s[4:5]
	s_add_i32 m0, s94, 0x2000
	s_lshl_b32 s4, s1, 11
	v_ashrrev_i32_e32 v97, 31, v96
	global_load_lds_dwordx4 v[12:13], off
	s_add_i32 s6, s4, 0
	v_lshlrev_b64 v[12:13], 1, v[96:97]
	s_add_i32 s48, s6, 0x18000
	v_lshl_add_u64 v[14:15], s[46:47], 0, v[12:13]
	v_lshl_add_u64 v[16:17], v[14:15], 0, s[96:97]
	s_mov_b32 m0, s48
	s_mov_b64 s[4:5], 0xc80
	global_load_lds_dwordx4 v[16:17], off
	v_lshl_add_u64 v[14:15], v[14:15], 0, s[4:5]
	s_add_i32 m0, s6, 0x18400
	s_mov_b64 s[4:5], 0x80080
	v_or_b32_e32 v98, 64, v96
	global_load_lds_dwordx4 v[14:15], off
	v_lshl_add_u64 v[10:11], v[10:11], 0, s[4:5]
	s_add_i32 m0, s94, 0x4000
	v_ashrrev_i32_e32 v99, 31, v98
	global_load_lds_dwordx4 v[10:11], off
	s_add_i32 m0, s6, 0x1c000
	v_lshl_add_u64 v[10:11], s[52:53], 0, v[12:13]
	v_and_b32_e32 v2, 31, v7
	global_load_lds_dwordx4 v[10:11], off
	v_lshl_add_u64 v[10:11], v[98:99], 1, s[52:53]
	s_add_i32 m0, s6, 0x1c400
	s_lshl_b32 s46, s1, 5
	global_load_lds_dwordx4 v[10:11], off
	v_or_b32_e32 v10, s46, v2
	v_ashrrev_i32_e32 v11, 31, v10
	v_bfe_u32 v8, v7, 5, 1
	v_lshlrev_b64 v[10:11], 12, v[10:11]
	v_lshl_add_u64 v[10:11], s[44:45], 0, v[10:11]
	v_lshlrev_b32_e32 v130, 4, v8
	v_lshl_add_u64 v[10:11], v[10:11], 0, v[130:131]
	global_load_dwordx4 v[92:95], v[10:11], off offset:1152
	global_load_dwordx4 v[88:91], v[10:11], off offset:1184
	global_load_dwordx4 v[84:87], v[10:11], off offset:1216
	global_load_dwordx4 v[80:83], v[10:11], off offset:1248
	v_and_b32_e32 v11, 0x70, v18
	v_mov_b32_e32 v9, s88
	v_mov_b32_e32 v10, s81
	v_lshl_add_u32 v114, v2, 7, 0
	v_bitop3_b32 v115, v130, v18, s64 bitop3:0x78
	v_bitop3_b32 v117, v130, v11, 64 bitop3:0x36
	s_add_i32 s4, s46, s89
	ds_read_b32 v9, v9
	ds_read_b32 v10, v10
	s_waitcnt vmcnt(3)
	s_barrier
	v_add_u32_e32 v107, v114, v115
	v_bitop3_b32 v116, v130, v11, 32 bitop3:0x36
	v_add_u32_e32 v109, v114, v117
	v_bitop3_b32 v118, v130, v11, s65 bitop3:0x36
	s_add_i32 s5, s4, 0xffffff81
	v_add_u32_e32 v108, v114, v116
	ds_read_b128 v[12:15], v107
	ds_read_b128 v[16:19], v108
	v_add_u32_e32 v110, v114, v118
	ds_read_b128 v[20:23], v109
	ds_read_b128 v[24:27], v110
	s_ashr_i32 s5, s5, 6
	s_cmpk_gt_i32 s4, 0xbe
	v_or_b32_e32 v111, s4, v2
	s_cselect_b32 s47, s5, 0
	s_addk_i32 s4, 0xde
	s_ashr_i32 s45, s4, 6
	s_waitcnt lgkmcnt(0)
	s_waitcnt vmcnt(0) lgkmcnt(0)
	v_mfma_f32_32x32x16_bf16 v[64:79], v[12:15], v[92:95], 0
	s_cmp_gt_i32 s47, 0
	s_cselect_b64 s[4:5], -1, 0
	s_cmp_lt_i32 s45, 1
	s_cselect_b64 s[6:7], -1, 0
	s_or_b64 s[4:5], s[6:7], s[4:5]
	s_and_b64 vcc, exec, s[4:5]
	v_mfma_f32_32x32x16_bf16 v[64:79], v[16:19], v[88:91], v[64:79]
	v_mfma_f32_32x32x16_bf16 v[64:79], v[20:23], v[84:87], v[64:79]
	v_mfma_f32_32x32x16_bf16 v[64:79], v[24:27], v[80:83], v[64:79]
	s_cbranch_vccnz .LBB0_1948
	v_lshlrev_b32_e32 v8, 2, v8
	v_sub_u32_e32 v8, v8, v111
	v_lshl_add_u32 v8, v8, 2, s88
	ds_read2_b32 v[12:13], v8 offset0:240 offset1:241
	ds_read2_b32 v[14:15], v8 offset0:242 offset1:243
	ds_read2_b32 v[16:17], v8 offset0:248 offset1:249
	ds_read2_b32 v[18:19], v8 offset0:250 offset1:251
	ds_read2_b32 v[20:21], v8 offset0:224 offset1:225
	ds_read2_b32 v[22:23], v8 offset0:226 offset1:227
	ds_read2_b32 v[24:25], v8 offset0:232 offset1:233
	ds_read2_b32 v[26:27], v8 offset0:234 offset1:235
	s_waitcnt lgkmcnt(4)
	v_pk_add_f32 v[78:79], v[78:79], v[18:19]
	v_pk_add_f32 v[76:77], v[76:77], v[16:17]
	v_pk_add_f32 v[74:75], v[74:75], v[14:15]
	v_pk_add_f32 v[72:73], v[72:73], v[12:13]
	s_waitcnt lgkmcnt(0)
	v_pk_add_f32 v[70:71], v[70:71], v[26:27]
	v_pk_add_f32 v[68:69], v[68:69], v[24:25]
	v_pk_add_f32 v[66:67], v[66:67], v[22:23]
	v_pk_add_f32 v[64:65], v[64:65], v[20:21]

; #define LAS __attribute__((address_space(3)))
; DI void expsum(f32x16& p, float& l_reg, bf16x8& pa0, bf16x8& pa1) {
; #pragma unroll
;     for (int r = 0; r < 16; ++r) p[r] = __builtin_amdgcn_exp2f(p[r]);
;     float ps = 0.f;
; #pragma unroll
;     for (int r = 0; r < 16; ++r) ps += p[r];
;     l_reg += ps; asm volatile("" : "+v"(l_reg));
;     ...
;     ATT_PK4(p, 0, pa0); ATT_PK4(p, 8, pa1);
;     ...
; }
; DI int v_rd_base(int lane) { return ((lane & 3) << 3) | (((lane >> 2) & 3) << 6) | (((lane >> 4) & 1) << 5) | (((lane >> 5) & 1) << 8); }
; template <int OFF> DI s16x4 tr_read(int vb) { s16x4 r; asm volatile("ds_read_b64_tr_b16 %0, %1 offset:%2" : "=&v"(r) : "v"(vb), "i"(OFF) : "memory"); return r; }
; template <int H> DI void v_reads(s16x4* vf, int vb) {
;     vf[0] = tr_read<v_rd_off(0, 2 * H, 0)>(vb); vf[1] = tr_read<v_rd_off(0, 2 * H, 1)>(vb); vf[2] = tr_read<v_rd_off(0, 2 * H + 1, 0)>(vb); vf[3] = tr_read<v_rd_off(0, 2 * H + 1, 1)>(vb);
;     vf[4] = tr_read<v_rd_off(1, 2 * H, 0)>(vb); vf[5] = tr_read<v_rd_off(1, 2 * H, 1)>(vb); vf[6] = tr_read<v_rd_off(1, 2 * H + 1, 0)>(vb); vf[7] = tr_read<v_rd_off(1, 2 * H + 1, 1)>(vb);
;     vf[8] = tr_read<v_rd_off(2, 2 * H, 0)>(vb); vf[9] = tr_read<v_rd_off(2, 2 * H, 1)>(vb); vf[10] = tr_read<v_rd_off(2, 2 * H + 1, 0)>(vb); vf[11] = tr_read<v_rd_off(2, 2 * H + 1, 1)>(vb);
;     vf[12] = tr_read<v_rd_off(3, 2 * H, 0)>(vb); vf[13] = tr_read<v_rd_off(3, 2 * H, 1)>(vb); vf[14] = tr_read<v_rd_off(3, 2 * H + 1, 0)>(vb); vf[15] = tr_read<v_rd_off(3, 2 * H + 1, 1)>(vb);
; }
; DI void pv_mma(f32x16* o, const s16x4* vf, bf16x8 pa0, bf16x8 pa1) {
;     ...
; #pragma unroll
;     for (int d0 = 0; d0 < 4; ++d0) {
;         o[d0] = __builtin_amdgcn_mfma_f32_32x32x16_bf16(pa0, ATT_PK(vf[4 * d0], vf[4 * d0 + 1]), o[d0], 0, 0, 0);
;         o[d0] = __builtin_amdgcn_mfma_f32_32x32x16_bf16(pa1, ATT_PK(vf[4 * d0 + 2], vf[4 * d0 + 3]), o[d0], 0, 0, 0); }
;     ...
; }
; template <int DQK, int D0A, int D0B> DI void k_reads(bf16x8* kf, const LAS unsigned char* Ks, int half, int r32, int hi) {
; #pragma unroll
;     for (int d0 = D0A; d0 < D0B; ++d0) kf[d0 - D0A] = *(const LAS bf16x8*)(Ks + half * (32 * DQK * 2) + kswz<DQK>(r32, (d0 * 16 + hi * 8) * 2));
; }
; template <int D0A, int D0B> DI void qk_mma(f32x16& p, const bf16x8* kf, const bf16x8* qr) {
; #pragma unroll
;     for (int d0 = D0A; d0 < D0B; ++d0) {
.LBB0_1953:
	s_add_i32 s3, s0, -1
	s_add_i32 s2, s22, 0xffffa000
	s_and_b32 s2, s2, 0x6000
	v_add_u32_e32 v121, s2, v114
	v_add_u32_e32 v122, v121, v115
	v_add_u32_e32 v126, v121, v116
	ds_read_b128 v[122:125], v122 offset:4096
	ds_read_b128 v[132:135], v126 offset:4096
	v_add_u32_e32 v126, v121, v117
	v_add_u32_e32 v121, v121, v118
	s_lshl_b32 s2, s23, 14
	ds_read_b128 v[136:139], v126 offset:4096
	ds_read_b128 v[140:143], v121 offset:4096
	v_add_u32_e32 v121, s2, v106
	ds_read_b64_tr_b16 v[144:145], v121 offset:0
	ds_read_b64_tr_b16 v[146:147], v121 offset:0x800
	ds_read_b64_tr_b16 v[148:149], v121 offset:0x1000
	ds_read_b64_tr_b16 v[150:151], v121 offset:0x1800
	ds_read_b64_tr_b16 v[152:153], v121 offset:0x200
	ds_read_b64_tr_b16 v[154:155], v121 offset:0xa00
	ds_read_b64_tr_b16 v[156:157], v121 offset:0x1200
	ds_read_b64_tr_b16 v[158:159], v121 offset:0x1a00
	ds_read_b64_tr_b16 v[162:163], v121 offset:0x400
	ds_read_b64_tr_b16 v[164:165], v121 offset:0xc00
	ds_read_b64_tr_b16 v[166:167], v121 offset:0x1400
	ds_read_b64_tr_b16 v[168:169], v121 offset:0x1c00
	ds_read_b64_tr_b16 v[170:171], v121 offset:0x600
	ds_read_b64_tr_b16 v[172:173], v121 offset:0xe00
	ds_read_b64_tr_b16 v[174:175], v121 offset:0x1600
	ds_read_b64_tr_b16 v[176:177], v121 offset:0x1e00
	s_setprio 2
	v_exp_f32_e32 v64, v64
	v_exp_f32_e32 v65, v65
	v_exp_f32_e32 v66, v66
	v_exp_f32_e32 v67, v67
	v_exp_f32_e32 v68, v68
	v_exp_f32_e32 v69, v69
	v_exp_f32_e32 v70, v70
	v_exp_f32_e32 v71, v71
	v_exp_f32_e32 v72, v72
	v_exp_f32_e32 v73, v73
	v_exp_f32_e32 v74, v74
	v_exp_f32_e32 v75, v75
	v_exp_f32_e32 v76, v76
	v_exp_f32_e32 v77, v77
	v_exp_f32_e32 v78, v78
	v_exp_f32_e32 v79, v79
	v_add_f32_e32 v126, v65, v64
	v_add_f32_e32 v126, v66, v126
	v_add_f32_e32 v126, v67, v126
	v_add_f32_e32 v126, v68, v126
	v_add_f32_e32 v126, v69, v126
	v_add_f32_e32 v126, v70, v126
	v_add_f32_e32 v126, v71, v126
	v_add_f32_e32 v126, v72, v126
	v_add_f32_e32 v126, v73, v126
	v_add_f32_e32 v126, v74, v126
	v_add_f32_e32 v126, v75, v126
	v_add_f32_e32 v126, v76, v126
	v_add_f32_e32 v126, v77, v126
	v_add_f32_e32 v126, v78, v126
	v_add_f32_e32 v126, v79, v126
	v_add_f32_e32 v120, v126, v120
	v_cvt_pk_bf16_f32 v64, v64, v65
	v_cvt_pk_bf16_f32 v65, v66, v67
	v_cvt_pk_bf16_f32 v66, v68, v69
	v_cvt_pk_bf16_f32 v67, v70, v71
	v_cvt_pk_bf16_f32 v68, v72, v73
	v_cvt_pk_bf16_f32 v69, v74, v75
	v_cvt_pk_bf16_f32 v70, v76, v77
	v_cvt_pk_bf16_f32 v71, v78, v79
	s_nop 0
	v_permlane32_swap_b32_e32 v64, v66
	v_permlane32_swap_b32_e32 v65, v67
	v_permlane32_swap_b32_e32 v68, v70
	v_permlane32_swap_b32_e32 v69, v71
	s_waitcnt lgkmcnt(0)
	s_setprio 1
	v_mfma_f32_32x32x16_bf16 v[0:15], v[64:67], v[144:147], v[0:15]
	s_cmp_lt_i32 s3, s47
	s_cselect_b64 s[74:75], -1, 0
	s_cmp_ge_i32 s3, s52
	s_cselect_b64 s[90:91], -1, 0
	s_or_b64 s[74:75], s[74:75], s[90:91]
	s_and_b64 vcc, exec, s[74:75]
	v_mfma_f32_32x32x16_bf16 v[48:63], v[64:67], v[152:155], v[48:63]
	v_mfma_f32_32x32x16_bf16 v[16:31], v[64:67], v[162:165], v[16:31]
	v_mfma_f32_32x32x16_bf16 v[32:47], v[64:67], v[170:173], v[32:47]
	v_mfma_f32_32x32x16_bf16 v[0:15], v[68:71], v[148:151], v[0:15]
	v_mfma_f32_32x32x16_bf16 v[48:63], v[68:71], v[156:159], v[48:63]
	v_mfma_f32_32x32x16_bf16 v[16:31], v[68:71], v[166:169], v[16:31]
	v_mfma_f32_32x32x16_bf16 v[32:47], v[68:71], v[174:177], v[32:47]
	v_mfma_f32_32x32x16_bf16 v[64:79], v[122:125], v[92:95], 0
	v_mfma_f32_32x32x16_bf16 v[64:79], v[132:135], v[88:91], v[64:79]
	v_mfma_f32_32x32x16_bf16 v[64:79], v[136:139], v[84:87], v[64:79]
	v_mfma_f32_32x32x16_bf16 v[64:79], v[140:143], v[80:83], v[64:79]
	s_setprio 0
	v_add_u32_e32 v122, s7, v119
	s_cbranch_vccnz .LBB0_1955
	v_add_u32_e32 v138, 0x28908, v122
	v_add_u32_e32 v140, 0x28920, v122
	v_add_u32_e32 v142, 0x28928, v122
	v_add_u32_e32 v124, 0x28940, v122
	v_add_u32_e32 v126, 0x28948, v122
	v_add_u32_e32 v132, 0x28960, v122
	v_add_u32_e32 v134, 0x28968, v122
	v_add_u32_e32 v123, 0x28900, v122
	ds_read2_b32 v[124:125], v124 offset1:1
	ds_read2_b32 v[126:127], v126 offset1:1
	ds_read2_b32 v[132:133], v132 offset1:1
	ds_read2_b32 v[134:135], v134 offset1:1
	ds_read2_b32 v[136:137], v123 offset1:1
	ds_read2_b32 v[138:139], v138 offset1:1
	ds_read2_b32 v[140:141], v140 offset1:1
	ds_read2_b32 v[142:143], v142 offset1:1
	s_waitcnt lgkmcnt(0)
	v_pk_add_f32 v[78:79], v[78:79], v[134:135]
	v_pk_add_f32 v[76:77], v[76:77], v[132:133]
	v_pk_add_f32 v[74:75], v[74:75], v[126:127]
	v_pk_add_f32 v[72:73], v[72:73], v[124:125]
	v_pk_add_f32 v[70:71], v[70:71], v[142:143]
	v_pk_add_f32 v[68:69], v[68:69], v[140:141]
	v_pk_add_f32 v[66:67], v[66:67], v[138:139]
	v_pk_add_f32 v[64:65], v[64:65], v[136:137]

; #define LAS __attribute__((address_space(3)))
; DI void expsum(f32x16& p, float& l_reg, bf16x8& pa0, bf16x8& pa1) {
; #pragma unroll
;     for (int r = 0; r < 16; ++r) p[r] = __builtin_amdgcn_exp2f(p[r]);
;     float ps = 0.f;
; #pragma unroll
;     for (int r = 0; r < 16; ++r) ps += p[r];
;     l_reg += ps; asm volatile("" : "+v"(l_reg));
;     ...
;     ATT_PK4(p, 0, pa0); ATT_PK4(p, 8, pa1);
;     ...
; }
; DI int v_rd_base(int lane) { return ((lane & 3) << 3) | (((lane >> 2) & 3) << 6) | (((lane >> 4) & 1) << 5) | (((lane >> 5) & 1) << 8); }
; template <int OFF> DI s16x4 tr_read(int vb) { s16x4 r; asm volatile("ds_read_b64_tr_b16 %0, %1 offset:%2" : "=&v"(r) : "v"(vb), "i"(OFF) : "memory"); return r; }
; template <int H> DI void v_reads(s16x4* vf, int vb) {
;     vf[0] = tr_read<v_rd_off(0, 2 * H, 0)>(vb); vf[1] = tr_read<v_rd_off(0, 2 * H, 1)>(vb); vf[2] = tr_read<v_rd_off(0, 2 * H + 1, 0)>(vb); vf[3] = tr_read<v_rd_off(0, 2 * H + 1, 1)>(vb);
;     vf[4] = tr_read<v_rd_off(1, 2 * H, 0)>(vb); vf[5] = tr_read<v_rd_off(1, 2 * H, 1)>(vb); vf[6] = tr_read<v_rd_off(1, 2 * H + 1, 0)>(vb); vf[7] = tr_read<v_rd_off(1, 2 * H + 1, 1)>(vb);
;     vf[8] = tr_read<v_rd_off(2, 2 * H, 0)>(vb); vf[9] = tr_read<v_rd_off(2, 2 * H, 1)>(vb); vf[10] = tr_read<v_rd_off(2, 2 * H + 1, 0)>(vb); vf[11] = tr_read<v_rd_off(2, 2 * H + 1, 1)>(vb);
;     vf[12] = tr_read<v_rd_off(3, 2 * H, 0)>(vb); vf[13] = tr_read<v_rd_off(3, 2 * H, 1)>(vb); vf[14] = tr_read<v_rd_off(3, 2 * H + 1, 0)>(vb); vf[15] = tr_read<v_rd_off(3, 2 * H + 1, 1)>(vb);
; }
; DI void pv_mma(f32x16* o, const s16x4* vf, bf16x8 pa0, bf16x8 pa1) {
;     ...
; #pragma unroll
;     for (int d0 = 0; d0 < 4; ++d0) {
;         o[d0] = __builtin_amdgcn_mfma_f32_32x32x16_bf16(pa0, ATT_PK(vf[4 * d0], vf[4 * d0 + 1]), o[d0], 0, 0, 0);
;         o[d0] = __builtin_amdgcn_mfma_f32_32x32x16_bf16(pa1, ATT_PK(vf[4 * d0 + 2], vf[4 * d0 + 3]), o[d0], 0, 0, 0); }
;     ...
; }
; template <int DQK, int D0A, int D0B> DI void k_reads(bf16x8* kf, const LAS unsigned char* Ks, int half, int r32, int hi) {
; #pragma unroll
;     for (int d0 = D0A; d0 < D0B; ++d0) kf[d0 - D0A] = *(const LAS bf16x8*)(Ks + half * (32 * DQK * 2) + kswz<DQK>(r32, (d0 * 16 + hi * 8) * 2));
; }
; template <int D0A, int D0B> DI void qk_mma(f32x16& p, const bf16x8* kf, const bf16x8* qr) {
; #pragma unroll
;     for (int d0 = D0A; d0 < D0B; ++d0) {
.LBB0_1961:
	ds_read_b128 v[98:101], v107 offset:12288
	ds_read_b128 v[102:105], v108 offset:12288
	ds_read_b128 v[114:117], v109 offset:12288
	ds_read_b128 v[122:125], v110 offset:12288
	v_lshl_add_u32 v96, s49, 14, v106
	ds_read_b64_tr_b16 v[132:133], v96 offset:0
	ds_read_b64_tr_b16 v[134:135], v96 offset:0x800
	ds_read_b64_tr_b16 v[136:137], v96 offset:0x1000
	ds_read_b64_tr_b16 v[138:139], v96 offset:0x1800
	ds_read_b64_tr_b16 v[140:141], v96 offset:0x200
	ds_read_b64_tr_b16 v[142:143], v96 offset:0xa00
	ds_read_b64_tr_b16 v[144:145], v96 offset:0x1200
	ds_read_b64_tr_b16 v[146:147], v96 offset:0x1a00
	ds_read_b64_tr_b16 v[148:149], v96 offset:0x400
	ds_read_b64_tr_b16 v[150:151], v96 offset:0xc00
	ds_read_b64_tr_b16 v[152:153], v96 offset:0x1400
	ds_read_b64_tr_b16 v[154:155], v96 offset:0x1c00
	ds_read_b64_tr_b16 v[156:157], v96 offset:0x600
	ds_read_b64_tr_b16 v[158:159], v96 offset:0xe00
	ds_read_b64_tr_b16 v[162:163], v96 offset:0x1600
	ds_read_b64_tr_b16 v[164:165], v96 offset:0x1e00
	s_setprio 2
	v_exp_f32_e32 v64, v64
	v_exp_f32_e32 v65, v65
	v_exp_f32_e32 v66, v66
	v_exp_f32_e32 v67, v67
	v_exp_f32_e32 v68, v68
	v_exp_f32_e32 v69, v69
	v_exp_f32_e32 v70, v70
	v_exp_f32_e32 v71, v71
	v_exp_f32_e32 v72, v72
	v_exp_f32_e32 v73, v73
	v_exp_f32_e32 v74, v74
	v_exp_f32_e32 v75, v75
	v_exp_f32_e32 v76, v76
	v_exp_f32_e32 v77, v77
	v_exp_f32_e32 v78, v78
	v_exp_f32_e32 v79, v79
	v_add_f32_e32 v97, v65, v64
	v_add_f32_e32 v97, v66, v97
	v_add_f32_e32 v97, v67, v97
	v_add_f32_e32 v97, v68, v97
	v_add_f32_e32 v97, v69, v97
	v_add_f32_e32 v97, v70, v97
	v_add_f32_e32 v97, v71, v97
	v_add_f32_e32 v97, v72, v97
	v_add_f32_e32 v97, v73, v97
	v_add_f32_e32 v97, v74, v97
	v_add_f32_e32 v97, v75, v97
	v_add_f32_e32 v97, v76, v97
	v_add_f32_e32 v97, v77, v97
	v_add_f32_e32 v97, v78, v97
	v_add_f32_e32 v97, v79, v97
	v_add_f32_e32 v97, v97, v120
	v_cvt_pk_bf16_f32 v64, v64, v65
	v_cvt_pk_bf16_f32 v65, v66, v67
	v_cvt_pk_bf16_f32 v66, v68, v69
	v_cvt_pk_bf16_f32 v67, v70, v71
	v_cvt_pk_bf16_f32 v68, v72, v73
	v_cvt_pk_bf16_f32 v69, v74, v75
	v_cvt_pk_bf16_f32 v70, v76, v77
	v_cvt_pk_bf16_f32 v71, v78, v79
	s_nop 0
	v_permlane32_swap_b32_e32 v64, v66
	v_permlane32_swap_b32_e32 v65, v67
	v_permlane32_swap_b32_e32 v68, v70
	v_permlane32_swap_b32_e32 v69, v71
	s_waitcnt lgkmcnt(0)
	s_setprio 1
	v_mfma_f32_32x32x16_bf16 v[0:15], v[64:67], v[132:135], v[0:15]
	s_cmp_gt_i32 s47, 61
	s_cselect_b64 s[0:1], -1, 0
	s_cmp_lt_i32 s45, 62
	s_cselect_b64 s[2:3], -1, 0
	s_or_b64 s[0:1], s[0:1], s[2:3]
	s_and_b64 vcc, exec, s[0:1]
	v_mfma_f32_32x32x16_bf16 v[48:63], v[64:67], v[140:143], v[48:63]
	v_mfma_f32_32x32x16_bf16 v[16:31], v[64:67], v[148:151], v[16:31]
	v_mfma_f32_32x32x16_bf16 v[32:47], v[64:67], v[156:159], v[32:47]
	v_mfma_f32_32x32x16_bf16 v[0:15], v[68:71], v[136:139], v[0:15]
	v_mfma_f32_32x32x16_bf16 v[48:63], v[68:71], v[144:147], v[48:63]
	v_mfma_f32_32x32x16_bf16 v[16:31], v[68:71], v[152:155], v[16:31]
	v_mfma_f32_32x32x16_bf16 v[32:47], v[68:71], v[162:165], v[32:47]
	s_waitcnt lgkmcnt(0)
	v_mfma_f32_32x32x16_bf16 v[64:79], v[98:101], v[92:95], 0
	v_mfma_f32_32x32x16_bf16 v[64:79], v[102:105], v[88:91], v[64:79]
	v_mfma_f32_32x32x16_bf16 v[64:79], v[114:117], v[84:87], v[64:79]
	v_mfma_f32_32x32x16_bf16 v[64:79], v[122:125], v[80:83], v[64:79]
	s_setprio 0
	s_cbranch_vccnz .LBB0_1963
	v_sub_u32_e32 v98, 0xf40, v111
	v_lshlrev_b32_e32 v98, 2, v98
	v_add3_u32 v98, s88, v98, v130
	v_add_u32_e32 v114, 0x400, v98
	v_add_u32_e32 v116, 0x408, v98
	v_add_u32_e32 v118, 0x420, v98
	v_add_u32_e32 v120, 0x428, v98
	v_add_u32_e32 v99, 0x440, v98
	v_add_u32_e32 v100, 0x448, v98
	v_add_u32_e32 v102, 0x460, v98
	v_add_u32_e32 v104, 0x468, v98
	ds_read2_b32 v[98:99], v99 offset1:1
	ds_read2_b32 v[100:101], v100 offset1:1
	ds_read2_b32 v[102:103], v102 offset1:1
	ds_read2_b32 v[104:105], v104 offset1:1
	ds_read2_b32 v[114:115], v114 offset1:1
	ds_read2_b32 v[116:117], v116 offset1:1
	ds_read2_b32 v[118:119], v118 offset1:1
	ds_read2_b32 v[120:121], v120 offset1:1
	s_waitcnt lgkmcnt(0)
	v_pk_add_f32 v[78:79], v[78:79], v[104:105]
	v_pk_add_f32 v[76:77], v[76:77], v[102:103]
	v_pk_add_f32 v[74:75], v[74:75], v[100:101]
	v_pk_add_f32 v[72:73], v[72:73], v[98:99]
	v_pk_add_f32 v[70:71], v[70:71], v[120:121]
	v_pk_add_f32 v[68:69], v[68:69], v[118:119]
	v_pk_add_f32 v[66:67], v[66:67], v[116:117]
	v_pk_add_f32 v[64:65], v[64:65], v[114:115]
.LBB0_1963:
	ds_read_b128 v[98:101], v107 offset:16384
	ds_read_b128 v[102:105], v108 offset:16384
	ds_read_b128 v[114:117], v109 offset:16384
	ds_read_b128 v[118:121], v110 offset:16384
	ds_read_b64_tr_b16 v[122:123], v96 offset:0x2000
	ds_read_b64_tr_b16 v[124:125], v96 offset:0x2800
	ds_read_b64_tr_b16 v[132:133], v96 offset:0x3000
	ds_read_b64_tr_b16 v[134:135], v96 offset:0x3800
	ds_read_b64_tr_b16 v[136:137], v96 offset:0x2200
	ds_read_b64_tr_b16 v[138:139], v96 offset:0x2a00
	ds_read_b64_tr_b16 v[140:141], v96 offset:0x3200
	ds_read_b64_tr_b16 v[142:143], v96 offset:0x3a00
	ds_read_b64_tr_b16 v[144:145], v96 offset:0x2400
	ds_read_b64_tr_b16 v[146:147], v96 offset:0x2c00
	ds_read_b64_tr_b16 v[148:149], v96 offset:0x3400
	ds_read_b64_tr_b16 v[150:151], v96 offset:0x3c00
	ds_read_b64_tr_b16 v[152:153], v96 offset:0x2600
	ds_read_b64_tr_b16 v[154:155], v96 offset:0x2e00
	ds_read_b64_tr_b16 v[156:157], v96 offset:0x3600
	ds_read_b64_tr_b16 v[158:159], v96 offset:0x3e00
	s_nop 6
	s_setprio 2
	v_exp_f32_e32 v64, v64
	v_exp_f32_e32 v65, v65
	v_exp_f32_e32 v66, v66
	v_exp_f32_e32 v67, v67
	v_exp_f32_e32 v68, v68
	v_exp_f32_e32 v69, v69
	v_exp_f32_e32 v70, v70
	v_exp_f32_e32 v71, v71
	v_exp_f32_e32 v72, v72
	v_exp_f32_e32 v73, v73
	v_exp_f32_e32 v74, v74
	v_exp_f32_e32 v75, v75
	v_exp_f32_e32 v76, v76
	v_exp_f32_e32 v77, v77
	v_exp_f32_e32 v78, v78
	v_exp_f32_e32 v79, v79
	v_add_f32_e32 v96, v65, v64
	v_add_f32_e32 v96, v66, v96
	v_add_f32_e32 v96, v67, v96
	v_add_f32_e32 v96, v68, v96
	v_add_f32_e32 v96, v69, v96
	v_add_f32_e32 v96, v70, v96
	v_add_f32_e32 v96, v71, v96
	v_add_f32_e32 v96, v72, v96
	v_add_f32_e32 v96, v73, v96
	v_add_f32_e32 v96, v74, v96
	v_add_f32_e32 v96, v75, v96
	v_add_f32_e32 v96, v76, v96
	v_add_f32_e32 v96, v77, v96
	v_add_f32_e32 v96, v78, v96
	v_add_f32_e32 v96, v79, v96
	v_add_f32_e32 v96, v97, v96
	v_cvt_pk_bf16_f32 v64, v64, v65
	v_cvt_pk_bf16_f32 v65, v66, v67
	v_cvt_pk_bf16_f32 v66, v68, v69
	v_cvt_pk_bf16_f32 v67, v70, v71
	v_cvt_pk_bf16_f32 v68, v72, v73
	v_cvt_pk_bf16_f32 v69, v74, v75
	v_cvt_pk_bf16_f32 v70, v76, v77
	v_cvt_pk_bf16_f32 v71, v78, v79
	s_nop 0
	v_permlane32_swap_b32_e32 v64, v66
	v_permlane32_swap_b32_e32 v65, v67
	v_permlane32_swap_b32_e32 v68, v70
	v_permlane32_swap_b32_e32 v69, v71
	s_waitcnt lgkmcnt(0)
	s_setprio 1
	s_cmp_lt_u32 s33, 0x100
	s_cbranch_scc1 .Lstg_d1_m61_21
	s_waitcnt vmcnt(0)
	s_barrier

; #define LAS __attribute__((address_space(3)))
; DI void expsum(f32x16& p, float& l_reg, bf16x8& pa0, bf16x8& pa1) {
; #pragma unroll
;     for (int r = 0; r < 16; ++r) p[r] = __builtin_amdgcn_exp2f(p[r]);
;     float ps = 0.f;
; #pragma unroll
;     for (int r = 0; r < 16; ++r) ps += p[r];
;     l_reg += ps; asm volatile("" : "+v"(l_reg));
;     ...
;     ATT_PK4(p, 0, pa0); ATT_PK4(p, 8, pa1);
;     ...
; }
; DI int v_rd_base(int lane) { return ((lane & 3) << 3) | (((lane >> 2) & 3) << 6) | (((lane >> 4) & 1) << 5) | (((lane >> 5) & 1) << 8); }
; template <int OFF> DI s16x4 tr_read(int vb) { s16x4 r; asm volatile("ds_read_b64_tr_b16 %0, %1 offset:%2" : "=&v"(r) : "v"(vb), "i"(OFF) : "memory"); return r; }
; template <int H> DI void v_reads(s16x4* vf, int vb) {
;     vf[0] = tr_read<v_rd_off(0, 2 * H, 0)>(vb); vf[1] = tr_read<v_rd_off(0, 2 * H, 1)>(vb); vf[2] = tr_read<v_rd_off(0, 2 * H + 1, 0)>(vb); vf[3] = tr_read<v_rd_off(0, 2 * H + 1, 1)>(vb);
;     vf[4] = tr_read<v_rd_off(1, 2 * H, 0)>(vb); vf[5] = tr_read<v_rd_off(1, 2 * H, 1)>(vb); vf[6] = tr_read<v_rd_off(1, 2 * H + 1, 0)>(vb); vf[7] = tr_read<v_rd_off(1, 2 * H + 1, 1)>(vb);
;     vf[8] = tr_read<v_rd_off(2, 2 * H, 0)>(vb); vf[9] = tr_read<v_rd_off(2, 2 * H, 1)>(vb); vf[10] = tr_read<v_rd_off(2, 2 * H + 1, 0)>(vb); vf[11] = tr_read<v_rd_off(2, 2 * H + 1, 1)>(vb);
;     vf[12] = tr_read<v_rd_off(3, 2 * H, 0)>(vb); vf[13] = tr_read<v_rd_off(3, 2 * H, 1)>(vb); vf[14] = tr_read<v_rd_off(3, 2 * H + 1, 0)>(vb); vf[15] = tr_read<v_rd_off(3, 2 * H + 1, 1)>(vb);
; }
; DI void pv_mma(f32x16* o, const s16x4* vf, bf16x8 pa0, bf16x8 pa1) {
;     ...
; #pragma unroll
;     for (int d0 = 0; d0 < 4; ++d0) {
;         o[d0] = __builtin_amdgcn_mfma_f32_32x32x16_bf16(pa0, ATT_PK(vf[4 * d0], vf[4 * d0 + 1]), o[d0], 0, 0, 0);
;         o[d0] = __builtin_amdgcn_mfma_f32_32x32x16_bf16(pa1, ATT_PK(vf[4 * d0 + 2], vf[4 * d0 + 3]), o[d0], 0, 0, 0); }
;     ...
; }
; template <int DQK, int D0A, int D0B> DI void k_reads(bf16x8* kf, const LAS unsigned char* Ks, int half, int r32, int hi) {
; #pragma unroll
;     for (int d0 = D0A; d0 < D0B; ++d0) kf[d0 - D0A] = *(const LAS bf16x8*)(Ks + half * (32 * DQK * 2) + kswz<DQK>(r32, (d0 * 16 + hi * 8) * 2));
; }
; template <int D0A, int D0B> DI void qk_mma(f32x16& p, const bf16x8* kf, const bf16x8* qr) {
; #pragma unroll
;     for (int d0 = D0A; d0 < D0B; ++d0) {
.LBB0_1967:
	ds_read_b128 v[100:103], v107 offset:20480
	ds_read_b128 v[114:117], v108 offset:20480
	ds_read_b128 v[118:121], v109 offset:20480
	ds_read_b128 v[122:125], v110 offset:20480
	v_add_u32_e32 v98, 0x8000, v106
	ds_read_b64_tr_b16 v[132:133], v98 offset:0
	ds_read_b64_tr_b16 v[134:135], v98 offset:0x800
	ds_read_b64_tr_b16 v[136:137], v98 offset:0x1000
	ds_read_b64_tr_b16 v[138:139], v98 offset:0x1800
	ds_read_b64_tr_b16 v[140:141], v98 offset:0x200
	ds_read_b64_tr_b16 v[142:143], v98 offset:0xa00
	ds_read_b64_tr_b16 v[144:145], v98 offset:0x1200
	ds_read_b64_tr_b16 v[146:147], v98 offset:0x1a00
	ds_read_b64_tr_b16 v[148:149], v98 offset:0x400
	ds_read_b64_tr_b16 v[150:151], v98 offset:0xc00
	ds_read_b64_tr_b16 v[152:153], v98 offset:0x1400
	ds_read_b64_tr_b16 v[154:155], v98 offset:0x1c00
	ds_read_b64_tr_b16 v[156:157], v98 offset:0x600
	ds_read_b64_tr_b16 v[158:159], v98 offset:0xe00
	ds_read_b64_tr_b16 v[162:163], v98 offset:0x1600
	ds_read_b64_tr_b16 v[164:165], v98 offset:0x1e00
	s_setprio 2
	v_exp_f32_e32 v64, v64
	v_exp_f32_e32 v65, v65
	v_exp_f32_e32 v66, v66
	v_exp_f32_e32 v67, v67
	v_exp_f32_e32 v68, v68
	v_exp_f32_e32 v69, v69
	v_exp_f32_e32 v70, v70
	v_exp_f32_e32 v71, v71
	v_exp_f32_e32 v72, v72
	v_exp_f32_e32 v73, v73
	v_exp_f32_e32 v74, v74
	v_exp_f32_e32 v75, v75
	v_exp_f32_e32 v76, v76
	v_exp_f32_e32 v77, v77
	v_exp_f32_e32 v78, v78
	v_exp_f32_e32 v79, v79
	v_add_f32_e32 v99, v65, v64
	v_add_f32_e32 v99, v66, v99
	v_add_f32_e32 v99, v67, v99
	v_add_f32_e32 v99, v68, v99
	v_add_f32_e32 v99, v69, v99
	v_add_f32_e32 v99, v70, v99
	v_add_f32_e32 v99, v71, v99
	v_add_f32_e32 v99, v72, v99
	v_add_f32_e32 v99, v73, v99
	v_add_f32_e32 v99, v74, v99
	v_add_f32_e32 v99, v75, v99
	v_add_f32_e32 v99, v76, v99
	v_add_f32_e32 v99, v77, v99
	v_add_f32_e32 v99, v78, v99
	v_add_f32_e32 v99, v79, v99
	v_add_f32_e32 v96, v99, v96
	v_cvt_pk_bf16_f32 v64, v64, v65
	v_cvt_pk_bf16_f32 v65, v66, v67
	v_cvt_pk_bf16_f32 v66, v68, v69
	v_cvt_pk_bf16_f32 v67, v70, v71
	v_cvt_pk_bf16_f32 v68, v72, v73
	v_cvt_pk_bf16_f32 v69, v74, v75
	v_cvt_pk_bf16_f32 v70, v76, v77
	v_cvt_pk_bf16_f32 v71, v78, v79
	s_nop 0
	v_permlane32_swap_b32_e32 v64, v66
	v_permlane32_swap_b32_e32 v65, v67
	v_permlane32_swap_b32_e32 v68, v70
	v_permlane32_swap_b32_e32 v69, v71
	s_waitcnt lgkmcnt(0)
	s_setprio 1
	v_mfma_f32_32x32x16_bf16 v[0:15], v[64:67], v[132:135], v[0:15]
	s_and_b64 vcc, exec, s[2:3]
	v_mfma_f32_32x32x16_bf16 v[48:63], v[64:67], v[140:143], v[48:63]
	v_mfma_f32_32x32x16_bf16 v[16:31], v[64:67], v[148:151], v[16:31]
	v_mfma_f32_32x32x16_bf16 v[32:47], v[64:67], v[156:159], v[32:47]
	v_mfma_f32_32x32x16_bf16 v[0:15], v[68:71], v[136:139], v[0:15]
	v_mfma_f32_32x32x16_bf16 v[48:63], v[68:71], v[144:147], v[48:63]
	v_mfma_f32_32x32x16_bf16 v[16:31], v[68:71], v[152:155], v[16:31]
	v_mfma_f32_32x32x16_bf16 v[32:47], v[68:71], v[162:165], v[32:47]
	s_waitcnt lgkmcnt(0)
	v_mfma_f32_32x32x16_bf16 v[64:79], v[100:103], v[92:95], 0
	v_mfma_f32_32x32x16_bf16 v[64:79], v[114:117], v[88:91], v[64:79]
	v_mfma_f32_32x32x16_bf16 v[64:79], v[118:121], v[84:87], v[64:79]
	v_mfma_f32_32x32x16_bf16 v[64:79], v[122:125], v[80:83], v[64:79]
	s_setprio 0
	s_cbranch_vccnz .LBB0_1969
	v_add3_u32 v97, s88, v97, v130
	v_add_u32_e32 v118, 0x408, v97
	v_add_u32_e32 v120, 0x420, v97
	v_add_u32_e32 v122, 0x428, v97
	v_add_u32_e32 v100, 0x440, v97
	v_add_u32_e32 v102, 0x448, v97
	v_add_u32_e32 v104, 0x460, v97
	v_add_u32_e32 v99, 0x400, v97
	v_add_u32_e32 v97, 0x468, v97
	ds_read2_b32 v[100:101], v100 offset1:1
	ds_read2_b32 v[102:103], v102 offset1:1
	ds_read2_b32 v[104:105], v104 offset1:1
	ds_read2_b32 v[114:115], v97 offset1:1
	ds_read2_b32 v[116:117], v99 offset1:1
	ds_read2_b32 v[118:119], v118 offset1:1
	ds_read2_b32 v[120:121], v120 offset1:1
	ds_read2_b32 v[122:123], v122 offset1:1
	s_waitcnt lgkmcnt(0)
	v_pk_add_f32 v[78:79], v[78:79], v[114:115]
	v_pk_add_f32 v[76:77], v[76:77], v[104:105]
	v_pk_add_f32 v[74:75], v[74:75], v[102:103]
	v_pk_add_f32 v[72:73], v[72:73], v[100:101]
	v_pk_add_f32 v[70:71], v[70:71], v[122:123]
	v_pk_add_f32 v[68:69], v[68:69], v[120:121]
	v_pk_add_f32 v[66:67], v[66:67], v[118:119]
	v_pk_add_f32 v[64:65], v[64:65], v[116:117]

; DI int v_rd_base(int lane) { return ((lane & 3) << 3) | (((lane >> 2) & 3) << 6) | (((lane >> 4) & 1) << 5) | (((lane >> 5) & 1) << 8); }
; DI void expsum(f32x16& p, float& l_reg, bf16x8& pa0, bf16x8& pa1) {
; #pragma unroll
;     for (int r = 0; r < 16; ++r) p[r] = __builtin_amdgcn_exp2f(p[r]);
;     float ps = 0.f;
; #pragma unroll
;     for (int r = 0; r < 16; ++r) ps += p[r];
;     l_reg += ps; asm volatile("" : "+v"(l_reg));
;     ...
;     ATT_PK4(p, 0, pa0); ATT_PK4(p, 8, pa1);
; template <int DQK, int MODE, int LDQ, int LDK, int LDV> ...
;     ...
;     const int vbase = (int)(unsigned)(size_t)lds + V_OFF + v_rd_base(lane);
;     ...
;     constexpr int NDA = ND0 > 6 ? 6 : ND0;
.LBB0_1973:
	ds_read_b128 v[98:101], v107 offset:28672
	ds_read_b128 v[102:105], v108 offset:28672
	ds_read_b128 v[112:115], v109 offset:28672
	ds_read_b128 v[108:111], v110 offset:28672
	ds_read_b64_tr_b16 v[116:117], v106 offset:0
	ds_read_b64_tr_b16 v[118:119], v106 offset:0x800
	ds_read_b64_tr_b16 v[120:121], v106 offset:0x1000
	ds_read_b64_tr_b16 v[122:123], v106 offset:0x1800
	ds_read_b64_tr_b16 v[124:125], v106 offset:0x200
	ds_read_b64_tr_b16 v[126:127], v106 offset:0xa00
	ds_read_b64_tr_b16 v[132:133], v106 offset:0x1200
	ds_read_b64_tr_b16 v[134:135], v106 offset:0x1a00
	ds_read_b64_tr_b16 v[136:137], v106 offset:0x400
	ds_read_b64_tr_b16 v[138:139], v106 offset:0xc00
	ds_read_b64_tr_b16 v[140:141], v106 offset:0x1400
	ds_read_b64_tr_b16 v[142:143], v106 offset:0x1c00
	ds_read_b64_tr_b16 v[144:145], v106 offset:0x600
	ds_read_b64_tr_b16 v[146:147], v106 offset:0xe00
	ds_read_b64_tr_b16 v[148:149], v106 offset:0x1600
	ds_read_b64_tr_b16 v[150:151], v106 offset:0x1e00
	s_setprio 2
	v_exp_f32_e32 v64, v64
	v_exp_f32_e32 v65, v65
	v_exp_f32_e32 v66, v66
	v_exp_f32_e32 v67, v67
	v_exp_f32_e32 v68, v68
	v_exp_f32_e32 v69, v69
	v_exp_f32_e32 v70, v70
	v_exp_f32_e32 v71, v71
	v_exp_f32_e32 v72, v72
	v_exp_f32_e32 v73, v73
	v_exp_f32_e32 v74, v74
	v_exp_f32_e32 v75, v75
	v_exp_f32_e32 v76, v76
	v_exp_f32_e32 v77, v77
	v_exp_f32_e32 v78, v78
	v_exp_f32_e32 v79, v79
	v_add_f32_e32 v107, v65, v64
	v_add_f32_e32 v107, v66, v107
	v_add_f32_e32 v107, v67, v107
	v_add_f32_e32 v107, v68, v107
	v_add_f32_e32 v107, v69, v107
	v_add_f32_e32 v107, v70, v107
	v_add_f32_e32 v107, v71, v107
	v_add_f32_e32 v107, v72, v107
	v_add_f32_e32 v107, v73, v107
	v_add_f32_e32 v107, v74, v107
	v_add_f32_e32 v107, v75, v107
	v_add_f32_e32 v107, v76, v107
	v_add_f32_e32 v107, v77, v107
	v_add_f32_e32 v107, v78, v107
	v_add_f32_e32 v107, v79, v107
	v_add_f32_e32 v96, v107, v96
	v_cvt_pk_bf16_f32 v64, v64, v65
	v_cvt_pk_bf16_f32 v65, v66, v67
	v_cvt_pk_bf16_f32 v66, v68, v69
	v_cvt_pk_bf16_f32 v67, v70, v71
	v_cvt_pk_bf16_f32 v68, v72, v73
	v_cvt_pk_bf16_f32 v69, v74, v75
	v_cvt_pk_bf16_f32 v70, v76, v77
	v_cvt_pk_bf16_f32 v71, v78, v79
	s_nop 0
	v_permlane32_swap_b32_e32 v64, v66
	v_permlane32_swap_b32_e32 v65, v67
	v_permlane32_swap_b32_e32 v68, v70
	v_permlane32_swap_b32_e32 v69, v71
	s_waitcnt lgkmcnt(0)
	s_setprio 1
	v_mfma_f32_32x32x16_bf16 v[0:15], v[64:67], v[116:119], v[0:15]
	s_and_b64 vcc, exec, s[2:3]
	v_mfma_f32_32x32x16_bf16 v[48:63], v[64:67], v[124:127], v[48:63]
	v_mfma_f32_32x32x16_bf16 v[16:31], v[64:67], v[136:139], v[16:31]
	v_mfma_f32_32x32x16_bf16 v[32:47], v[64:67], v[144:147], v[32:47]
	v_mfma_f32_32x32x16_bf16 v[0:15], v[68:71], v[120:123], v[0:15]
	v_mfma_f32_32x32x16_bf16 v[48:63], v[68:71], v[132:135], v[48:63]
	v_mfma_f32_32x32x16_bf16 v[16:31], v[68:71], v[140:143], v[16:31]
	v_mfma_f32_32x32x16_bf16 v[32:47], v[68:71], v[148:151], v[32:47]
	s_waitcnt lgkmcnt(0)
	v_mfma_f32_32x32x16_bf16 v[64:79], v[98:101], v[92:95], 0
	v_mfma_f32_32x32x16_bf16 v[64:79], v[102:105], v[88:91], v[64:79]
	v_mfma_f32_32x32x16_bf16 v[64:79], v[112:115], v[84:87], v[64:79]
	v_mfma_f32_32x32x16_bf16 v[64:79], v[108:111], v[80:83], v[64:79]
	s_setprio 0
	s_cbranch_vccnz .LBB0_1975
	v_add3_u32 v80, s88, v97, v130
	v_add_u32_e32 v88, 0x400, v80
	v_add_u32_e32 v90, 0x408, v80
	v_add_u32_e32 v92, 0x420, v80
	v_add_u32_e32 v94, 0x428, v80
	v_add_u32_e32 v81, 0x440, v80
	v_add_u32_e32 v82, 0x448, v80
	v_add_u32_e32 v84, 0x460, v80
	v_add_u32_e32 v86, 0x468, v80
	ds_read2_b32 v[80:81], v81 offset1:1
	ds_read2_b32 v[82:83], v82 offset1:1
	ds_read2_b32 v[84:85], v84 offset1:1
	ds_read2_b32 v[86:87], v86 offset1:1
	ds_read2_b32 v[88:89], v88 offset1:1
	ds_read2_b32 v[90:91], v90 offset1:1
	ds_read2_b32 v[92:93], v92 offset1:1
	ds_read2_b32 v[94:95], v94 offset1:1
	s_waitcnt lgkmcnt(0)
	v_pk_add_f32 v[78:79], v[78:79], v[86:87]
	v_pk_add_f32 v[76:77], v[76:77], v[84:85]
	v_pk_add_f32 v[74:75], v[74:75], v[82:83]
	v_pk_add_f32 v[72:73], v[72:73], v[80:81]
	v_pk_add_f32 v[70:71], v[70:71], v[94:95]
	v_pk_add_f32 v[68:69], v[68:69], v[92:93]
	v_pk_add_f32 v[66:67], v[66:67], v[90:91]
	v_pk_add_f32 v[64:65], v[64:65], v[88:89]
.LBB0_1975:
	s_lshl_b32 s0, s44, 2
	s_add_i32 s0, s0, 0
	s_add_i32 s0, s0, 0x24000
	ds_read_b64_tr_b16 v[80:81], v106 offset:0x2000
	ds_read_b64_tr_b16 v[82:83], v106 offset:0x2800
	ds_read_b64_tr_b16 v[84:85], v106 offset:0x3000
	ds_read_b64_tr_b16 v[86:87], v106 offset:0x3800
	ds_read_b64_tr_b16 v[88:89], v106 offset:0x2200
	ds_read_b64_tr_b16 v[90:91], v106 offset:0x2a00
	ds_read_b64_tr_b16 v[92:93], v106 offset:0x3200
	ds_read_b64_tr_b16 v[94:95], v106 offset:0x3a00
	ds_read_b64_tr_b16 v[98:99], v106 offset:0x2400
	ds_read_b64_tr_b16 v[100:101], v106 offset:0x2c00
	ds_read_b64_tr_b16 v[102:103], v106 offset:0x3400
	ds_read_b64_tr_b16 v[104:105], v106 offset:0x3c00
	ds_read_b64_tr_b16 v[108:109], v106 offset:0x2600
	ds_read_b64_tr_b16 v[110:111], v106 offset:0x2e00
	ds_read_b64_tr_b16 v[112:113], v106 offset:0x3600
	ds_read_b64_tr_b16 v[114:115], v106 offset:0x3e00
	s_nop 7
	s_setprio 2
	v_exp_f32_e32 v97, v64
	v_exp_f32_e32 v65, v65
	v_exp_f32_e32 v106, v66
	v_exp_f32_e32 v67, v67
	v_exp_f32_e32 v68, v68
	v_exp_f32_e32 v69, v69
	v_exp_f32_e32 v70, v70
	v_exp_f32_e32 v71, v71
	v_exp_f32_e32 v72, v72
	v_exp_f32_e32 v73, v73
	v_exp_f32_e32 v74, v74
	v_exp_f32_e32 v75, v75
	v_exp_f32_e32 v76, v76
	v_exp_f32_e32 v77, v77
	v_exp_f32_e32 v78, v78
	v_exp_f32_e32 v79, v79
	v_add_f32_e32 v64, v65, v97
	v_add_f32_e32 v64, v106, v64
	v_add_f32_e32 v64, v67, v64
	v_add_f32_e32 v64, v68, v64
	v_add_f32_e32 v64, v69, v64
	v_add_f32_e32 v64, v70, v64
	v_add_f32_e32 v64, v71, v64
	v_add_f32_e32 v64, v72, v64
	v_add_f32_e32 v64, v73, v64
	v_add_f32_e32 v64, v74, v64
	v_add_f32_e32 v64, v75, v64
	v_add_f32_e32 v64, v76, v64
	v_add_f32_e32 v64, v77, v64
	v_add_f32_e32 v64, v78, v64
	v_add_f32_e32 v64, v79, v64
	v_add_f32_e32 v64, v96, v64
	v_cvt_pk_bf16_f32 v66, v97, v65
	v_cvt_pk_bf16_f32 v67, v106, v67
	v_cvt_pk_bf16_f32 v68, v68, v69
	v_cvt_pk_bf16_f32 v69, v70, v71
	v_cvt_pk_bf16_f32 v70, v72, v73
	v_cvt_pk_bf16_f32 v71, v74, v75
	v_cvt_pk_bf16_f32 v72, v76, v77
	v_cvt_pk_bf16_f32 v73, v78, v79
	s_nop 0
	v_permlane32_swap_b32_e32 v66, v68
	v_permlane32_swap_b32_e32 v67, v69
	v_permlane32_swap_b32_e32 v70, v72
	v_permlane32_swap_b32_e32 v71, v73
	s_waitcnt lgkmcnt(0)
; template <int TAG = 0> DI int fresh_tid(int wv) { int l; asm volatile("v_mbcnt_lo_u32_b32 %0, -1, 0\n\tv_mbcnt_hi_u32_b32 %0, -1, %0 ; site %1" : "=v"(l) : "n"(TAG)); return wv * 64 + l; }
; DI int crow(int r, int hi) { return (r & 3) + 8 * (r >> 2) + 4 * hi; }
; DI float swap_sum(float v) { auto rr = __builtin_amdgcn_permlane32_swap(__float_as_uint(v), __float_as_uint(v), false, false); return __uint_as_float(rr[0]) + __uint_as_float(rr[1]); }
; DI void pv_mma(f32x16* o, const s16x4* vf, bf16x8 pa0, bf16x8 pa1) {
;     ...
; #pragma unroll
;     for (int d0 = 0; d0 < 4; ++d0) {
;         o[d0] = __builtin_amdgcn_mfma_f32_32x32x16_bf16(pa0, ATT_PK(vf[4 * d0], vf[4 * d0 + 1]), o[d0], 0, 0, 0);
;         o[d0] = __builtin_amdgcn_mfma_f32_32x32x16_bf16(pa1, ATT_PK(vf[4 * d0 + 2], vf[4 * d0 + 3]), o[d0], 0, 0, 0); }
; template <int DQK, int MODE, int LDQ, int LDK, int LDV> ...
;     ...
;     l_reg = swap_sum(l_reg);
;     { const int lane2 = fresh_tid<110 + MODE>(wv) & 63, r32 = lane2 & 31, hi = lane2 >> 5;
;     if (hi == 0) li_l[r32] = l_reg;
;     asm volatile("s_waitcnt lgkmcnt(0)" ::: "memory");
;     float s0v[MODE == 2 ? 16 : 1][4];
;     if constexpr (MODE == 2) {
; #pragma unroll
;         for (int r = 0; r < 16; ++r)
; #pragma unroll
;             for (int d0 = 0; d0 < 4; ++d0) s0v[r][d0] = S0[(size_t)(wid * 32 + crow(r, hi)) * 512 + d0 * 32 + r32];
	s_setprio 1
	v_mfma_f32_32x32x16_bf16 v[0:15], v[66:69], v[80:83], v[0:15]
	v_mfma_f32_32x32x16_bf16 v[48:63], v[66:69], v[88:91], v[48:63]
	v_mfma_f32_32x32x16_bf16 v[16:31], v[66:69], v[98:101], v[16:31]
	v_mfma_f32_32x32x16_bf16 v[32:47], v[66:69], v[108:111], v[32:47]
	v_mfma_f32_32x32x16_bf16 v[0:15], v[70:73], v[84:87], v[0:15]
	v_mfma_f32_32x32x16_bf16 v[48:63], v[70:73], v[92:95], v[48:63]
	v_mfma_f32_32x32x16_bf16 v[16:31], v[70:73], v[102:105], v[16:31]
	v_mfma_f32_32x32x16_bf16 v[32:47], v[70:73], v[112:115], v[32:47]
	s_setprio 0
	v_mov_b32_e32 v66, v64
	v_mbcnt_lo_u32_b32 v65, -1, 0
	v_mbcnt_hi_u32_b32 v65, -1, v65
	s_nop 1
	v_permlane32_swap_b32_e32 v64, v66
	v_and_b32_e32 v114, 63, v65
	v_and_b32_e32 v170, 31, v65
	v_cmp_gt_u32_e32 vcc, 32, v114
	s_and_saveexec_b64 s[2:3], vcc
	v_lshl_add_u32 v67, v170, 2, s0
	v_add_f32_e32 v64, v64, v66
	ds_write_b32 v67, v64
	s_or_b64 exec, exec, s[2:3]
	v_lshrrev_b32_e32 v64, 3, v65
	v_and_b32_e32 v69, 4, v64
	v_or_b32_e32 v102, s46, v69
	v_lshlrev_b32_e32 v130, 2, v170
	v_ashrrev_i32_e32 v103, 31, v102
	v_or_b32_e32 v66, 1, v102
	v_lshl_add_u64 v[92:93], s[54:55], 0, v[130:131]
	v_lshlrev_b64 v[156:157], 11, v[102:103]
	v_ashrrev_i32_e32 v67, 31, v66
	s_waitcnt lgkmcnt(0)
	v_lshl_add_u64 v[64:65], v[92:93], 0, v[156:157]
	v_lshlrev_b64 v[148:149], 11, v[66:67]
	v_lshl_add_u64 v[66:67], v[92:93], 0, v[148:149]
	global_load_dword v110, v[64:65], off
	global_load_dword v111, v[64:65], off offset:128
	global_load_dword v109, v[64:65], off offset:256
	global_load_dword v108, v[64:65], off offset:384
	global_load_dword v106, v[66:67], off
	global_load_dword v107, v[66:67], off offset:128
	global_load_dword v105, v[66:67], off offset:256
	global_load_dword v104, v[66:67], off offset:384
	v_or_b32_e32 v64, 2, v102
	v_or_b32_e32 v66, 3, v102
	v_ashrrev_i32_e32 v65, 31, v64
	v_ashrrev_i32_e32 v67, 31, v66
	v_lshlrev_b64 v[146:147], 11, v[64:65]
	v_lshlrev_b64 v[136:137], 11, v[66:67]
	v_lshl_add_u64 v[64:65], v[92:93], 0, v[146:147]
	v_lshl_add_u64 v[66:67], v[92:93], 0, v[136:137]
	global_load_dword v158, v[64:65], off
	global_load_dword v159, v[64:65], off offset:128
	global_load_dword v155, v[64:65], off offset:256
	global_load_dword v154, v[64:65], off offset:384
	global_load_dword v152, v[66:67], off
	global_load_dword v153, v[66:67], off offset:128
	global_load_dword v151, v[66:67], off offset:256
	global_load_dword v150, v[66:67], off offset:384
	v_or_b32_e32 v64, 8, v102
	v_or_b32_e32 v66, 9, v102
	v_ashrrev_i32_e32 v65, 31, v64
	v_ashrrev_i32_e32 v67, 31, v66
	v_lshlrev_b64 v[134:135], 11, v[64:65]
	v_lshlrev_b64 v[120:121], 11, v[66:67]
	v_lshl_add_u64 v[64:65], v[92:93], 0, v[134:135]
	v_lshl_add_u64 v[66:67], v[92:93], 0, v[120:121]
	global_load_dword v144, v[64:65], off
	global_load_dword v145, v[64:65], off offset:128
	global_load_dword v143, v[64:65], off offset:256
	global_load_dword v142, v[64:65], off offset:384
	global_load_dword v140, v[66:67], off
	global_load_dword v141, v[66:67], off offset:128
	global_load_dword v139, v[66:67], off offset:256
	global_load_dword v138, v[66:67], off offset:384
	v_or_b32_e32 v64, 10, v102
	v_or_b32_e32 v66, 11, v102
	v_ashrrev_i32_e32 v65, 31, v64
	v_ashrrev_i32_e32 v67, 31, v66
	v_lshlrev_b64 v[118:119], 11, v[64:65]
	v_lshlrev_b64 v[90:91], 11, v[66:67]
	v_lshl_add_u64 v[64:65], v[92:93], 0, v[118:119]
	v_lshl_add_u64 v[66:67], v[92:93], 0, v[90:91]
	global_load_dword v132, v[64:65], off
	global_load_dword v133, v[64:65], off offset:128
	global_load_dword v127, v[64:65], off offset:256
	global_load_dword v126, v[64:65], off offset:384
	global_load_dword v124, v[66:67], off
	global_load_dword v125, v[66:67], off offset:128
	global_load_dword v123, v[66:67], off offset:256
	global_load_dword v122, v[66:67], off offset:384
	v_or_b32_e32 v64, 16, v102
	v_or_b32_e32 v66, 17, v102
	v_ashrrev_i32_e32 v65, 31, v64
	v_ashrrev_i32_e32 v67, 31, v66
	v_lshlrev_b64 v[86:87], 11, v[64:65]
	v_lshlrev_b64 v[78:79], 11, v[66:67]
	v_lshl_add_u64 v[64:65], v[92:93], 0, v[86:87]
	v_lshl_add_u64 v[66:67], v[92:93], 0, v[78:79]
	global_load_dword v100, v[64:65], off
	global_load_dword v101, v[64:65], off offset:128
	global_load_dword v99, v[64:65], off offset:256
	global_load_dword v98, v[64:65], off offset:384
	global_load_dword v96, v[66:67], off
	global_load_dword v97, v[66:67], off offset:128
	global_load_dword v95, v[66:67], off offset:256
	global_load_dword v94, v[66:67], off offset:384
	v_or_b32_e32 v64, 18, v102
	v_or_b32_e32 v66, 19, v102
	v_ashrrev_i32_e32 v65, 31, v64
	v_ashrrev_i32_e32 v67, 31, v66
	v_lshlrev_b64 v[76:77], 11, v[64:65]
	v_lshlrev_b64 v[72:73], 11, v[66:67]
	v_lshl_add_u64 v[64:65], v[92:93], 0, v[76:77]
	v_lshl_add_u64 v[66:67], v[92:93], 0, v[72:73]
	v_lshl_add_u32 v169, v69, 2, s0
	global_load_dword v88, v[64:65], off
	global_load_dword v89, v[64:65], off offset:128
	global_load_dword v85, v[64:65], off offset:256
	global_load_dword v84, v[64:65], off offset:384
	global_load_dword v82, v[66:67], off
	global_load_dword v83, v[66:67], off offset:128
	global_load_dword v81, v[66:67], off offset:256
	global_load_dword v80, v[66:67], off offset:384
	ds_read_b128 v[64:67], v169
	v_or_b32_e32 v68, 24, v102
	v_ashrrev_i32_e32 v69, 31, v68
	v_lshlrev_b64 v[74:75], 11, v[68:69]
	ds_read_b128 v[68:71], v169 offset:32
	s_waitcnt lgkmcnt(0)
; DI unsigned short f2bf(float x) { unsigned u = __float_as_uint(x); u += 0x7fffu + ((u >> 16) & 1u); return (unsigned short)(u >> 16); }
; DI float shx(float v, int mask, int lane) { return __int_as_float(__builtin_amdgcn_ds_bpermute((lane ^ mask) << 2, __float_as_int(v))); }
; DI int crow(int r, int hi) { return (r & 3) + 8 * (r >> 2) + 4 * hi; }
; template <int DQK, int MODE, int LDQ, int LDK, int LDV> ...
;     ...
;     for (int r = 0; r < 16; ++r) { const int orow = wid * 32 + crow(r, hi); const float rl = __builtin_amdgcn_rcpf(li_l[crow(r, hi)]);
;         if constexpr (MODE == 0) {
; #pragma unroll
;             for (int d0 = 0; d0 < 4; ++d0) AOb[(size_t)orow * 1024 + d0 * 32 + r32] = f2bf(o[d0][r] * rl);
;         } else if constexpr (MODE == 1) {
; #pragma unroll
;             for (int d0 = 0; d0 < 4; ++d0) S0[(size_t)orow * 512 + d0 * 32 + r32] = o[d0][r] * rl;
;         } else {
;             float v[4]; float ss = 0.f;
; #pragma unroll
;             for (int d0 = 0; d0 < 4; ++d0) { v[d0] = s0v[r][d0] - lam * (o[d0][r] * rl); ss += v[d0] * v[d0]; }
; #pragma unroll
;             for (int mk = 1; mk <= 16; mk <<= 1) ss += shx(ss, mk, lane2);
;             const float rs = rsqrtf(ss * (1.f / 128.f) + EPS) * 0.8f;
; #pragma unroll
;             for (int d0 = 0; d0 < 4; ++d0) AOb[(size_t)orow * 1024 + d0 * 32 + r32] = f2bf(v[d0] * rs * gout[d0 * 32 + r32]);
	v_rcp_f32_e32 v64, v64
	v_mov_b32_e32 v162, v0
	v_mov_b32_e32 v163, v48
	v_rcp_f32_e32 v0, v65
	v_pk_mul_f32 v[162:163], v[162:163], v[64:65] op_sel_hi:[1,0]
	v_mov_b32_e32 v48, v1
	v_lshlrev_b32_e32 v166, 2, v114
	v_pk_mul_f32 v[48:49], v[48:49], v[0:1] op_sel_hi:[1,0]
	v_xor_b32_e32 v164, 4, v166
	v_xor_b32_e32 v165, 8, v166
	v_xor_b32_e32 v168, 16, v166
	v_xor_b32_e32 v167, 32, v166
	v_or_b32_e32 v116, 25, v102
	v_ashrrev_i32_e32 v117, 31, v116
	v_xor_b32_e32 v166, 64, v166
	v_lshl_add_u64 v[112:113], v[92:93], 0, v[74:75]
	s_add_u32 s1, s60, s58
	s_mov_b32 s0, 0x358637bd
	s_addc_u32 s3, s61, s59
	s_lshl_b32 s2, s87, 1
	s_add_u32 s2, s1, s2
	s_addc_u32 s3, s3, 0
	s_waitcnt vmcnt(0)
	v_pk_fma_f32 v[172:173], v[128:129], v[162:163], v[110:111] neg_lo:[1,0,0] neg_hi:[1,0,0]
	v_mov_b32_e32 v162, v32
	v_mov_b32_e32 v163, v16
	v_pk_mul_f32 v[162:163], v[162:163], v[64:65] op_sel_hi:[1,0]
	v_mov_b32_e32 v16, v33
	v_pk_fma_f32 v[174:175], v[128:129], v[162:163], v[108:109] neg_lo:[1,0,0] neg_hi:[1,0,0]
	global_load_dword v163, v130, s[50:51]
	global_load_dword v162, v130, s[50:51] offset:128
	global_load_dword v161, v130, s[50:51] offset:256
	s_nop 0
	global_load_dword v130, v130, s[50:51] offset:384
	v_pk_fma_f32 v[176:177], v[128:129], v[48:49], v[106:107] neg_lo:[1,0,0] neg_hi:[1,0,0]
	v_pk_mul_f32 v[0:1], v[16:17], v[0:1] op_sel_hi:[1,0]
	v_pk_mul_f32 v[110:111], v[172:173], v[172:173]
	v_pk_mul_f32 v[48:49], v[176:177], v[176:177]
	v_pk_fma_f32 v[0:1], v[128:129], v[0:1], v[104:105] neg_lo:[1,0,0] neg_hi:[1,0,0]
	v_pk_mul_f32 v[108:109], v[174:175], v[174:175]
	v_pk_mul_f32 v[16:17], v[0:1], v[0:1]
	v_mov_b32_e32 v32, v48
	v_mov_b32_e32 v33, v110
	v_mov_b32_e32 v110, v49
	v_pk_add_f32 v[32:33], v[32:33], v[110:111]
	v_mov_b32_e32 v48, v17
	v_mov_b32_e32 v49, v109
	v_pk_add_f32 v[32:33], v[48:49], v[32:33]
	v_mov_b32_e32 v17, v108
	v_pk_add_f32 v[16:17], v[16:17], v[32:33]
	ds_bpermute_b32 v33, v164, v17
	ds_bpermute_b32 v32, v164, v16
	v_lshlrev_b64 v[64:65], 11, v[116:117]
	v_lshl_add_u64 v[48:49], v[92:93], 0, v[64:65]
	global_load_dword v116, v[112:113], off
	global_load_dword v117, v[112:113], off offset:128
	global_load_dword v115, v[112:113], off offset:256
	global_load_dword v114, v[112:113], off offset:384
	s_nop 0
	global_load_dword v112, v[48:49], off
	global_load_dword v113, v[48:49], off offset:128
	global_load_dword v111, v[48:49], off offset:256
	global_load_dword v110, v[48:49], off offset:384
	v_or_b32_e32 v48, 26, v102
	s_waitcnt lgkmcnt(0)
	v_pk_add_f32 v[16:17], v[16:17], v[32:33]
	ds_bpermute_b32 v33, v165, v17
	ds_bpermute_b32 v32, v165, v16
	v_or_b32_e32 v102, 27, v102
	v_ashrrev_i32_e32 v49, 31, v48
	v_ashrrev_i32_e32 v103, 31, v102
	v_lshlrev_b64 v[48:49], 11, v[48:49]
	s_waitcnt lgkmcnt(0)
	v_pk_add_f32 v[16:17], v[16:17], v[32:33]
	ds_bpermute_b32 v33, v168, v17
	ds_bpermute_b32 v32, v168, v16
	v_lshl_add_u64 v[104:105], v[92:93], 0, v[48:49]
	v_lshlrev_b32_e32 v170, 1, v170
	v_mov_b32_e32 v171, v131
	v_rcp_f32_e32 v66, v66
	s_waitcnt lgkmcnt(0)
	v_pk_add_f32 v[32:33], v[16:17], v[32:33]
	ds_bpermute_b32 v107, v167, v33
	ds_bpermute_b32 v106, v167, v32
	v_lshlrev_b64 v[16:17], 11, v[102:103]
	v_lshl_add_u64 v[92:93], v[92:93], 0, v[16:17]
	s_waitcnt lgkmcnt(0)
	v_pk_add_f32 v[32:33], v[32:33], v[106:107]
	ds_bpermute_b32 v179, v166, v33
	ds_bpermute_b32 v178, v166, v32
	global_load_dword v108, v[104:105], off
	global_load_dword v109, v[104:105], off offset:128
	global_load_dword v107, v[104:105], off offset:256
	global_load_dword v106, v[104:105], off offset:384
	s_nop 0
	global_load_dword v104, v[92:93], off
	global_load_dword v105, v[92:93], off offset:128
	global_load_dword v103, v[92:93], off offset:256
	global_load_dword v102, v[92:93], off offset:384
	v_mov_b64_e32 v[92:93], s[0:1]
	s_waitcnt lgkmcnt(0)
	v_pk_add_f32 v[32:33], v[32:33], v[178:179]
	s_nop 0
	v_pk_fma_f32 v[178:179], v[32:33], s[24:25], v[92:93] op_sel_hi:[1,0,0]
	s_nop 0
	v_mul_f32_e32 v32, 0x4b800000, v179
	v_cmp_gt_f32_e32 vcc, s67, v179
	s_nop 1
	v_cndmask_b32_e32 v32, v179, v32, vcc
	v_rsq_f32_e32 v179, v32
	v_lshl_add_u64 v[32:33], s[2:3], 0, v[170:171]
	v_lshl_add_u64 v[156:157], v[32:33], 0, v[156:157]
	v_lshl_add_u64 v[148:149], v[32:33], 0, v[148:149]
	v_mul_f32_e32 v170, 0x45800000, v179
	v_cndmask_b32_e32 v170, v179, v170, vcc
	v_mul_f32_e32 v170, 0x3f4ccccd, v170
	v_mul_f32_e32 v171, v172, v170
	v_cmp_gt_f32_e32 vcc, s67, v178
	s_mov_b64 s[2:3], 0
	s_waitcnt vmcnt(19)
	v_mul_f32_e32 v171, v163, v171
	v_bfe_u32 v172, v171, 16, 1
	v_add3_u32 v171, v171, v172, s68
	global_store_short_d16_hi v[156:157], v171, off offset:1024
	v_mul_f32_e32 v171, v173, v170
	s_waitcnt vmcnt(19)
	v_mul_f32_e32 v171, v162, v171
	v_bfe_u32 v172, v171, 16, 1
	v_add3_u32 v171, v171, v172, s68
	global_store_short_d16_hi v[156:157], v171, off offset:1088
	v_mul_f32_e32 v171, v175, v170
	s_waitcnt vmcnt(19)
	v_mul_f32_e32 v171, v161, v171
	v_bfe_u32 v172, v171, 16, 1
	v_add3_u32 v171, v171, v172, s68
	global_store_short_d16_hi v[156:157], v171, off offset:1152
	v_mul_f32_e32 v171, 0x4b800000, v178
	v_cndmask_b32_e32 v171, v178, v171, vcc
	v_mul_f32_e32 v170, v174, v170
	v_rsq_f32_e32 v171, v171
	s_waitcnt vmcnt(19)
; DI unsigned short f2bf(float x) { unsigned u = __float_as_uint(x); u += 0x7fffu + ((u >> 16) & 1u); return (unsigned short)(u >> 16); }
; DI float shx(float v, int mask, int lane) { return __int_as_float(__builtin_amdgcn_ds_bpermute((lane ^ mask) << 2, __float_as_int(v))); }
; DI int crow(int r, int hi) { return (r & 3) + 8 * (r >> 2) + 4 * hi; }
; template <int DQK, int MODE, int LDQ, int LDK, int LDV> ...
;     ...
;     for (int r = 0; r < 16; ++r) { const int orow = wid * 32 + crow(r, hi); const float rl = __builtin_amdgcn_rcpf(li_l[crow(r, hi)]);
;         if constexpr (MODE == 0) {
; #pragma unroll
;             for (int d0 = 0; d0 < 4; ++d0) AOb[(size_t)orow * 1024 + d0 * 32 + r32] = f2bf(o[d0][r] * rl);
;         } else if constexpr (MODE == 1) {
; #pragma unroll
;             for (int d0 = 0; d0 < 4; ++d0) S0[(size_t)orow * 512 + d0 * 32 + r32] = o[d0][r] * rl;
;         } else {
;             float v[4]; float ss = 0.f;
; #pragma unroll
;             for (int d0 = 0; d0 < 4; ++d0) { v[d0] = s0v[r][d0] - lam * (o[d0][r] * rl); ss += v[d0] * v[d0]; }
; #pragma unroll
;             for (int mk = 1; mk <= 16; mk <<= 1) ss += shx(ss, mk, lane2);
;             const float rs = rsqrtf(ss * (1.f / 128.f) + EPS) * 0.8f;
; #pragma unroll
;             for (int d0 = 0; d0 < 4; ++d0) AOb[(size_t)orow * 1024 + d0 * 32 + r32] = f2bf(v[d0] * rs * gout[d0 * 32 + r32]);
	v_mul_f32_e32 v170, v130, v170
	v_bfe_u32 v172, v170, 16, 1
	v_add3_u32 v170, v170, v172, s68
	global_store_short_d16_hi v[156:157], v170, off offset:1216
	v_mul_f32_e32 v156, 0x45800000, v171
	v_cndmask_b32_e32 v172, v171, v156, vcc
	v_mov_b32_e32 v156, v2
	v_rcp_f32_e32 v2, v67
	v_mov_b32_e32 v157, v50
	v_mov_b32_e32 v50, v3
	v_pk_mul_f32 v[156:157], v[156:157], v[66:67] op_sel_hi:[1,0]
	v_mov_b32_e32 v170, v34
	v_mov_b32_e32 v171, v18
	v_pk_mul_f32 v[50:51], v[50:51], v[2:3] op_sel_hi:[1,0]
	v_mov_b32_e32 v18, v35
	v_pk_fma_f32 v[156:157], v[128:129], v[156:157], v[158:159] neg_lo:[1,0,0] neg_hi:[1,0,0]
	v_pk_mul_f32 v[170:171], v[170:171], v[66:67] op_sel_hi:[1,0]
	v_pk_fma_f32 v[50:51], v[128:129], v[50:51], v[152:153] neg_lo:[1,0,0] neg_hi:[1,0,0]
	v_pk_mul_f32 v[2:3], v[18:19], v[2:3] op_sel_hi:[1,0]
	v_pk_mul_f32 v[158:159], v[156:157], v[156:157]
	v_pk_fma_f32 v[66:67], v[128:129], v[170:171], v[154:155] neg_lo:[1,0,0] neg_hi:[1,0,0]
	v_pk_mul_f32 v[152:153], v[50:51], v[50:51]
	v_pk_fma_f32 v[2:3], v[128:129], v[2:3], v[150:151] neg_lo:[1,0,0] neg_hi:[1,0,0]
	v_pk_mul_f32 v[154:155], v[66:67], v[66:67]
	v_pk_mul_f32 v[18:19], v[2:3], v[2:3]
	v_mov_b32_e32 v34, v152
	v_mov_b32_e32 v35, v158
	v_mov_b32_e32 v158, v153
	v_pk_add_f32 v[34:35], v[34:35], v[158:159]
	v_mov_b32_e32 v150, v19
	v_mov_b32_e32 v151, v155
	v_pk_add_f32 v[34:35], v[150:151], v[34:35]
	v_mov_b32_e32 v19, v154
	v_pk_add_f32 v[18:19], v[18:19], v[34:35]
	ds_bpermute_b32 v35, v164, v19
	ds_bpermute_b32 v34, v164, v18
	v_mul_f32_e32 v150, 0x3f4ccccd, v172
	v_mul_f32_e32 v151, v176, v150
	v_mul_f32_e32 v151, v163, v151
	v_bfe_u32 v152, v151, 16, 1
	s_waitcnt lgkmcnt(0)
	v_pk_add_f32 v[18:19], v[18:19], v[34:35]
	ds_bpermute_b32 v35, v165, v19
	ds_bpermute_b32 v34, v165, v18
	v_add3_u32 v151, v151, v152, s68
	global_store_short_d16_hi v[148:149], v151, off offset:1024
	v_mul_f32_e32 v151, v177, v150
	v_mul_f32_e32 v151, v162, v151
	s_waitcnt lgkmcnt(0)
	v_pk_add_f32 v[18:19], v[18:19], v[34:35]
	ds_bpermute_b32 v35, v168, v19
	ds_bpermute_b32 v34, v168, v18
	v_bfe_u32 v152, v151, 16, 1
	v_mul_f32_e32 v1, v1, v150
	v_add3_u32 v151, v151, v152, s68
	v_mul_f32_e32 v1, v161, v1
	s_waitcnt lgkmcnt(0)
	v_pk_add_f32 v[18:19], v[18:19], v[34:35]
	ds_bpermute_b32 v35, v167, v19
	ds_bpermute_b32 v34, v167, v18
	global_store_short_d16_hi v[148:149], v151, off offset:1088
	v_bfe_u32 v151, v1, 16, 1
	v_add3_u32 v1, v1, v151, s68
	v_mul_f32_e32 v0, v0, v150
	s_waitcnt lgkmcnt(0)
	v_pk_add_f32 v[18:19], v[18:19], v[34:35]
	ds_bpermute_b32 v35, v166, v19
	ds_bpermute_b32 v34, v166, v18
	global_store_short_d16_hi v[148:149], v1, off offset:1152
	v_mul_f32_e32 v150, v130, v0
	v_bfe_u32 v151, v150, 16, 1
	s_waitcnt lgkmcnt(0)
	v_pk_add_f32 v[0:1], v[18:19], v[34:35]
	s_nop 0
	v_pk_fma_f32 v[0:1], v[0:1], s[24:25], v[92:93] op_sel_hi:[1,0,0]
	s_nop 0
	v_mul_f32_e32 v18, 0x4b800000, v1
	v_cmp_gt_f32_e32 vcc, s67, v1
	s_nop 1
	v_cndmask_b32_e32 v1, v1, v18, vcc
	v_rsq_f32_e32 v1, v1
	v_add3_u32 v18, v150, v151, s68
	global_store_short_d16_hi v[148:149], v18, off offset:1216
	v_lshl_add_u64 v[18:19], v[32:33], 0, v[146:147]
	v_mul_f32_e32 v34, 0x45800000, v1
	v_cndmask_b32_e32 v1, v1, v34, vcc
	v_mul_f32_e32 v1, 0x3f4ccccd, v1
	v_mul_f32_e32 v34, v156, v1
	v_mul_f32_e32 v34, v163, v34
	v_bfe_u32 v35, v34, 16, 1
	v_add3_u32 v34, v34, v35, s68
	global_store_short_d16_hi v[18:19], v34, off offset:1024
	v_mul_f32_e32 v34, v157, v1
	v_mul_f32_e32 v34, v162, v34
	v_bfe_u32 v35, v34, 16, 1
	v_add3_u32 v34, v34, v35, s68
	global_store_short_d16_hi v[18:19], v34, off offset:1088
	v_mul_f32_e32 v34, v67, v1
	v_mul_f32_e32 v34, v161, v34
	v_bfe_u32 v35, v34, 16, 1
	v_add3_u32 v34, v34, v35, s68
	global_store_short_d16_hi v[18:19], v34, off offset:1152
	v_mul_f32_e32 v1, v66, v1
	v_mul_f32_e32 v34, 0x4b800000, v0
	v_cmp_gt_f32_e32 vcc, s67, v0
	v_mul_f32_e32 v1, v130, v1
	v_mov_b32_e32 v66, v36
	v_cndmask_b32_e32 v0, v0, v34, vcc
	v_rsq_f32_e32 v34, v0
	v_bfe_u32 v0, v1, 16, 1
	v_add3_u32 v0, v1, v0, s68
	global_store_short_d16_hi v[18:19], v0, off offset:1216
	v_rcp_f32_e32 v0, v68
	v_mov_b32_e32 v18, v4
	v_rcp_f32_e32 v4, v69
	v_mul_f32_e32 v1, 0x45800000, v34
	v_mov_b32_e32 v19, v52
	v_mov_b32_e32 v52, v5
	v_pk_mul_f32 v[18:19], v[18:19], v[0:1] op_sel_hi:[1,0]
	v_mov_b32_e32 v67, v20
	v_pk_mul_f32 v[52:53], v[52:53], v[4:5] op_sel_hi:[1,0]
	v_mov_b32_e32 v20, v37
	v_cndmask_b32_e32 v146, v34, v1, vcc
	v_pk_fma_f32 v[18:19], v[128:129], v[18:19], v[144:145] neg_lo:[1,0,0] neg_hi:[1,0,0]
	v_pk_mul_f32 v[0:1], v[66:67], v[0:1] op_sel_hi:[1,0]
	v_pk_fma_f32 v[52:53], v[128:129], v[52:53], v[140:141] neg_lo:[1,0,0] neg_hi:[1,0,0]
	v_pk_mul_f32 v[4:5], v[20:21], v[4:5] op_sel_hi:[1,0]
	v_pk_mul_f32 v[34:35], v[18:19], v[18:19]
	v_pk_fma_f32 v[0:1], v[128:129], v[0:1], v[142:143] neg_lo:[1,0,0] neg_hi:[1,0,0]
	v_pk_mul_f32 v[68:69], v[52:53], v[52:53]
	v_pk_fma_f32 v[4:5], v[128:129], v[4:5], v[138:139] neg_lo:[1,0,0] neg_hi:[1,0,0]
	v_pk_mul_f32 v[66:67], v[0:1], v[0:1]
	v_pk_mul_f32 v[20:21], v[4:5], v[4:5]
	v_mov_b32_e32 v36, v68
	v_mov_b32_e32 v37, v34
	v_mov_b32_e32 v34, v69
	v_pk_add_f32 v[34:35], v[36:37], v[34:35]
	v_mov_b32_e32 v36, v21
	v_mov_b32_e32 v37, v67
	v_pk_add_f32 v[34:35], v[36:37], v[34:35]
	v_mov_b32_e32 v21, v66
	v_pk_add_f32 v[20:21], v[20:21], v[34:35]
	ds_bpermute_b32 v35, v164, v21
	ds_bpermute_b32 v34, v164, v20
	v_mul_f32_e32 v66, 0x3f4ccccd, v146
	v_mul_f32_e32 v50, v50, v66
	v_mul_f32_e32 v50, v163, v50
	v_bfe_u32 v67, v50, 16, 1
	s_waitcnt lgkmcnt(0)
; DI unsigned short f2bf(float x) { unsigned u = __float_as_uint(x); u += 0x7fffu + ((u >> 16) & 1u); return (unsigned short)(u >> 16); }
; DI float shx(float v, int mask, int lane) { return __int_as_float(__builtin_amdgcn_ds_bpermute((lane ^ mask) << 2, __float_as_int(v))); }
; DI int crow(int r, int hi) { return (r & 3) + 8 * (r >> 2) + 4 * hi; }
; template <int DQK, int MODE, int LDQ, int LDK, int LDV> ...
;     ...
;     for (int r = 0; r < 16; ++r) { const int orow = wid * 32 + crow(r, hi); const float rl = __builtin_amdgcn_rcpf(li_l[crow(r, hi)]);
;         if constexpr (MODE == 0) {
; #pragma unroll
;             for (int d0 = 0; d0 < 4; ++d0) AOb[(size_t)orow * 1024 + d0 * 32 + r32] = f2bf(o[d0][r] * rl);
;         } else if constexpr (MODE == 1) {
; #pragma unroll
;             for (int d0 = 0; d0 < 4; ++d0) S0[(size_t)orow * 512 + d0 * 32 + r32] = o[d0][r] * rl;
;         } else {
;             float v[4]; float ss = 0.f;
; #pragma unroll
;             for (int d0 = 0; d0 < 4; ++d0) { v[d0] = s0v[r][d0] - lam * (o[d0][r] * rl); ss += v[d0] * v[d0]; }
; #pragma unroll
;             for (int mk = 1; mk <= 16; mk <<= 1) ss += shx(ss, mk, lane2);
;             const float rs = rsqrtf(ss * (1.f / 128.f) + EPS) * 0.8f;
; #pragma unroll
;             for (int d0 = 0; d0 < 4; ++d0) AOb[(size_t)orow * 1024 + d0 * 32 + r32] = f2bf(v[d0] * rs * gout[d0 * 32 + r32]);
	v_pk_add_f32 v[20:21], v[20:21], v[34:35]
	ds_bpermute_b32 v35, v165, v21
	ds_bpermute_b32 v34, v165, v20
	v_lshl_add_u64 v[36:37], v[32:33], 0, v[136:137]
	v_add3_u32 v50, v50, v67, s68
	global_store_short_d16_hi v[36:37], v50, off offset:1024
	v_mul_f32_e32 v50, v51, v66
	s_waitcnt lgkmcnt(0)
	v_pk_add_f32 v[20:21], v[20:21], v[34:35]
	ds_bpermute_b32 v35, v168, v21
	ds_bpermute_b32 v34, v168, v20
	v_mul_f32_e32 v50, v162, v50
	v_bfe_u32 v51, v50, 16, 1
	v_mul_f32_e32 v3, v3, v66
	v_add3_u32 v50, v50, v51, s68
	s_waitcnt lgkmcnt(0)
	v_pk_add_f32 v[20:21], v[20:21], v[34:35]
	ds_bpermute_b32 v35, v167, v21
	ds_bpermute_b32 v34, v167, v20
	v_mul_f32_e32 v3, v161, v3
	global_store_short_d16_hi v[36:37], v50, off offset:1088
	v_bfe_u32 v50, v3, 16, 1
	v_add3_u32 v3, v3, v50, s68
	s_waitcnt lgkmcnt(0)
	v_pk_add_f32 v[20:21], v[20:21], v[34:35]
	ds_bpermute_b32 v35, v166, v21
	ds_bpermute_b32 v34, v166, v20
	v_mul_f32_e32 v2, v2, v66
	global_store_short_d16_hi v[36:37], v3, off offset:1152
	v_mul_f32_e32 v50, v130, v2
	v_bfe_u32 v51, v50, 16, 1
	s_waitcnt lgkmcnt(0)
	v_pk_add_f32 v[2:3], v[20:21], v[34:35]
	s_nop 0
	v_pk_fma_f32 v[2:3], v[2:3], s[24:25], v[92:93] op_sel_hi:[1,0,0]
	s_nop 0
	v_mul_f32_e32 v20, 0x4b800000, v3
	v_cmp_gt_f32_e32 vcc, s67, v3
	s_nop 1
	v_cndmask_b32_e32 v3, v3, v20, vcc
	v_rsq_f32_e32 v3, v3
	v_add3_u32 v20, v50, v51, s68
	global_store_short_d16_hi v[36:37], v20, off offset:1216
	v_lshl_add_u64 v[20:21], v[32:33], 0, v[134:135]
	v_mul_f32_e32 v34, 0x45800000, v3
	v_cndmask_b32_e32 v3, v3, v34, vcc
	v_mul_f32_e32 v3, 0x3f4ccccd, v3
	v_mul_f32_e32 v18, v18, v3
	v_mul_f32_e32 v18, v163, v18
	v_bfe_u32 v34, v18, 16, 1
	v_add3_u32 v18, v18, v34, s68
	global_store_short_d16_hi v[20:21], v18, off offset:1024
	v_mul_f32_e32 v18, v19, v3
	v_mul_f32_e32 v18, v162, v18
	v_bfe_u32 v19, v18, 16, 1
	v_mul_f32_e32 v1, v1, v3
	v_add3_u32 v18, v18, v19, s68
	v_mul_f32_e32 v1, v161, v1
	global_store_short_d16_hi v[20:21], v18, off offset:1088
	v_bfe_u32 v18, v1, 16, 1
	v_add3_u32 v1, v1, v18, s68
	global_store_short_d16_hi v[20:21], v1, off offset:1152
	v_mul_f32_e32 v1, 0x4b800000, v2
	v_cmp_gt_f32_e32 vcc, s67, v2
	v_mul_f32_e32 v0, v0, v3
	v_mul_f32_e32 v0, v130, v0
	v_cndmask_b32_e32 v1, v2, v1, vcc
	v_rsq_f32_e32 v1, v1
	v_bfe_u32 v2, v0, 16, 1
	v_add3_u32 v0, v0, v2, s68
	global_store_short_d16_hi v[20:21], v0, off offset:1216
	v_mul_f32_e32 v2, 0x45800000, v1
	v_rcp_f32_e32 v0, v70
	v_cndmask_b32_e32 v66, v1, v2, vcc
	v_mov_b32_e32 v2, v6
	v_rcp_f32_e32 v6, v71
	v_mov_b32_e32 v3, v54
	v_mov_b32_e32 v18, v38
	v_mov_b32_e32 v19, v22
	v_mov_b32_e32 v54, v7
	v_pk_mul_f32 v[2:3], v[2:3], v[0:1] op_sel_hi:[1,0]
	v_pk_mul_f32 v[0:1], v[18:19], v[0:1] op_sel_hi:[1,0]
	v_pk_mul_f32 v[18:19], v[54:55], v[6:7] op_sel_hi:[1,0]
	v_mov_b32_e32 v22, v39
	v_pk_fma_f32 v[2:3], v[128:129], v[2:3], v[132:133] neg_lo:[1,0,0] neg_hi:[1,0,0]
	v_pk_fma_f32 v[20:21], v[128:129], v[18:19], v[124:125] neg_lo:[1,0,0] neg_hi:[1,0,0]
	v_pk_mul_f32 v[6:7], v[22:23], v[6:7] op_sel_hi:[1,0]
	v_pk_mul_f32 v[34:35], v[2:3], v[2:3]
	v_pk_fma_f32 v[0:1], v[128:129], v[0:1], v[126:127] neg_lo:[1,0,0] neg_hi:[1,0,0]
	v_pk_mul_f32 v[50:51], v[20:21], v[20:21]
	v_pk_fma_f32 v[18:19], v[128:129], v[6:7], v[122:123] neg_lo:[1,0,0] neg_hi:[1,0,0]
	v_pk_mul_f32 v[36:37], v[0:1], v[0:1]
	v_pk_mul_f32 v[6:7], v[18:19], v[18:19]
	v_mov_b32_e32 v22, v50
	v_mov_b32_e32 v23, v34
	v_mov_b32_e32 v34, v51
	v_pk_add_f32 v[22:23], v[22:23], v[34:35]
	v_mov_b32_e32 v34, v7
	v_mov_b32_e32 v35, v37
	v_pk_add_f32 v[22:23], v[34:35], v[22:23]
	v_mov_b32_e32 v7, v36
	v_pk_add_f32 v[6:7], v[6:7], v[22:23]
	ds_bpermute_b32 v23, v164, v7
	ds_bpermute_b32 v22, v164, v6
	v_mul_f32_e32 v36, 0x3f4ccccd, v66
	v_mul_f32_e32 v37, v52, v36
	v_mul_f32_e32 v37, v163, v37
	v_bfe_u32 v38, v37, 16, 1
	s_waitcnt lgkmcnt(0)
	v_pk_add_f32 v[6:7], v[6:7], v[22:23]
	ds_bpermute_b32 v23, v165, v7
	ds_bpermute_b32 v22, v165, v6
	v_lshl_add_u64 v[34:35], v[32:33], 0, v[120:121]
	v_add3_u32 v37, v37, v38, s68
	global_store_short_d16_hi v[34:35], v37, off offset:1024
	v_mul_f32_e32 v37, v53, v36
	s_waitcnt lgkmcnt(0)
	v_pk_add_f32 v[6:7], v[6:7], v[22:23]
	ds_bpermute_b32 v23, v168, v7
	ds_bpermute_b32 v22, v168, v6
	v_mul_f32_e32 v37, v162, v37
	v_bfe_u32 v38, v37, 16, 1
	v_mul_f32_e32 v5, v5, v36
	v_add3_u32 v37, v37, v38, s68
	s_waitcnt lgkmcnt(0)
	v_pk_add_f32 v[6:7], v[6:7], v[22:23]
	ds_bpermute_b32 v23, v167, v7
	ds_bpermute_b32 v22, v167, v6
	v_mul_f32_e32 v5, v161, v5
	global_store_short_d16_hi v[34:35], v37, off offset:1088
	v_bfe_u32 v37, v5, 16, 1
	v_add3_u32 v5, v5, v37, s68
	s_waitcnt lgkmcnt(0)
	v_pk_add_f32 v[6:7], v[6:7], v[22:23]
	ds_bpermute_b32 v23, v166, v7
	ds_bpermute_b32 v22, v166, v6
	v_mul_f32_e32 v4, v4, v36
	global_store_short_d16_hi v[34:35], v5, off offset:1152
	v_mul_f32_e32 v36, v130, v4
	v_bfe_u32 v37, v36, 16, 1
	s_waitcnt lgkmcnt(0)
	v_pk_add_f32 v[4:5], v[6:7], v[22:23]
	v_lshl_add_u64 v[22:23], v[32:33], 0, v[118:119]
	v_pk_fma_f32 v[4:5], v[4:5], s[24:25], v[92:93] op_sel_hi:[1,0,0]
	s_nop 0
	v_mul_f32_e32 v6, 0x4b800000, v5
	v_cmp_gt_f32_e32 vcc, s67, v5
	s_nop 1
	v_cndmask_b32_e32 v5, v5, v6, vcc
	v_rsq_f32_e32 v5, v5
	v_add3_u32 v6, v36, v37, s68
	global_store_short_d16_hi v[34:35], v6, off offset:1216
	v_mov_b32_e32 v36, v40
	v_mul_f32_e32 v6, 0x45800000, v5
	v_cndmask_b32_e32 v5, v5, v6, vcc
	v_mul_f32_e32 v5, 0x3f4ccccd, v5
	v_mul_f32_e32 v2, v2, v5
	v_mul_f32_e32 v2, v163, v2
	v_bfe_u32 v6, v2, 16, 1
	v_add3_u32 v2, v2, v6, s68
	global_store_short_d16_hi v[22:23], v2, off offset:1024
	v_mul_f32_e32 v2, v3, v5
	v_mul_f32_e32 v2, v162, v2
	v_bfe_u32 v3, v2, 16, 1
	v_mul_f32_e32 v1, v1, v5
	v_add3_u32 v2, v2, v3, s68
	v_mul_f32_e32 v1, v161, v1
	global_store_short_d16_hi v[22:23], v2, off offset:1088
	v_bfe_u32 v2, v1, 16, 1
	v_add3_u32 v1, v1, v2, s68
	v_mul_f32_e32 v2, 0x4b800000, v4
	v_cmp_gt_f32_e32 vcc, s67, v4
	v_mul_f32_e32 v0, v0, v5
	v_mul_f32_e32 v0, v130, v0
	v_cndmask_b32_e32 v2, v4, v2, vcc
	ds_read_b128 v[4:7], v169 offset:64
	global_store_short_d16_hi v[22:23], v1, off offset:1152
	v_bfe_u32 v1, v0, 16, 1
	v_rsq_f32_e32 v34, v2
	v_add3_u32 v0, v0, v1, s68
	global_store_short_d16_hi v[22:23], v0, off offset:1216
	ds_read_b128 v[0:3], v169 offset:96
	s_waitcnt lgkmcnt(1)
; DI unsigned short f2bf(float x) { unsigned u = __float_as_uint(x); u += 0x7fffu + ((u >> 16) & 1u); return (unsigned short)(u >> 16); }
; DI float shx(float v, int mask, int lane) { return __int_as_float(__builtin_amdgcn_ds_bpermute((lane ^ mask) << 2, __float_as_int(v))); }
; DI int crow(int r, int hi) { return (r & 3) + 8 * (r >> 2) + 4 * hi; }
; template <int DQK, int MODE, int LDQ, int LDK, int LDV> ...
;     ...
;     for (int r = 0; r < 16; ++r) { const int orow = wid * 32 + crow(r, hi); const float rl = __builtin_amdgcn_rcpf(li_l[crow(r, hi)]);
;         if constexpr (MODE == 0) {
; #pragma unroll
;             for (int d0 = 0; d0 < 4; ++d0) AOb[(size_t)orow * 1024 + d0 * 32 + r32] = f2bf(o[d0][r] * rl);
;         } else if constexpr (MODE == 1) {
; #pragma unroll
;             for (int d0 = 0; d0 < 4; ++d0) S0[(size_t)orow * 512 + d0 * 32 + r32] = o[d0][r] * rl;
;         } else {
;             float v[4]; float ss = 0.f;
; #pragma unroll
;             for (int d0 = 0; d0 < 4; ++d0) { v[d0] = s0v[r][d0] - lam * (o[d0][r] * rl); ss += v[d0] * v[d0]; }
; #pragma unroll
;             for (int mk = 1; mk <= 16; mk <<= 1) ss += shx(ss, mk, lane2);
;             const float rs = rsqrtf(ss * (1.f / 128.f) + EPS) * 0.8f;
; #pragma unroll
;             for (int d0 = 0; d0 < 4; ++d0) AOb[(size_t)orow * 1024 + d0 * 32 + r32] = f2bf(v[d0] * rs * gout[d0 * 32 + r32]);
	v_rcp_f32_e32 v4, v4
	v_mul_f32_e32 v22, 0x45800000, v34
	v_cndmask_b32_e32 v52, v34, v22, vcc
	v_mov_b32_e32 v22, v8
	v_mov_b32_e32 v23, v56
	v_mov_b32_e32 v37, v24
	v_pk_mul_f32 v[22:23], v[22:23], v[4:5] op_sel_hi:[1,0]
	v_pk_mul_f32 v[36:37], v[36:37], v[4:5] op_sel_hi:[1,0]
	v_rcp_f32_e32 v4, v5
	v_mov_b32_e32 v56, v9
	v_mov_b32_e32 v24, v41
	v_pk_fma_f32 v[22:23], v[128:129], v[22:23], v[100:101] neg_lo:[1,0,0] neg_hi:[1,0,0]
	v_pk_mul_f32 v[8:9], v[56:57], v[4:5] op_sel_hi:[1,0]
	v_pk_mul_f32 v[4:5], v[24:25], v[4:5] op_sel_hi:[1,0]
	v_pk_fma_f32 v[8:9], v[128:129], v[8:9], v[96:97] neg_lo:[1,0,0] neg_hi:[1,0,0]
	v_pk_mul_f32 v[34:35], v[22:23], v[22:23]
	v_pk_fma_f32 v[36:37], v[128:129], v[36:37], v[98:99] neg_lo:[1,0,0] neg_hi:[1,0,0]
	v_pk_mul_f32 v[50:51], v[8:9], v[8:9]
	v_pk_fma_f32 v[4:5], v[128:129], v[4:5], v[94:95] neg_lo:[1,0,0] neg_hi:[1,0,0]
	v_pk_mul_f32 v[38:39], v[36:37], v[36:37]
	v_pk_mul_f32 v[24:25], v[4:5], v[4:5]
	v_mov_b32_e32 v40, v50
	v_mov_b32_e32 v41, v34
	v_mov_b32_e32 v34, v51
	v_pk_add_f32 v[34:35], v[40:41], v[34:35]
	v_mov_b32_e32 v40, v25
	v_mov_b32_e32 v41, v39
	v_pk_add_f32 v[34:35], v[40:41], v[34:35]
	v_mov_b32_e32 v25, v38
	v_pk_add_f32 v[24:25], v[24:25], v[34:35]
	ds_bpermute_b32 v35, v164, v25
	ds_bpermute_b32 v34, v164, v24
	v_mul_f32_e32 v40, 0x3f4ccccd, v52
	v_mul_f32_e32 v20, v20, v40
	v_mul_f32_e32 v20, v163, v20
	v_bfe_u32 v41, v20, 16, 1
	s_waitcnt lgkmcnt(0)
	v_pk_add_f32 v[24:25], v[24:25], v[34:35]
	ds_bpermute_b32 v35, v165, v25
	ds_bpermute_b32 v34, v165, v24
	v_lshl_add_u64 v[38:39], v[32:33], 0, v[90:91]
	v_add3_u32 v20, v20, v41, s68
	global_store_short_d16_hi v[38:39], v20, off offset:1024
	v_mul_f32_e32 v41, v21, v40
	s_waitcnt lgkmcnt(0)
	v_pk_add_f32 v[20:21], v[24:25], v[34:35]
	ds_bpermute_b32 v25, v168, v21
	ds_bpermute_b32 v24, v168, v20
	v_mul_f32_e32 v34, v162, v41
	v_bfe_u32 v35, v34, 16, 1
	v_mul_f32_e32 v19, v19, v40
	v_add3_u32 v34, v34, v35, s68
	s_waitcnt lgkmcnt(0)
	v_pk_add_f32 v[20:21], v[20:21], v[24:25]
	ds_bpermute_b32 v25, v167, v21
	ds_bpermute_b32 v24, v167, v20
	v_mul_f32_e32 v19, v161, v19
	global_store_short_d16_hi v[38:39], v34, off offset:1088
	v_bfe_u32 v34, v19, 16, 1
	v_add3_u32 v19, v19, v34, s68
	s_waitcnt lgkmcnt(0)
	v_pk_add_f32 v[20:21], v[20:21], v[24:25]
	ds_bpermute_b32 v25, v166, v21
	ds_bpermute_b32 v24, v166, v20
	v_mul_f32_e32 v18, v18, v40
	global_store_short_d16_hi v[38:39], v19, off offset:1152
	v_mul_f32_e32 v34, v130, v18
	v_bfe_u32 v35, v34, 16, 1
	s_waitcnt lgkmcnt(0)
	v_pk_add_f32 v[18:19], v[20:21], v[24:25]
	v_rcp_f32_e32 v6, v6
	v_pk_fma_f32 v[18:19], v[18:19], s[24:25], v[92:93] op_sel_hi:[1,0,0]
	v_rcp_f32_e32 v0, v0
	v_mul_f32_e32 v20, 0x4b800000, v19
	v_cmp_gt_f32_e32 vcc, s67, v19
	v_rcp_f32_e32 v2, v2
	s_nop 0
	v_cndmask_b32_e32 v19, v19, v20, vcc
	v_rsq_f32_e32 v19, v19
	v_add3_u32 v20, v34, v35, s68
	global_store_short_d16_hi v[38:39], v20, off offset:1216
	v_lshl_add_u64 v[20:21], v[32:33], 0, v[86:87]
	v_mul_f32_e32 v24, 0x45800000, v19
	v_cndmask_b32_e32 v19, v19, v24, vcc
	v_mul_f32_e32 v19, 0x3f4ccccd, v19
	v_mul_f32_e32 v22, v22, v19
	v_mul_f32_e32 v22, v163, v22
	v_bfe_u32 v24, v22, 16, 1
	v_add3_u32 v22, v22, v24, s68
	global_store_short_d16_hi v[20:21], v22, off offset:1024
	v_mul_f32_e32 v22, v23, v19
	v_mul_f32_e32 v22, v162, v22
	v_bfe_u32 v23, v22, 16, 1
	v_add3_u32 v22, v22, v23, s68
	global_store_short_d16_hi v[20:21], v22, off offset:1088
	v_mul_f32_e32 v22, v37, v19
	v_mul_f32_e32 v22, v161, v22
	v_bfe_u32 v23, v22, 16, 1
	v_add3_u32 v22, v22, v23, s68
	global_store_short_d16_hi v[20:21], v22, off offset:1152
	v_mul_f32_e32 v22, 0x4b800000, v18
	v_cmp_gt_f32_e32 vcc, s67, v18
	v_mul_f32_e32 v19, v36, v19
	v_mul_f32_e32 v19, v130, v19
	v_cndmask_b32_e32 v18, v18, v22, vcc
	v_rsq_f32_e32 v18, v18
	v_bfe_u32 v22, v19, 16, 1
	v_add3_u32 v19, v19, v22, s68
	global_store_short_d16_hi v[20:21], v19, off offset:1216
	v_mul_f32_e32 v19, 0x45800000, v18
	v_cndmask_b32_e32 v38, v18, v19, vcc
	v_mov_b32_e32 v18, v10
	v_mov_b32_e32 v19, v58
	v_mov_b32_e32 v22, v42
	v_mov_b32_e32 v23, v26
	v_pk_mul_f32 v[18:19], v[18:19], v[6:7] op_sel_hi:[1,0]
	v_pk_mul_f32 v[22:23], v[22:23], v[6:7] op_sel_hi:[1,0]
	v_rcp_f32_e32 v6, v7
	v_mov_b32_e32 v58, v11
	v_mov_b32_e32 v26, v43
	v_pk_fma_f32 v[18:19], v[128:129], v[18:19], v[88:89] neg_lo:[1,0,0] neg_hi:[1,0,0]
	v_pk_mul_f32 v[10:11], v[58:59], v[6:7] op_sel_hi:[1,0]
	v_pk_mul_f32 v[6:7], v[26:27], v[6:7] op_sel_hi:[1,0]
	v_pk_fma_f32 v[10:11], v[128:129], v[10:11], v[82:83] neg_lo:[1,0,0] neg_hi:[1,0,0]
	v_pk_mul_f32 v[20:21], v[18:19], v[18:19]
	v_pk_fma_f32 v[22:23], v[128:129], v[22:23], v[84:85] neg_lo:[1,0,0] neg_hi:[1,0,0]
	v_pk_mul_f32 v[34:35], v[10:11], v[10:11]
	v_pk_fma_f32 v[6:7], v[128:129], v[6:7], v[80:81] neg_lo:[1,0,0] neg_hi:[1,0,0]
	v_pk_mul_f32 v[24:25], v[22:23], v[22:23]
	v_pk_mul_f32 v[26:27], v[6:7], v[6:7]
	v_mov_b32_e32 v36, v34
	v_mov_b32_e32 v37, v20
	v_mov_b32_e32 v20, v35
	v_pk_add_f32 v[20:21], v[36:37], v[20:21]
	v_mov_b32_e32 v34, v27
	v_mov_b32_e32 v35, v25
	v_pk_add_f32 v[20:21], v[34:35], v[20:21]
	v_mov_b32_e32 v27, v24
	v_pk_add_f32 v[20:21], v[26:27], v[20:21]
	ds_bpermute_b32 v25, v164, v21
	ds_bpermute_b32 v24, v164, v20
	v_mul_f32_e32 v34, 0x3f4ccccd, v38
	v_mul_f32_e32 v8, v8, v34
	v_mul_f32_e32 v8, v163, v8
	v_bfe_u32 v35, v8, 16, 1
	s_waitcnt lgkmcnt(0)
	v_pk_add_f32 v[20:21], v[20:21], v[24:25]
	ds_bpermute_b32 v25, v165, v21
	ds_bpermute_b32 v24, v165, v20
	v_lshl_add_u64 v[26:27], v[32:33], 0, v[78:79]
	v_add3_u32 v8, v8, v35, s68
	global_store_short_d16_hi v[26:27], v8, off offset:1024
	v_mul_f32_e32 v35, v9, v34
	s_waitcnt lgkmcnt(0)
; DI unsigned short f2bf(float x) { unsigned u = __float_as_uint(x); u += 0x7fffu + ((u >> 16) & 1u); return (unsigned short)(u >> 16); }
; DI float shx(float v, int mask, int lane) { return __int_as_float(__builtin_amdgcn_ds_bpermute((lane ^ mask) << 2, __float_as_int(v))); }
; DI int crow(int r, int hi) { return (r & 3) + 8 * (r >> 2) + 4 * hi; }
; template <int DQK, int MODE, int LDQ, int LDK, int LDV> ...
;     ...
;     for (int r = 0; r < 16; ++r) { const int orow = wid * 32 + crow(r, hi); const float rl = __builtin_amdgcn_rcpf(li_l[crow(r, hi)]);
;         if constexpr (MODE == 0) {
; #pragma unroll
;             for (int d0 = 0; d0 < 4; ++d0) AOb[(size_t)orow * 1024 + d0 * 32 + r32] = f2bf(o[d0][r] * rl);
;         } else if constexpr (MODE == 1) {
; #pragma unroll
;             for (int d0 = 0; d0 < 4; ++d0) S0[(size_t)orow * 512 + d0 * 32 + r32] = o[d0][r] * rl;
;         } else {
;             float v[4]; float ss = 0.f;
; #pragma unroll
;             for (int d0 = 0; d0 < 4; ++d0) { v[d0] = s0v[r][d0] - lam * (o[d0][r] * rl); ss += v[d0] * v[d0]; }
; #pragma unroll
;             for (int mk = 1; mk <= 16; mk <<= 1) ss += shx(ss, mk, lane2);
;             const float rs = rsqrtf(ss * (1.f / 128.f) + EPS) * 0.8f;
; #pragma unroll
;             for (int d0 = 0; d0 < 4; ++d0) AOb[(size_t)orow * 1024 + d0 * 32 + r32] = f2bf(v[d0] * rs * gout[d0 * 32 + r32]);
	v_pk_add_f32 v[8:9], v[20:21], v[24:25]
	ds_bpermute_b32 v21, v168, v9
	ds_bpermute_b32 v20, v168, v8
	v_mul_f32_e32 v24, v162, v35
	v_bfe_u32 v25, v24, 16, 1
	v_mul_f32_e32 v5, v5, v34
	v_add3_u32 v24, v24, v25, s68
	s_waitcnt lgkmcnt(0)
	v_pk_add_f32 v[8:9], v[8:9], v[20:21]
	ds_bpermute_b32 v21, v167, v9
	ds_bpermute_b32 v20, v167, v8
	v_mul_f32_e32 v5, v161, v5
	global_store_short_d16_hi v[26:27], v24, off offset:1088
	v_bfe_u32 v24, v5, 16, 1
	v_add3_u32 v5, v5, v24, s68
	s_waitcnt lgkmcnt(0)
	v_pk_add_f32 v[8:9], v[8:9], v[20:21]
	ds_bpermute_b32 v21, v166, v9
	ds_bpermute_b32 v20, v166, v8
	v_mul_f32_e32 v4, v4, v34
	global_store_short_d16_hi v[26:27], v5, off offset:1152
	v_mul_f32_e32 v24, v130, v4
	v_bfe_u32 v25, v24, 16, 1
	s_waitcnt lgkmcnt(0)
	v_pk_add_f32 v[4:5], v[8:9], v[20:21]
	s_nop 0
	v_pk_fma_f32 v[4:5], v[4:5], s[24:25], v[92:93] op_sel_hi:[1,0,0]
	s_nop 0
	v_mul_f32_e32 v8, 0x4b800000, v5
	v_cmp_gt_f32_e32 vcc, s67, v5
	s_nop 1
	v_cndmask_b32_e32 v5, v5, v8, vcc
	v_rsq_f32_e32 v5, v5
	v_add3_u32 v8, v24, v25, s68
	global_store_short_d16_hi v[26:27], v8, off offset:1216
	v_lshl_add_u64 v[8:9], v[32:33], 0, v[76:77]
	v_mul_f32_e32 v20, 0x45800000, v5
	v_cndmask_b32_e32 v5, v5, v20, vcc
	v_mul_f32_e32 v5, 0x3f4ccccd, v5
	v_mul_f32_e32 v18, v18, v5
	v_mul_f32_e32 v18, v163, v18
	v_bfe_u32 v20, v18, 16, 1
	v_add3_u32 v18, v18, v20, s68
	global_store_short_d16_hi v[8:9], v18, off offset:1024
	v_mul_f32_e32 v18, v19, v5
	v_mul_f32_e32 v18, v162, v18
	v_bfe_u32 v19, v18, 16, 1
	v_add3_u32 v18, v18, v19, s68
	global_store_short_d16_hi v[8:9], v18, off offset:1088
	v_mul_f32_e32 v18, v23, v5
	v_mul_f32_e32 v18, v161, v18
	v_bfe_u32 v19, v18, 16, 1
	v_add3_u32 v18, v18, v19, s68
	global_store_short_d16_hi v[8:9], v18, off offset:1152
	v_mul_f32_e32 v18, 0x4b800000, v4
	v_cmp_gt_f32_e32 vcc, s67, v4
	v_mul_f32_e32 v5, v22, v5
	v_mul_f32_e32 v5, v130, v5
	v_cndmask_b32_e32 v4, v4, v18, vcc
	v_rsq_f32_e32 v4, v4
	v_bfe_u32 v18, v5, 16, 1
	v_add3_u32 v5, v5, v18, s68
	global_store_short_d16_hi v[8:9], v5, off offset:1216
	v_mul_f32_e32 v5, 0x45800000, v4
	v_cndmask_b32_e32 v34, v4, v5, vcc
	v_mov_b32_e32 v4, v12
	v_mov_b32_e32 v5, v60
	v_mov_b32_e32 v18, v44
	v_mov_b32_e32 v19, v28
	v_pk_mul_f32 v[4:5], v[4:5], v[0:1] op_sel_hi:[1,0]
	v_pk_mul_f32 v[18:19], v[18:19], v[0:1] op_sel_hi:[1,0]
	v_rcp_f32_e32 v0, v1
	v_mov_b32_e32 v60, v13
	v_mov_b32_e32 v28, v45
	s_waitcnt vmcnt(58)
	v_pk_fma_f32 v[4:5], v[128:129], v[4:5], v[116:117] neg_lo:[1,0,0] neg_hi:[1,0,0]
	v_pk_mul_f32 v[12:13], v[60:61], v[0:1] op_sel_hi:[1,0]
	v_pk_mul_f32 v[0:1], v[28:29], v[0:1] op_sel_hi:[1,0]
	s_waitcnt vmcnt(54)
	v_pk_fma_f32 v[12:13], v[128:129], v[12:13], v[112:113] neg_lo:[1,0,0] neg_hi:[1,0,0]
	v_pk_mul_f32 v[8:9], v[4:5], v[4:5]
	v_pk_fma_f32 v[18:19], v[128:129], v[18:19], v[114:115] neg_lo:[1,0,0] neg_hi:[1,0,0]
	v_pk_mul_f32 v[22:23], v[12:13], v[12:13]
	s_waitcnt vmcnt(52)
	v_pk_fma_f32 v[0:1], v[128:129], v[0:1], v[110:111] neg_lo:[1,0,0] neg_hi:[1,0,0]
	v_pk_mul_f32 v[20:21], v[18:19], v[18:19]
	v_pk_mul_f32 v[24:25], v[0:1], v[0:1]
	v_mov_b32_e32 v26, v22
	v_mov_b32_e32 v27, v8
	v_mov_b32_e32 v8, v23
	v_pk_add_f32 v[8:9], v[26:27], v[8:9]
	v_mov_b32_e32 v22, v25
	v_mov_b32_e32 v23, v21
	v_pk_add_f32 v[8:9], v[22:23], v[8:9]
	v_mov_b32_e32 v25, v20
	v_pk_add_f32 v[8:9], v[24:25], v[8:9]
	ds_bpermute_b32 v21, v164, v9
	ds_bpermute_b32 v20, v164, v8
	v_mul_f32_e32 v24, 0x3f4ccccd, v34
	v_mul_f32_e32 v10, v10, v24
	v_mul_f32_e32 v10, v163, v10
	v_bfe_u32 v25, v10, 16, 1
	s_waitcnt lgkmcnt(0)
	v_pk_add_f32 v[8:9], v[8:9], v[20:21]
	ds_bpermute_b32 v21, v165, v9
	ds_bpermute_b32 v20, v165, v8
	v_lshl_add_u64 v[22:23], v[32:33], 0, v[72:73]
	v_add3_u32 v10, v10, v25, s68
	global_store_short_d16_hi v[22:23], v10, off offset:1024
	v_mul_f32_e32 v25, v11, v24
	s_waitcnt lgkmcnt(0)
	v_pk_add_f32 v[8:9], v[8:9], v[20:21]
	ds_bpermute_b32 v11, v168, v9
	ds_bpermute_b32 v10, v168, v8
	v_mul_f32_e32 v20, v162, v25
	v_bfe_u32 v21, v20, 16, 1
	v_mul_f32_e32 v7, v7, v24
	v_add3_u32 v20, v20, v21, s68
	s_waitcnt lgkmcnt(0)
	v_pk_add_f32 v[8:9], v[8:9], v[10:11]
	ds_bpermute_b32 v11, v167, v9
	ds_bpermute_b32 v10, v167, v8
	v_mul_f32_e32 v7, v161, v7
	global_store_short_d16_hi v[22:23], v20, off offset:1088
	v_bfe_u32 v20, v7, 16, 1
	v_add3_u32 v7, v7, v20, s68
	s_waitcnt lgkmcnt(0)
	v_pk_add_f32 v[8:9], v[8:9], v[10:11]
	ds_bpermute_b32 v11, v166, v9
	ds_bpermute_b32 v10, v166, v8
	v_mul_f32_e32 v6, v6, v24
	global_store_short_d16_hi v[22:23], v7, off offset:1152
	v_mul_f32_e32 v20, v130, v6
	v_bfe_u32 v21, v20, 16, 1
	s_waitcnt lgkmcnt(0)
; DI unsigned short f2bf(float x) { unsigned u = __float_as_uint(x); u += 0x7fffu + ((u >> 16) & 1u); return (unsigned short)(u >> 16); }
; DI float shx(float v, int mask, int lane) { return __int_as_float(__builtin_amdgcn_ds_bpermute((lane ^ mask) << 2, __float_as_int(v))); }
; DI int crow(int r, int hi) { return (r & 3) + 8 * (r >> 2) + 4 * hi; }
; template <int DQK, int MODE, int LDQ, int LDK, int LDV> ...
;     ...
;     for (int r = 0; r < 16; ++r) { const int orow = wid * 32 + crow(r, hi); const float rl = __builtin_amdgcn_rcpf(li_l[crow(r, hi)]);
;         if constexpr (MODE == 0) {
; #pragma unroll
;             for (int d0 = 0; d0 < 4; ++d0) AOb[(size_t)orow * 1024 + d0 * 32 + r32] = f2bf(o[d0][r] * rl);
;         } else if constexpr (MODE == 1) {
; #pragma unroll
;             for (int d0 = 0; d0 < 4; ++d0) S0[(size_t)orow * 512 + d0 * 32 + r32] = o[d0][r] * rl;
;         } else {
;             float v[4]; float ss = 0.f;
; #pragma unroll
;             for (int d0 = 0; d0 < 4; ++d0) { v[d0] = s0v[r][d0] - lam * (o[d0][r] * rl); ss += v[d0] * v[d0]; }
; #pragma unroll
;             for (int mk = 1; mk <= 16; mk <<= 1) ss += shx(ss, mk, lane2);
;             const float rs = rsqrtf(ss * (1.f / 128.f) + EPS) * 0.8f;
; #pragma unroll
;             for (int d0 = 0; d0 < 4; ++d0) AOb[(size_t)orow * 1024 + d0 * 32 + r32] = f2bf(v[d0] * rs * gout[d0 * 32 + r32]);
;         } }
	v_pk_add_f32 v[6:7], v[8:9], v[10:11]
	s_nop 0
	v_pk_fma_f32 v[6:7], v[6:7], s[24:25], v[92:93] op_sel_hi:[1,0,0]
	s_nop 0
	v_mul_f32_e32 v8, 0x4b800000, v7
	v_cmp_gt_f32_e32 vcc, s67, v7
	s_nop 1
	v_cndmask_b32_e32 v7, v7, v8, vcc
	v_rsq_f32_e32 v7, v7
	v_add3_u32 v8, v20, v21, s68
	global_store_short_d16_hi v[22:23], v8, off offset:1216
	v_lshl_add_u64 v[8:9], v[32:33], 0, v[74:75]
	v_mul_f32_e32 v10, 0x45800000, v7
	v_cndmask_b32_e32 v7, v7, v10, vcc
	v_mul_f32_e32 v7, 0x3f4ccccd, v7
	v_mul_f32_e32 v4, v4, v7
	v_mul_f32_e32 v4, v163, v4
	v_bfe_u32 v10, v4, 16, 1
	v_add3_u32 v4, v4, v10, s68
	global_store_short_d16_hi v[8:9], v4, off offset:1024
	v_mul_f32_e32 v4, v5, v7
	v_mul_f32_e32 v4, v162, v4
	v_bfe_u32 v5, v4, 16, 1
	v_add3_u32 v4, v4, v5, s68
	global_store_short_d16_hi v[8:9], v4, off offset:1088
	v_mul_f32_e32 v4, v19, v7
	v_mul_f32_e32 v4, v161, v4
	v_bfe_u32 v5, v4, 16, 1
	v_add3_u32 v4, v4, v5, s68
	v_mul_f32_e32 v5, 0x4b800000, v6
	v_cmp_gt_f32_e32 vcc, s67, v6
	global_store_short_d16_hi v[8:9], v4, off offset:1152
	v_mul_f32_e32 v4, v18, v7
	v_cndmask_b32_e32 v5, v6, v5, vcc
	v_rsq_f32_e32 v5, v5
	v_mul_f32_e32 v4, v130, v4
	v_bfe_u32 v6, v4, 16, 1
	v_add3_u32 v4, v4, v6, s68
	global_store_short_d16_hi v[8:9], v4, off offset:1216
	v_mul_f32_e32 v4, 0x45800000, v5
	v_cndmask_b32_e32 v24, v5, v4, vcc
	v_mov_b32_e32 v4, v14
	v_mov_b32_e32 v5, v62
	v_mov_b32_e32 v8, v46
	v_mov_b32_e32 v9, v30
	v_pk_mul_f32 v[4:5], v[4:5], v[2:3] op_sel_hi:[1,0]
	v_pk_mul_f32 v[8:9], v[8:9], v[2:3] op_sel_hi:[1,0]
	v_rcp_f32_e32 v2, v3
	v_mov_b32_e32 v62, v15
	v_mov_b32_e32 v30, v47
	s_waitcnt vmcnt(58)
	v_pk_fma_f32 v[4:5], v[128:129], v[4:5], v[108:109] neg_lo:[1,0,0] neg_hi:[1,0,0]
	v_pk_mul_f32 v[14:15], v[62:63], v[2:3] op_sel_hi:[1,0]
	v_pk_mul_f32 v[2:3], v[30:31], v[2:3] op_sel_hi:[1,0]
	s_waitcnt vmcnt(54)
	v_pk_fma_f32 v[14:15], v[128:129], v[14:15], v[104:105] neg_lo:[1,0,0] neg_hi:[1,0,0]
	v_pk_mul_f32 v[6:7], v[4:5], v[4:5]
	v_pk_fma_f32 v[8:9], v[128:129], v[8:9], v[106:107] neg_lo:[1,0,0] neg_hi:[1,0,0]
	v_pk_mul_f32 v[18:19], v[14:15], v[14:15]
	s_waitcnt vmcnt(52)
	v_pk_fma_f32 v[2:3], v[128:129], v[2:3], v[102:103] neg_lo:[1,0,0] neg_hi:[1,0,0]
	v_pk_mul_f32 v[10:11], v[8:9], v[8:9]
	v_pk_mul_f32 v[20:21], v[2:3], v[2:3]
	v_mov_b32_e32 v22, v18
	v_mov_b32_e32 v23, v6
	v_mov_b32_e32 v6, v19
	v_pk_add_f32 v[6:7], v[22:23], v[6:7]
	v_mov_b32_e32 v18, v21
	v_mov_b32_e32 v19, v11
	v_pk_add_f32 v[6:7], v[18:19], v[6:7]
	v_mov_b32_e32 v21, v10
	v_pk_add_f32 v[6:7], v[20:21], v[6:7]
	ds_bpermute_b32 v11, v164, v7
	ds_bpermute_b32 v10, v164, v6
	v_mul_f32_e32 v20, 0x3f4ccccd, v24
	v_mul_f32_e32 v12, v12, v20
	v_mul_f32_e32 v12, v163, v12
	v_bfe_u32 v21, v12, 16, 1
	s_waitcnt lgkmcnt(0)
	v_pk_add_f32 v[6:7], v[6:7], v[10:11]
	ds_bpermute_b32 v11, v165, v7
	ds_bpermute_b32 v10, v165, v6
	v_lshl_add_u64 v[18:19], v[32:33], 0, v[64:65]
	v_add3_u32 v12, v12, v21, s68
	global_store_short_d16_hi v[18:19], v12, off offset:1024
	v_mul_f32_e32 v12, v13, v20
	s_waitcnt lgkmcnt(0)
	v_pk_add_f32 v[6:7], v[6:7], v[10:11]
	ds_bpermute_b32 v11, v168, v7
	ds_bpermute_b32 v10, v168, v6
	v_mul_f32_e32 v12, v162, v12
	v_bfe_u32 v13, v12, 16, 1
	v_mul_f32_e32 v1, v1, v20
	v_add3_u32 v12, v12, v13, s68
	s_waitcnt lgkmcnt(0)
	v_pk_add_f32 v[6:7], v[6:7], v[10:11]
	ds_bpermute_b32 v11, v167, v7
	ds_bpermute_b32 v10, v167, v6
	v_mul_f32_e32 v1, v161, v1
	global_store_short_d16_hi v[18:19], v12, off offset:1088
	v_bfe_u32 v12, v1, 16, 1
	v_add3_u32 v1, v1, v12, s68
	s_waitcnt lgkmcnt(0)
	v_pk_add_f32 v[6:7], v[6:7], v[10:11]
	ds_bpermute_b32 v11, v166, v7
	ds_bpermute_b32 v10, v166, v6
	v_mul_f32_e32 v0, v0, v20
	global_store_short_d16_hi v[18:19], v1, off offset:1152
	v_mul_f32_e32 v12, v130, v0
	v_bfe_u32 v13, v12, 16, 1
	s_waitcnt lgkmcnt(0)
	v_pk_add_f32 v[0:1], v[6:7], v[10:11]
	s_nop 0
	v_pk_fma_f32 v[0:1], v[0:1], s[24:25], v[92:93] op_sel_hi:[1,0,0]
	s_nop 0
	v_mul_f32_e32 v6, 0x4b800000, v1
	v_cmp_gt_f32_e32 vcc, s67, v1
	s_nop 1
	v_cndmask_b32_e32 v1, v1, v6, vcc
	v_rsq_f32_e32 v1, v1
	v_add3_u32 v6, v12, v13, s68
	global_store_short_d16_hi v[18:19], v6, off offset:1216
	v_lshl_add_u64 v[6:7], v[32:33], 0, v[48:49]
	v_mul_f32_e32 v10, 0x45800000, v1
	v_cndmask_b32_e32 v1, v1, v10, vcc
	v_mul_f32_e32 v1, 0x3f4ccccd, v1
	v_mul_f32_e32 v4, v4, v1
	v_mul_f32_e32 v4, v163, v4
	v_bfe_u32 v10, v4, 16, 1
	v_add3_u32 v4, v4, v10, s68
	global_store_short_d16_hi v[6:7], v4, off offset:1024
	v_mul_f32_e32 v4, v5, v1
	v_mul_f32_e32 v4, v162, v4
	v_bfe_u32 v5, v4, 16, 1
	v_add3_u32 v4, v4, v5, s68
	global_store_short_d16_hi v[6:7], v4, off offset:1088
	v_mul_f32_e32 v4, v9, v1
	v_mul_f32_e32 v4, v161, v4
	v_bfe_u32 v5, v4, 16, 1
	v_add3_u32 v4, v4, v5, s68
	global_store_short_d16_hi v[6:7], v4, off offset:1152
	v_mul_f32_e32 v4, 0x4b800000, v0
	v_cmp_gt_f32_e32 vcc, s67, v0
	v_mul_f32_e32 v1, v8, v1
	v_mul_f32_e32 v1, v130, v1
	v_cndmask_b32_e32 v0, v0, v4, vcc
	v_rsq_f32_e32 v0, v0
	v_bfe_u32 v4, v1, 16, 1
	v_add3_u32 v1, v1, v4, s68
	global_store_short_d16_hi v[6:7], v1, off offset:1216
	v_mul_f32_e32 v1, 0x45800000, v0
	v_cndmask_b32_e32 v0, v0, v1, vcc
	v_mul_f32_e32 v4, 0x3f4ccccd, v0
	v_mul_f32_e32 v5, v14, v4
	v_mul_f32_e32 v5, v163, v5
	v_bfe_u32 v6, v5, 16, 1
	v_lshl_add_u64 v[0:1], v[32:33], 0, v[16:17]
	v_add3_u32 v5, v5, v6, s68
	global_store_short_d16_hi v[0:1], v5, off offset:1024
	v_mul_f32_e32 v5, v15, v4
	v_mul_f32_e32 v5, v162, v5
	v_bfe_u32 v6, v5, 16, 1
	v_mul_f32_e32 v3, v3, v4
	v_add3_u32 v5, v5, v6, s68
	v_mul_f32_e32 v3, v161, v3
	global_store_short_d16_hi v[0:1], v5, off offset:1088
	v_bfe_u32 v5, v3, 16, 1
	v_mul_f32_e32 v2, v2, v4
	v_add3_u32 v3, v3, v5, s68
	v_mul_f32_e32 v2, v130, v2
	global_store_short_d16_hi v[0:1], v3, off offset:1152
	v_bfe_u32 v3, v2, 16, 1
	v_add3_u32 v2, v2, v3, s68
	global_store_short_d16_hi v[0:1], v2, off offset:1216
	s_waitcnt vmcnt(63) expcnt(7) lgkmcnt(15)
	s_barrier

.Lstg_mla_top_2:
	s_setprio 0
	s_mov_b32 m0, s1
	s_mov_b32 s0, s5
	s_mov_b32 s5, s44
	s_mov_b32 s44, s4
	s_lshl_b32 s4, s4, 14
	global_load_lds_dwordx4 v136, s[34:35]
	s_add_i32 m0, s1, 0x2000
	s_add_i32 s4, s52, s4
	global_load_lds_dwordx4 v138, s[34:35]
	s_add_i32 m0, s1, 0x4000
	s_add_i32 s6, s4, 0x400
	global_load_lds_dwordx4 v140, s[34:35]
	s_mov_b32 m0, s4
	s_add_i32 s1, s43, -3
	global_load_lds_dwordx4 v144, s[34:35]
	s_mov_b32 m0, s6
	s_nop 0
	global_load_lds_dwordx4 v142, s[34:35]
	s_and_b32 s1, s1, 3
	s_mulk_i32 s1, 0x6000
	v_add_u32_e32 v246, s1, v158
	v_add_u32_e32 v174, v246, v151
	v_add_u32_e32 v178, v246, v149
	v_add_u32_e32 v182, v246, v148
	v_add_u32_e32 v186, v246, v147
	s_lshl_b32 s1, s0, 14
	ds_read_b128 v[190:193], v174 offset:12416
	ds_read_b128 v[194:197], v178 offset:12416
	ds_read_b128 v[174:177], v174 offset:12288
	ds_read_b128 v[178:181], v178 offset:12288
	ds_read_b128 v[182:185], v182 offset:12288
	ds_read_b128 v[186:189], v186 offset:12288
	v_add_u32_e32 v254, s1, v130
	ds_read_b64_tr_b16 v[198:199], v254 offset:0
	ds_read_b64_tr_b16 v[200:201], v254 offset:0x800
	ds_read_b64_tr_b16 v[202:203], v254 offset:0x1000
	ds_read_b64_tr_b16 v[204:205], v254 offset:0x1800
	ds_read_b64_tr_b16 v[206:207], v254 offset:0x200
	ds_read_b64_tr_b16 v[208:209], v254 offset:0xa00
	ds_read_b64_tr_b16 v[210:211], v254 offset:0x1200
	ds_read_b64_tr_b16 v[212:213], v254 offset:0x1a00
	ds_read_b64_tr_b16 v[214:215], v254 offset:0x400
	ds_read_b64_tr_b16 v[216:217], v254 offset:0xc00
	ds_read_b64_tr_b16 v[218:219], v254 offset:0x1400
	ds_read_b64_tr_b16 v[220:221], v254 offset:0x1c00
	ds_read_b64_tr_b16 v[222:223], v254 offset:0x600
	ds_read_b64_tr_b16 v[224:225], v254 offset:0xe00
	ds_read_b64_tr_b16 v[226:227], v254 offset:0x1600
	ds_read_b64_tr_b16 v[228:229], v254 offset:0x1e00
	s_setprio 2
	v_exp_f32_e32 v64, v64
	v_exp_f32_e32 v65, v65
	v_exp_f32_e32 v66, v66
	v_exp_f32_e32 v67, v67
	v_exp_f32_e32 v68, v68
	v_exp_f32_e32 v69, v69
	v_exp_f32_e32 v70, v70
	v_exp_f32_e32 v71, v71
	v_exp_f32_e32 v72, v72
	v_exp_f32_e32 v73, v73
	v_exp_f32_e32 v74, v74
	v_exp_f32_e32 v75, v75
	v_exp_f32_e32 v76, v76
	v_exp_f32_e32 v77, v77
	v_exp_f32_e32 v78, v78
	v_exp_f32_e32 v79, v79
	v_add_f32_e32 v230, v65, v64
	v_add_f32_e32 v230, v66, v230
	v_add_f32_e32 v230, v67, v230
	v_add_f32_e32 v230, v68, v230
	v_add_f32_e32 v230, v69, v230
	v_add_f32_e32 v230, v70, v230
	v_add_f32_e32 v230, v71, v230
	v_add_f32_e32 v230, v72, v230
	v_add_f32_e32 v230, v73, v230
	v_add_f32_e32 v230, v74, v230
	v_add_f32_e32 v230, v75, v230
	v_add_f32_e32 v230, v76, v230
	v_add_f32_e32 v230, v77, v230
	v_add_f32_e32 v230, v78, v230
	v_add_f32_e32 v230, v79, v230
	v_add_f32_e32 v173, v173, v230
	v_cvt_pk_bf16_f32 v64, v64, v65
	v_cvt_pk_bf16_f32 v65, v66, v67
	v_cvt_pk_bf16_f32 v66, v68, v69
	v_cvt_pk_bf16_f32 v67, v70, v71
	v_cvt_pk_bf16_f32 v68, v72, v73
	v_cvt_pk_bf16_f32 v69, v74, v75
	v_cvt_pk_bf16_f32 v70, v76, v77
	v_cvt_pk_bf16_f32 v71, v78, v79
	s_nop 0
	v_permlane32_swap_b32_e32 v64, v66
	v_permlane32_swap_b32_e32 v65, v67
	v_permlane32_swap_b32_e32 v68, v70
	v_permlane32_swap_b32_e32 v69, v71
	s_waitcnt lgkmcnt(0)
	v_add_u32_e32 v72, v246, v151
	v_add_u32_e32 v73, v246, v149
	v_add_u32_e32 v74, v246, v148
	v_add_u32_e32 v75, v246, v147
	ds_read_b128 v[230:233], v74 offset:12416
	ds_read_b128 v[234:237], v75 offset:12416
	ds_read_b128 v[238:241], v72 offset:12544
	ds_read_b128 v[242:245], v73 offset:12544
	ds_read_b128 v[246:249], v74 offset:12544
	ds_read_b128 v[250:253], v75 offset:12544
	s_setprio 1
	v_mfma_f32_32x32x16_bf16 v[48:63], v[64:67], v[198:201], v[48:63]
	v_mfma_f32_32x32x16_bf16 v[32:47], v[64:67], v[206:209], v[32:47]
	v_mfma_f32_32x32x16_bf16 v[16:31], v[64:67], v[214:217], v[16:31]
	v_mfma_f32_32x32x16_bf16 v[0:15], v[64:67], v[222:225], v[0:15]
	v_mfma_f32_32x32x16_bf16 v[48:63], v[68:71], v[202:205], v[48:63]
	v_mfma_f32_32x32x16_bf16 v[32:47], v[68:71], v[210:213], v[32:47]
	v_mfma_f32_32x32x16_bf16 v[16:31], v[68:71], v[218:221], v[16:31]
	v_mfma_f32_32x32x16_bf16 v[0:15], v[68:71], v[226:229], v[0:15]
	s_waitcnt lgkmcnt(0)
; #define SBAR() __builtin_amdgcn_sched_barrier(0)
; #define ATT_DMA_K(t) do { const bf16_t* kg_ = Kh + (size_t)(t) * 64 * LDK; LAS unsigned char* sb_ = lds + ((t) & 3) * KBUF; \
;     _Pragma("unroll") for (int i_ = 0; i_ < NKP; ++i_) __builtin_amdgcn_global_load_lds((const unsigned*)(kg_ + kgo[i_]), (LAS unsigned*)(sb_ + (wid + 8 * i_) * 1024), 16, 0, 0); } while (0)
; #define ATT_DMA_V(t, vs) do { const bf16_t* vg_ = Vh + (size_t)(t) * 64 * LDV; LAS unsigned char* sb_ = lds + V_OFF + (vs) * SHM_V; \
;     _Pragma("unroll") for (int i_ = 0; i_ < 2; ++i_) __builtin_amdgcn_global_load_lds((const unsigned*)(vg_ + vgo[i_]), (LAS unsigned*)(sb_ + (2 * wid + i_) * 1024), 16, 0, 0); } while (0)
; #define ATT_SEG(t) do { if constexpr (MODE != 0) { if (((t) == tL && tL > 0) || (t) == tR) { const float f_ = (t) == tR ? fR : fL; l_reg *= f_; \
;     _Pragma("unroll") for (int d = 0; d < 4; ++d) _Pragma("unroll") for (int r = 0; r < 16; ++r) o[d][r] *= f_; } } } while (0)
; #define ATT_TOP(N) do { asm volatile("s_waitcnt vmcnt(%0)" :: "n"(N) : "memory"); __builtin_amdgcn_s_barrier(); asm volatile("" ::: "memory"); } while (0)
; template <int DQK, int MODE, int LDQ, int LDK, int LDV> ...
;     ...
;     for (int j = 0; j < NT; ++j) {
;         if (j + 2 < NT) ATT_TOP(NKP + 2); else ATT_TOP(0);
;         if (j + 3 < NT) ATT_DMA_K(j + 3);
;         if (j + 2 < NT) ATT_DMA_V(j + 2, v2);
;         ATT_SEG(j); SBAR();
;         ATT_STEP(pA, pB, 0, v0, true, 1, j);
;         ATT_STEP(pB, pA, 1, v0, (j + 1 < NT), 0, j + 1);
	v_mfma_f32_32x32x16_bf16 v[64:79], v[174:177], v[80:83], 0
	v_mfma_f32_32x32x16_bf16 v[64:79], v[178:181], v[84:87], v[64:79]
	v_mfma_f32_32x32x16_bf16 v[64:79], v[182:185], v[88:91], v[64:79]
	v_mfma_f32_32x32x16_bf16 v[64:79], v[186:189], v[92:95], v[64:79]
	v_mfma_f32_32x32x16_bf16 v[64:79], v[190:193], v[96:99], v[64:79]
	v_mfma_f32_32x32x16_bf16 v[64:79], v[194:197], v[100:103], v[64:79]
	v_mfma_f32_32x32x16_bf16 v[64:79], v[230:233], v[104:107], v[64:79]
	v_mfma_f32_32x32x16_bf16 v[64:79], v[234:237], v[108:111], v[64:79]
	v_mfma_f32_32x32x16_bf16 v[64:79], v[238:241], v[112:115], v[64:79]
	v_mfma_f32_32x32x16_bf16 v[64:79], v[242:245], v[116:119], v[64:79]
	v_mfma_f32_32x32x16_bf16 v[64:79], v[246:249], v[120:123], v[64:79]
	v_mfma_f32_32x32x16_bf16 v[64:79], v[250:253], v[124:127], v[64:79]
	s_setprio 0
	s_add_i32 s4, s43, -2
	s_and_b32 s4, s4, 3
	s_mulk_i32 s4, 0x6000
	v_add_u32_e32 v246, s4, v158
	v_add_u32_e32 v174, v246, v151
	v_add_u32_e32 v178, v246, v149
	v_add_u32_e32 v182, v246, v148
	v_add_u32_e32 v186, v246, v147
	ds_read_b128 v[190:193], v174 offset:128
	ds_read_b128 v[194:197], v178 offset:128
	ds_read_b128 v[174:177], v174
	ds_read_b128 v[178:181], v178
	ds_read_b128 v[182:185], v182
	ds_read_b128 v[186:189], v186
	ds_read_b64_tr_b16 v[198:199], v254 offset:0x2000
	ds_read_b64_tr_b16 v[200:201], v254 offset:0x2800
	ds_read_b64_tr_b16 v[202:203], v254 offset:0x3000
	ds_read_b64_tr_b16 v[204:205], v254 offset:0x3800
	ds_read_b64_tr_b16 v[206:207], v254 offset:0x2200
	ds_read_b64_tr_b16 v[208:209], v254 offset:0x2a00
	ds_read_b64_tr_b16 v[210:211], v254 offset:0x3200
	ds_read_b64_tr_b16 v[212:213], v254 offset:0x3a00
	ds_read_b64_tr_b16 v[214:215], v254 offset:0x2400
	ds_read_b64_tr_b16 v[216:217], v254 offset:0x2c00
	ds_read_b64_tr_b16 v[218:219], v254 offset:0x3400
	ds_read_b64_tr_b16 v[220:221], v254 offset:0x3c00
	ds_read_b64_tr_b16 v[222:223], v254 offset:0x2600
	ds_read_b64_tr_b16 v[224:225], v254 offset:0x2e00
	ds_read_b64_tr_b16 v[226:227], v254 offset:0x3600
	ds_read_b64_tr_b16 v[228:229], v254 offset:0x3e00
	s_setprio 2
	v_exp_f32_e32 v64, v64
	v_exp_f32_e32 v65, v65
	v_exp_f32_e32 v66, v66
	v_exp_f32_e32 v67, v67
	v_exp_f32_e32 v68, v68
	v_exp_f32_e32 v69, v69
	v_exp_f32_e32 v70, v70
	v_exp_f32_e32 v71, v71
	v_exp_f32_e32 v72, v72
	v_exp_f32_e32 v73, v73
	v_exp_f32_e32 v74, v74
	v_exp_f32_e32 v75, v75
	v_exp_f32_e32 v76, v76
	v_exp_f32_e32 v77, v77
	v_exp_f32_e32 v78, v78
	v_exp_f32_e32 v79, v79
	v_add_f32_e32 v230, v65, v64
	v_add_f32_e32 v230, v66, v230
	v_add_f32_e32 v230, v67, v230
	v_add_f32_e32 v230, v68, v230
	v_add_f32_e32 v230, v69, v230
	v_add_f32_e32 v230, v70, v230
	v_add_f32_e32 v230, v71, v230
	v_add_f32_e32 v230, v72, v230
	v_add_f32_e32 v230, v73, v230
	v_add_f32_e32 v230, v74, v230
	v_add_f32_e32 v230, v75, v230
	v_add_f32_e32 v230, v76, v230
	v_add_f32_e32 v230, v77, v230
	v_add_f32_e32 v230, v78, v230
	v_add_f32_e32 v230, v79, v230
	v_add_f32_e32 v173, v173, v230
	v_cvt_pk_bf16_f32 v64, v64, v65
	v_cvt_pk_bf16_f32 v65, v66, v67
	v_cvt_pk_bf16_f32 v66, v68, v69
	v_cvt_pk_bf16_f32 v67, v70, v71
	v_cvt_pk_bf16_f32 v68, v72, v73
	v_cvt_pk_bf16_f32 v69, v74, v75
	v_cvt_pk_bf16_f32 v70, v76, v77
	v_cvt_pk_bf16_f32 v71, v78, v79
	s_nop 0
	v_permlane32_swap_b32_e32 v64, v66
	v_permlane32_swap_b32_e32 v65, v67
	v_permlane32_swap_b32_e32 v68, v70
	v_permlane32_swap_b32_e32 v69, v71
	s_waitcnt lgkmcnt(0)
	v_add_u32_e32 v72, v246, v151
	v_add_u32_e32 v73, v246, v149
	v_add_u32_e32 v74, v246, v148
	v_add_u32_e32 v75, v246, v147
	ds_read_b128 v[230:233], v74 offset:128
	ds_read_b128 v[234:237], v75 offset:128
	ds_read_b128 v[238:241], v72 offset:256
	ds_read_b128 v[242:245], v73 offset:256
	ds_read_b128 v[246:249], v74 offset:256
	ds_read_b128 v[250:253], v75 offset:256
	s_setprio 1
	s_cmp_lt_u32 s33, 0x100
	s_cbranch_scc1 .Lstg_mla_mid_3
	s_waitcnt vmcnt(5)
	s_barrier

; #define SBAR() __builtin_amdgcn_sched_barrier(0)
; #define ATT_DMA_K(t) do { const bf16_t* kg_ = Kh + (size_t)(t) * 64 * LDK; LAS unsigned char* sb_ = lds + ((t) & 3) * KBUF; \
;     _Pragma("unroll") for (int i_ = 0; i_ < NKP; ++i_) __builtin_amdgcn_global_load_lds((const unsigned*)(kg_ + kgo[i_]), (LAS unsigned*)(sb_ + (wid + 8 * i_) * 1024), 16, 0, 0); } while (0)
; #define ATT_DMA_V(t, vs) do { const bf16_t* vg_ = Vh + (size_t)(t) * 64 * LDV; LAS unsigned char* sb_ = lds + V_OFF + (vs) * SHM_V; \
;     _Pragma("unroll") for (int i_ = 0; i_ < 2; ++i_) __builtin_amdgcn_global_load_lds((const unsigned*)(vg_ + vgo[i_]), (LAS unsigned*)(sb_ + (2 * wid + i_) * 1024), 16, 0, 0); } while (0)
; #define ATT_SEG(t) do { if constexpr (MODE != 0) { if (((t) == tL && tL > 0) || (t) == tR) { const float f_ = (t) == tR ? fR : fL; l_reg *= f_; \
;     _Pragma("unroll") for (int d = 0; d < 4; ++d) _Pragma("unroll") for (int r = 0; r < 16; ++r) o[d][r] *= f_; } } } while (0)
; #define ATT_TOP(N) do { asm volatile("s_waitcnt vmcnt(%0)" :: "n"(N) : "memory"); __builtin_amdgcn_s_barrier(); asm volatile("" ::: "memory"); } while (0)
; template <int DQK, int MODE, int LDQ, int LDK, int LDV> ...
;     ...
;     for (int j = 0; j < NT; ++j) {
;         if (j + 2 < NT) ATT_TOP(NKP + 2); else ATT_TOP(0);
;         if (j + 3 < NT) ATT_DMA_K(j + 3);
;         if (j + 2 < NT) ATT_DMA_V(j + 2, v2);
;         ATT_SEG(j); SBAR();
;         ATT_STEP(pA, pB, 0, v0, true, 1, j);
;         ATT_STEP(pB, pA, 1, v0, (j + 1 < NT), 0, j + 1);
.Lstg_mla_t61_4:
	s_setprio 0
	v_lshl_add_u64 v[132:133], v[132:133], 1, s[0:1]
	s_mov_b32 m0, s6
	v_lshl_add_u64 v[134:135], v[134:135], 1, s[0:1]
	global_load_lds_dwordx4 v[132:133], off
	s_mov_b32 m0, s7
	s_nop 0
	global_load_lds_dwordx4 v[134:135], off
	ds_read_b128 v[132:135], v161 offset:36864
	ds_read_b128 v[136:139], v162 offset:36864
	ds_read_b128 v[140:143], v163 offset:36864
	ds_read_b128 v[174:177], v164 offset:36864
	ds_read_b128 v[178:181], v165 offset:36864
	ds_read_b128 v[182:185], v166 offset:36864
	v_lshl_add_u32 v144, s5, 14, v130
	ds_read_b64_tr_b16 v[186:187], v144 offset:0
	ds_read_b64_tr_b16 v[188:189], v144 offset:0x800
	ds_read_b64_tr_b16 v[190:191], v144 offset:0x1000
	ds_read_b64_tr_b16 v[192:193], v144 offset:0x1800
	ds_read_b64_tr_b16 v[194:195], v144 offset:0x200
	ds_read_b64_tr_b16 v[196:197], v144 offset:0xa00
	ds_read_b64_tr_b16 v[198:199], v144 offset:0x1200
	ds_read_b64_tr_b16 v[200:201], v144 offset:0x1a00
	ds_read_b64_tr_b16 v[202:203], v144 offset:0x400
	ds_read_b64_tr_b16 v[204:205], v144 offset:0xc00
	ds_read_b64_tr_b16 v[206:207], v144 offset:0x1400
	ds_read_b64_tr_b16 v[208:209], v144 offset:0x1c00
	ds_read_b64_tr_b16 v[210:211], v144 offset:0x600
	ds_read_b64_tr_b16 v[212:213], v144 offset:0xe00
	ds_read_b64_tr_b16 v[214:215], v144 offset:0x1600
	ds_read_b64_tr_b16 v[216:217], v144 offset:0x1e00
	s_setprio 2
	v_exp_f32_e32 v64, v64
	v_exp_f32_e32 v65, v65
	v_exp_f32_e32 v66, v66
	v_exp_f32_e32 v67, v67
	v_exp_f32_e32 v68, v68
	v_exp_f32_e32 v69, v69
	v_exp_f32_e32 v70, v70
	v_exp_f32_e32 v71, v71
	v_exp_f32_e32 v72, v72
	v_exp_f32_e32 v73, v73
	v_exp_f32_e32 v74, v74
	v_exp_f32_e32 v75, v75
	v_exp_f32_e32 v76, v76
	v_exp_f32_e32 v77, v77
	v_exp_f32_e32 v78, v78
	v_exp_f32_e32 v79, v79
	v_add_f32_e32 v145, v65, v64
	v_add_f32_e32 v145, v66, v145
	v_add_f32_e32 v145, v67, v145
	v_add_f32_e32 v145, v68, v145
	v_add_f32_e32 v145, v69, v145
	v_add_f32_e32 v145, v70, v145
	v_add_f32_e32 v145, v71, v145
	v_add_f32_e32 v145, v72, v145
	v_add_f32_e32 v145, v73, v145
	v_add_f32_e32 v145, v74, v145
	v_add_f32_e32 v145, v75, v145
	v_add_f32_e32 v145, v76, v145
	v_add_f32_e32 v145, v77, v145
	v_add_f32_e32 v145, v78, v145
	v_add_f32_e32 v145, v79, v145
	v_add_f32_e32 v145, v173, v145
	v_cvt_pk_bf16_f32 v64, v64, v65
	v_cvt_pk_bf16_f32 v65, v66, v67
	v_cvt_pk_bf16_f32 v66, v68, v69
	v_cvt_pk_bf16_f32 v67, v70, v71
	v_cvt_pk_bf16_f32 v68, v72, v73
	v_cvt_pk_bf16_f32 v69, v74, v75
	v_cvt_pk_bf16_f32 v70, v76, v77
	v_cvt_pk_bf16_f32 v71, v78, v79
	s_nop 0
	v_permlane32_swap_b32_e32 v64, v66
	v_permlane32_swap_b32_e32 v65, v67
	v_permlane32_swap_b32_e32 v68, v70
	v_permlane32_swap_b32_e32 v69, v71
	s_waitcnt lgkmcnt(0)
	ds_read_b128 v[218:221], v167 offset:36864
	ds_read_b128 v[222:225], v168 offset:36864
	ds_read_b128 v[226:229], v169 offset:36864
	ds_read_b128 v[230:233], v170 offset:36864
	ds_read_b128 v[234:237], v171 offset:36864
	ds_read_b128 v[238:241], v172 offset:36864
	s_setprio 1
	v_mfma_f32_32x32x16_bf16 v[48:63], v[64:67], v[186:189], v[48:63]
	v_mfma_f32_32x32x16_bf16 v[32:47], v[64:67], v[194:197], v[32:47]
	v_mfma_f32_32x32x16_bf16 v[16:31], v[64:67], v[202:205], v[16:31]
	v_mfma_f32_32x32x16_bf16 v[0:15], v[64:67], v[210:213], v[0:15]
	v_mfma_f32_32x32x16_bf16 v[48:63], v[68:71], v[190:193], v[48:63]
	v_mfma_f32_32x32x16_bf16 v[32:47], v[68:71], v[198:201], v[32:47]
	v_mfma_f32_32x32x16_bf16 v[16:31], v[68:71], v[206:209], v[16:31]
	v_mfma_f32_32x32x16_bf16 v[0:15], v[68:71], v[214:217], v[0:15]
	s_waitcnt lgkmcnt(0)
; #define SBAR() __builtin_amdgcn_sched_barrier(0)
; #define ATT_DMA_K(t) do { const bf16_t* kg_ = Kh + (size_t)(t) * 64 * LDK; LAS unsigned char* sb_ = lds + ((t) & 3) * KBUF; \
;     _Pragma("unroll") for (int i_ = 0; i_ < NKP; ++i_) __builtin_amdgcn_global_load_lds((const unsigned*)(kg_ + kgo[i_]), (LAS unsigned*)(sb_ + (wid + 8 * i_) * 1024), 16, 0, 0); } while (0)
; #define ATT_DMA_V(t, vs) do { const bf16_t* vg_ = Vh + (size_t)(t) * 64 * LDV; LAS unsigned char* sb_ = lds + V_OFF + (vs) * SHM_V; \
;     _Pragma("unroll") for (int i_ = 0; i_ < 2; ++i_) __builtin_amdgcn_global_load_lds((const unsigned*)(vg_ + vgo[i_]), (LAS unsigned*)(sb_ + (2 * wid + i_) * 1024), 16, 0, 0); } while (0)
; #define ATT_SEG(t) do { if constexpr (MODE != 0) { if (((t) == tL && tL > 0) || (t) == tR) { const float f_ = (t) == tR ? fR : fL; l_reg *= f_; \
;     _Pragma("unroll") for (int d = 0; d < 4; ++d) _Pragma("unroll") for (int r = 0; r < 16; ++r) o[d][r] *= f_; } } } while (0)
; #define ATT_TOP(N) do { asm volatile("s_waitcnt vmcnt(%0)" :: "n"(N) : "memory"); __builtin_amdgcn_s_barrier(); asm volatile("" ::: "memory"); } while (0)
; template <int DQK, int MODE, int LDQ, int LDK, int LDV> ...
;     ...
;     for (int j = 0; j < NT; ++j) {
;         if (j + 2 < NT) ATT_TOP(NKP + 2); else ATT_TOP(0);
;         if (j + 3 < NT) ATT_DMA_K(j + 3);
;         if (j + 2 < NT) ATT_DMA_V(j + 2, v2);
;         ATT_SEG(j); SBAR();
;         ATT_STEP(pA, pB, 0, v0, true, 1, j);
;         ATT_STEP(pB, pA, 1, v0, (j + 1 < NT), 0, j + 1);
	v_mfma_f32_32x32x16_bf16 v[64:79], v[132:135], v[80:83], 0
	v_mfma_f32_32x32x16_bf16 v[64:79], v[136:139], v[84:87], v[64:79]
	v_mfma_f32_32x32x16_bf16 v[64:79], v[140:143], v[88:91], v[64:79]
	v_mfma_f32_32x32x16_bf16 v[64:79], v[174:177], v[92:95], v[64:79]
	v_mfma_f32_32x32x16_bf16 v[64:79], v[178:181], v[96:99], v[64:79]
	v_mfma_f32_32x32x16_bf16 v[64:79], v[182:185], v[100:103], v[64:79]
	s_waitcnt lgkmcnt(0)
	v_mfma_f32_32x32x16_bf16 v[64:79], v[218:221], v[104:107], v[64:79]
	v_mfma_f32_32x32x16_bf16 v[64:79], v[222:225], v[108:111], v[64:79]
	v_mfma_f32_32x32x16_bf16 v[64:79], v[226:229], v[112:115], v[64:79]
	v_mfma_f32_32x32x16_bf16 v[64:79], v[230:233], v[116:119], v[64:79]
	v_mfma_f32_32x32x16_bf16 v[64:79], v[234:237], v[120:123], v[64:79]
	v_mfma_f32_32x32x16_bf16 v[64:79], v[238:241], v[124:127], v[64:79]
	s_setprio 0
	ds_read_b128 v[132:135], v161 offset:49152
	ds_read_b128 v[136:139], v162 offset:49152
	ds_read_b128 v[140:143], v163 offset:49152
	ds_read_b128 v[174:177], v164 offset:49152
	ds_read_b128 v[178:181], v165 offset:49152
	ds_read_b128 v[182:185], v166 offset:49152
	ds_read_b64_tr_b16 v[186:187], v144 offset:0x2000
	ds_read_b64_tr_b16 v[188:189], v144 offset:0x2800
	ds_read_b64_tr_b16 v[190:191], v144 offset:0x3000
	ds_read_b64_tr_b16 v[192:193], v144 offset:0x3800
	ds_read_b64_tr_b16 v[194:195], v144 offset:0x2200
	ds_read_b64_tr_b16 v[196:197], v144 offset:0x2a00
	ds_read_b64_tr_b16 v[198:199], v144 offset:0x3200
	ds_read_b64_tr_b16 v[200:201], v144 offset:0x3a00
	ds_read_b64_tr_b16 v[202:203], v144 offset:0x2400
	ds_read_b64_tr_b16 v[204:205], v144 offset:0x2c00
	ds_read_b64_tr_b16 v[206:207], v144 offset:0x3400
	ds_read_b64_tr_b16 v[208:209], v144 offset:0x3c00
	ds_read_b64_tr_b16 v[210:211], v144 offset:0x2600
	ds_read_b64_tr_b16 v[212:213], v144 offset:0x2e00
	ds_read_b64_tr_b16 v[214:215], v144 offset:0x3600
	ds_read_b64_tr_b16 v[216:217], v144 offset:0x3e00
	s_nop 5
	s_setprio 2
	v_exp_f32_e32 v64, v64
	v_exp_f32_e32 v65, v65
	v_exp_f32_e32 v66, v66
	v_exp_f32_e32 v67, v67
	v_exp_f32_e32 v68, v68
	v_exp_f32_e32 v69, v69
	v_exp_f32_e32 v70, v70
	v_exp_f32_e32 v71, v71
	v_exp_f32_e32 v72, v72
	v_exp_f32_e32 v73, v73
	v_exp_f32_e32 v74, v74
	v_exp_f32_e32 v75, v75
	v_exp_f32_e32 v76, v76
	v_exp_f32_e32 v77, v77
	v_exp_f32_e32 v78, v78
	v_exp_f32_e32 v79, v79
	v_add_f32_e32 v144, v65, v64
	v_add_f32_e32 v144, v66, v144
	v_add_f32_e32 v144, v67, v144
	v_add_f32_e32 v144, v68, v144
	v_add_f32_e32 v144, v69, v144
	v_add_f32_e32 v144, v70, v144
	v_add_f32_e32 v144, v71, v144
	v_add_f32_e32 v144, v72, v144
	v_add_f32_e32 v144, v73, v144
	v_add_f32_e32 v144, v74, v144
	v_add_f32_e32 v144, v75, v144
	v_add_f32_e32 v144, v76, v144
	v_add_f32_e32 v144, v77, v144
	v_add_f32_e32 v144, v78, v144
	v_add_f32_e32 v144, v79, v144
	v_add_f32_e32 v144, v145, v144
	v_cvt_pk_bf16_f32 v64, v64, v65
	v_cvt_pk_bf16_f32 v65, v66, v67
	v_cvt_pk_bf16_f32 v66, v68, v69
	v_cvt_pk_bf16_f32 v67, v70, v71
	v_cvt_pk_bf16_f32 v68, v72, v73
	v_cvt_pk_bf16_f32 v69, v74, v75
	v_cvt_pk_bf16_f32 v70, v76, v77
	v_cvt_pk_bf16_f32 v71, v78, v79
	s_nop 0
	v_permlane32_swap_b32_e32 v64, v66
	v_permlane32_swap_b32_e32 v65, v67
	v_permlane32_swap_b32_e32 v68, v70
	v_permlane32_swap_b32_e32 v69, v71
	s_waitcnt lgkmcnt(0)
	ds_read_b128 v[218:221], v167 offset:49152
	ds_read_b128 v[222:225], v168 offset:49152
	ds_read_b128 v[226:229], v169 offset:49152
	ds_read_b128 v[230:233], v170 offset:49152
	ds_read_b128 v[234:237], v171 offset:49152
	ds_read_b128 v[238:241], v172 offset:49152
	s_setprio 1
	s_cmp_lt_u32 s33, 0x100
	s_cbranch_scc1 .Lstg_mla_m61_5
	s_waitcnt vmcnt(0)
	s_barrier

; #define SBAR() __builtin_amdgcn_sched_barrier(0)
; #define ATT_DMA_K(t) do { const bf16_t* kg_ = Kh + (size_t)(t) * 64 * LDK; LAS unsigned char* sb_ = lds + ((t) & 3) * KBUF; \
;     _Pragma("unroll") for (int i_ = 0; i_ < NKP; ++i_) __builtin_amdgcn_global_load_lds((const unsigned*)(kg_ + kgo[i_]), (LAS unsigned*)(sb_ + (wid + 8 * i_) * 1024), 16, 0, 0); } while (0)
; #define ATT_DMA_V(t, vs) do { const bf16_t* vg_ = Vh + (size_t)(t) * 64 * LDV; LAS unsigned char* sb_ = lds + V_OFF + (vs) * SHM_V; \
;     _Pragma("unroll") for (int i_ = 0; i_ < 2; ++i_) __builtin_amdgcn_global_load_lds((const unsigned*)(vg_ + vgo[i_]), (LAS unsigned*)(sb_ + (2 * wid + i_) * 1024), 16, 0, 0); } while (0)
; #define ATT_SEG(t) do { if constexpr (MODE != 0) { if (((t) == tL && tL > 0) || (t) == tR) { const float f_ = (t) == tR ? fR : fL; l_reg *= f_; \
;     _Pragma("unroll") for (int d = 0; d < 4; ++d) _Pragma("unroll") for (int r = 0; r < 16; ++r) o[d][r] *= f_; } } } while (0)
; #define ATT_TOP(N) do { asm volatile("s_waitcnt vmcnt(%0)" :: "n"(N) : "memory"); __builtin_amdgcn_s_barrier(); asm volatile("" ::: "memory"); } while (0)
; template <int DQK, int MODE, int LDQ, int LDK, int LDV> ...
;     ...
;     for (int j = 0; j < NT; ++j) {
;         if (j + 2 < NT) ATT_TOP(NKP + 2); else ATT_TOP(0);
;         if (j + 3 < NT) ATT_DMA_K(j + 3);
;         if (j + 2 < NT) ATT_DMA_V(j + 2, v2);
;         ATT_SEG(j); SBAR();
;         ATT_STEP(pA, pB, 0, v0, true, 1, j);
;         ATT_STEP(pB, pA, 1, v0, (j + 1 < NT), 0, j + 1);
.Lstg_mla_t62_6:
	s_setprio 0
	ds_read_b128 v[132:135], v161 offset:61440
	ds_read_b128 v[136:139], v162 offset:61440
	ds_read_b128 v[140:143], v163 offset:61440
	ds_read_b128 v[174:177], v164 offset:61440
	ds_read_b128 v[162:165], v165 offset:61440
	ds_read_b128 v[178:181], v166 offset:61440
	v_add_u32_e32 v145, 0x8000, v130
	ds_read_b64_tr_b16 v[182:183], v145 offset:0
	ds_read_b64_tr_b16 v[184:185], v145 offset:0x800
	ds_read_b64_tr_b16 v[186:187], v145 offset:0x1000
	ds_read_b64_tr_b16 v[188:189], v145 offset:0x1800
	ds_read_b64_tr_b16 v[190:191], v145 offset:0x200
	ds_read_b64_tr_b16 v[192:193], v145 offset:0xa00
	ds_read_b64_tr_b16 v[194:195], v145 offset:0x1200
	ds_read_b64_tr_b16 v[196:197], v145 offset:0x1a00
	ds_read_b64_tr_b16 v[198:199], v145 offset:0x400
	ds_read_b64_tr_b16 v[200:201], v145 offset:0xc00
	ds_read_b64_tr_b16 v[202:203], v145 offset:0x1400
	ds_read_b64_tr_b16 v[204:205], v145 offset:0x1c00
	ds_read_b64_tr_b16 v[206:207], v145 offset:0x600
	ds_read_b64_tr_b16 v[208:209], v145 offset:0xe00
	ds_read_b64_tr_b16 v[210:211], v145 offset:0x1600
	ds_read_b64_tr_b16 v[212:213], v145 offset:0x1e00
	s_nop 3
	s_setprio 2
	v_exp_f32_e32 v64, v64
	v_exp_f32_e32 v65, v65
	v_exp_f32_e32 v66, v66
	v_exp_f32_e32 v67, v67
	v_exp_f32_e32 v68, v68
	v_exp_f32_e32 v69, v69
	v_exp_f32_e32 v70, v70
	v_exp_f32_e32 v71, v71
	v_exp_f32_e32 v72, v72
	v_exp_f32_e32 v73, v73
	v_exp_f32_e32 v74, v74
	v_exp_f32_e32 v75, v75
	v_exp_f32_e32 v76, v76
	v_exp_f32_e32 v77, v77
	v_exp_f32_e32 v78, v78
	v_exp_f32_e32 v79, v79
	v_add_f32_e32 v161, v65, v64
	v_add_f32_e32 v161, v66, v161
	v_add_f32_e32 v161, v67, v161
	v_add_f32_e32 v161, v68, v161
	v_add_f32_e32 v161, v69, v161
	v_add_f32_e32 v161, v70, v161
	v_add_f32_e32 v161, v71, v161
	v_add_f32_e32 v161, v72, v161
	v_add_f32_e32 v161, v73, v161
	v_add_f32_e32 v161, v74, v161
	v_add_f32_e32 v161, v75, v161
	v_add_f32_e32 v161, v76, v161
	v_add_f32_e32 v161, v77, v161
	v_add_f32_e32 v161, v78, v161
	v_add_f32_e32 v161, v79, v161
	v_add_f32_e32 v144, v144, v161
	v_cvt_pk_bf16_f32 v64, v64, v65
	v_cvt_pk_bf16_f32 v65, v66, v67
	v_cvt_pk_bf16_f32 v66, v68, v69
	v_cvt_pk_bf16_f32 v67, v70, v71
	v_cvt_pk_bf16_f32 v68, v72, v73
	v_cvt_pk_bf16_f32 v69, v74, v75
	v_cvt_pk_bf16_f32 v70, v76, v77
	v_cvt_pk_bf16_f32 v71, v78, v79
	s_nop 0
	v_permlane32_swap_b32_e32 v64, v66
	v_permlane32_swap_b32_e32 v65, v67
	v_permlane32_swap_b32_e32 v68, v70
	v_permlane32_swap_b32_e32 v69, v71
	s_waitcnt lgkmcnt(0)
	ds_read_b128 v[214:217], v167 offset:61440
	ds_read_b128 v[218:221], v168 offset:61440
	ds_read_b128 v[166:169], v169 offset:61440
	ds_read_b128 v[222:225], v170 offset:61440
	ds_read_b128 v[226:229], v171 offset:61440
	ds_read_b128 v[170:173], v172 offset:61440
	s_setprio 1
	v_mfma_f32_32x32x16_bf16 v[48:63], v[64:67], v[182:185], v[48:63]
	v_mfma_f32_32x32x16_bf16 v[32:47], v[64:67], v[190:193], v[32:47]
	v_mfma_f32_32x32x16_bf16 v[16:31], v[64:67], v[198:201], v[16:31]
	v_mfma_f32_32x32x16_bf16 v[0:15], v[64:67], v[206:209], v[0:15]
	v_mfma_f32_32x32x16_bf16 v[48:63], v[68:71], v[186:189], v[48:63]
	v_mfma_f32_32x32x16_bf16 v[32:47], v[68:71], v[194:197], v[32:47]
	v_mfma_f32_32x32x16_bf16 v[16:31], v[68:71], v[202:205], v[16:31]
	v_mfma_f32_32x32x16_bf16 v[0:15], v[68:71], v[210:213], v[0:15]
	s_waitcnt lgkmcnt(0)
	v_mfma_f32_32x32x16_bf16 v[64:79], v[132:135], v[80:83], 0
	v_mfma_f32_32x32x16_bf16 v[64:79], v[136:139], v[84:87], v[64:79]
	v_mfma_f32_32x32x16_bf16 v[64:79], v[140:143], v[88:91], v[64:79]
	v_mfma_f32_32x32x16_bf16 v[64:79], v[174:177], v[92:95], v[64:79]
	v_mfma_f32_32x32x16_bf16 v[64:79], v[162:165], v[96:99], v[64:79]
	v_mfma_f32_32x32x16_bf16 v[64:79], v[178:181], v[100:103], v[64:79]
	s_waitcnt lgkmcnt(0)
; #define SBAR() __builtin_amdgcn_sched_barrier(0)
; #define ATT_DMA_K(t) do { const bf16_t* kg_ = Kh + (size_t)(t) * 64 * LDK; LAS unsigned char* sb_ = lds + ((t) & 3) * KBUF; \
;     _Pragma("unroll") for (int i_ = 0; i_ < NKP; ++i_) __builtin_amdgcn_global_load_lds((const unsigned*)(kg_ + kgo[i_]), (LAS unsigned*)(sb_ + (wid + 8 * i_) * 1024), 16, 0, 0); } while (0)
; #define ATT_DMA_V(t, vs) do { const bf16_t* vg_ = Vh + (size_t)(t) * 64 * LDV; LAS unsigned char* sb_ = lds + V_OFF + (vs) * SHM_V; \
;     _Pragma("unroll") for (int i_ = 0; i_ < 2; ++i_) __builtin_amdgcn_global_load_lds((const unsigned*)(vg_ + vgo[i_]), (LAS unsigned*)(sb_ + (2 * wid + i_) * 1024), 16, 0, 0); } while (0)
; #define ATT_SEG(t) do { if constexpr (MODE != 0) { if (((t) == tL && tL > 0) || (t) == tR) { const float f_ = (t) == tR ? fR : fL; l_reg *= f_; \
;     _Pragma("unroll") for (int d = 0; d < 4; ++d) _Pragma("unroll") for (int r = 0; r < 16; ++r) o[d][r] *= f_; } } } while (0)
; #define ATT_TOP(N) do { asm volatile("s_waitcnt vmcnt(%0)" :: "n"(N) : "memory"); __builtin_amdgcn_s_barrier(); asm volatile("" ::: "memory"); } while (0)
; template <int DQK, int MODE, int LDQ, int LDK, int LDV> ...
;     ...
;     for (int j = 0; j < NT; ++j) {
;         if (j + 2 < NT) ATT_TOP(NKP + 2); else ATT_TOP(0);
;         if (j + 3 < NT) ATT_DMA_K(j + 3);
;         if (j + 2 < NT) ATT_DMA_V(j + 2, v2);
;         ATT_SEG(j); SBAR();
;         ATT_STEP(pA, pB, 0, v0, true, 1, j);
;         ATT_STEP(pB, pA, 1, v0, (j + 1 < NT), 0, j + 1);
	v_mfma_f32_32x32x16_bf16 v[64:79], v[214:217], v[104:107], v[64:79]
	v_mfma_f32_32x32x16_bf16 v[64:79], v[218:221], v[108:111], v[64:79]
	v_mfma_f32_32x32x16_bf16 v[64:79], v[166:169], v[112:115], v[64:79]
	v_mfma_f32_32x32x16_bf16 v[64:79], v[222:225], v[116:119], v[64:79]
	v_mfma_f32_32x32x16_bf16 v[64:79], v[226:229], v[120:123], v[64:79]
	v_mfma_f32_32x32x16_bf16 v[64:79], v[170:173], v[124:127], v[64:79]
	s_setprio 0
	v_add_u32_e32 v158, 0x12000, v158
	v_add_u32_e32 v132, v158, v151
	v_add_u32_e32 v136, v158, v149
	v_add_u32_e32 v140, v158, v148
	v_add_u32_e32 v161, v158, v147
	ds_read_b128 v[132:135], v132
	ds_read_b128 v[136:139], v136
	ds_read_b128 v[140:143], v140
	ds_read_b128 v[162:165], v161
	v_add_u32_e32 v161, v158, v146
	v_add_u32_e32 v170, v158, v150
	ds_read_b128 v[166:169], v161
	ds_read_b128 v[170:173], v170
	ds_read_b64_tr_b16 v[174:175], v145 offset:0x2000
	ds_read_b64_tr_b16 v[176:177], v145 offset:0x2800
	ds_read_b64_tr_b16 v[178:179], v145 offset:0x3000
	ds_read_b64_tr_b16 v[180:181], v145 offset:0x3800
	ds_read_b64_tr_b16 v[182:183], v145 offset:0x2200
	ds_read_b64_tr_b16 v[184:185], v145 offset:0x2a00
	ds_read_b64_tr_b16 v[186:187], v145 offset:0x3200
	ds_read_b64_tr_b16 v[188:189], v145 offset:0x3a00
	ds_read_b64_tr_b16 v[190:191], v145 offset:0x2400
	ds_read_b64_tr_b16 v[192:193], v145 offset:0x2c00
	ds_read_b64_tr_b16 v[194:195], v145 offset:0x3400
	ds_read_b64_tr_b16 v[196:197], v145 offset:0x3c00
	ds_read_b64_tr_b16 v[198:199], v145 offset:0x2600
	ds_read_b64_tr_b16 v[200:201], v145 offset:0x2e00
	ds_read_b64_tr_b16 v[202:203], v145 offset:0x3600
	ds_read_b64_tr_b16 v[204:205], v145 offset:0x3e00
	s_setprio 2
	v_exp_f32_e32 v64, v64
	v_exp_f32_e32 v65, v65
	v_exp_f32_e32 v66, v66
	v_exp_f32_e32 v67, v67
	v_exp_f32_e32 v68, v68
	v_exp_f32_e32 v69, v69
	v_exp_f32_e32 v70, v70
	v_exp_f32_e32 v71, v71
	v_exp_f32_e32 v72, v72
	v_exp_f32_e32 v73, v73
	v_exp_f32_e32 v74, v74
	v_exp_f32_e32 v75, v75
	v_exp_f32_e32 v76, v76
	v_exp_f32_e32 v77, v77
	v_exp_f32_e32 v78, v78
	v_exp_f32_e32 v79, v79
	v_add_f32_e32 v145, v65, v64
	v_add_f32_e32 v145, v66, v145
	v_add_f32_e32 v145, v67, v145
	v_add_f32_e32 v145, v68, v145
	v_add_f32_e32 v145, v69, v145
	v_add_f32_e32 v145, v70, v145
	v_add_f32_e32 v145, v71, v145
	v_add_f32_e32 v145, v72, v145
	v_add_f32_e32 v145, v73, v145
	v_add_f32_e32 v145, v74, v145
	v_add_f32_e32 v145, v75, v145
	v_add_f32_e32 v145, v76, v145
	v_add_f32_e32 v145, v77, v145
	v_add_f32_e32 v145, v78, v145
	v_add_f32_e32 v145, v79, v145
	v_add_f32_e32 v161, v144, v145
	v_cvt_pk_bf16_f32 v64, v64, v65
	v_cvt_pk_bf16_f32 v65, v66, v67
	v_cvt_pk_bf16_f32 v66, v68, v69
	v_cvt_pk_bf16_f32 v67, v70, v71
	v_cvt_pk_bf16_f32 v68, v72, v73
	v_cvt_pk_bf16_f32 v69, v74, v75
	v_cvt_pk_bf16_f32 v70, v76, v77
	v_cvt_pk_bf16_f32 v71, v78, v79
	s_nop 0
	v_permlane32_swap_b32_e32 v64, v66
	v_permlane32_swap_b32_e32 v65, v67
	v_permlane32_swap_b32_e32 v68, v70
	v_permlane32_swap_b32_e32 v69, v71
	s_waitcnt lgkmcnt(0)
	v_add_u32_e32 v72, v158, v152
	v_add_u32_e32 v73, v158, v153
	ds_read_b128 v[206:209], v72
	ds_read_b128 v[210:213], v73
	v_add_u32_e32 v72, v158, v154
	v_add_u32_e32 v73, v158, v155
	ds_read_b128 v[214:217], v72
	ds_read_b128 v[218:221], v73
	v_add_u32_e32 v72, v158, v156
	v_add_u32_e32 v73, v158, v157
	ds_read_b128 v[222:225], v72
	ds_read_b128 v[226:229], v73
	s_setprio 1
	s_cmp_lt_u32 s33, 0x100
	s_cbranch_scc1 .Lstg_mla_m62_7
	s_waitcnt vmcnt(0)
	s_barrier

; #define SBAR() __builtin_amdgcn_sched_barrier(0)
; #define ATT_DMA_K(t) do { const bf16_t* kg_ = Kh + (size_t)(t) * 64 * LDK; LAS unsigned char* sb_ = lds + ((t) & 3) * KBUF; \
;     _Pragma("unroll") for (int i_ = 0; i_ < NKP; ++i_) __builtin_amdgcn_global_load_lds((const unsigned*)(kg_ + kgo[i_]), (LAS unsigned*)(sb_ + (wid + 8 * i_) * 1024), 16, 0, 0); } while (0)
; #define ATT_DMA_V(t, vs) do { const bf16_t* vg_ = Vh + (size_t)(t) * 64 * LDV; LAS unsigned char* sb_ = lds + V_OFF + (vs) * SHM_V; \
;     _Pragma("unroll") for (int i_ = 0; i_ < 2; ++i_) __builtin_amdgcn_global_load_lds((const unsigned*)(vg_ + vgo[i_]), (LAS unsigned*)(sb_ + (2 * wid + i_) * 1024), 16, 0, 0); } while (0)
; #define ATT_SEG(t) do { if constexpr (MODE != 0) { if (((t) == tL && tL > 0) || (t) == tR) { const float f_ = (t) == tR ? fR : fL; l_reg *= f_; \
;     _Pragma("unroll") for (int d = 0; d < 4; ++d) _Pragma("unroll") for (int r = 0; r < 16; ++r) o[d][r] *= f_; } } } while (0)
; #define ATT_TOP(N) do { asm volatile("s_waitcnt vmcnt(%0)" :: "n"(N) : "memory"); __builtin_amdgcn_s_barrier(); asm volatile("" ::: "memory"); } while (0)
; template <int DQK, int MODE, int LDQ, int LDK, int LDV> ...
;     ...
;     for (int j = 0; j < NT; ++j) {
;         if (j + 2 < NT) ATT_TOP(NKP + 2); else ATT_TOP(0);
;         if (j + 3 < NT) ATT_DMA_K(j + 3);
;         if (j + 2 < NT) ATT_DMA_V(j + 2, v2);
;         ATT_SEG(j); SBAR();
;         ATT_STEP(pA, pB, 0, v0, true, 1, j);
;         ATT_STEP(pB, pA, 1, v0, (j + 1 < NT), 0, j + 1);
.Lstg_mla_t63_8:
	s_setprio 0
	v_add_u32_e32 v158, s82, v159
	v_add_u32_e32 v132, v158, v151
	v_add_u32_e32 v136, v158, v149
	v_add_u32_e32 v140, v158, v148
	v_add_u32_e32 v144, v158, v147
	ds_read_b128 v[132:135], v132
	ds_read_b128 v[136:139], v136
	ds_read_b128 v[140:143], v140
	ds_read_b128 v[162:165], v144
	v_add_u32_e32 v144, v158, v146
	v_add_u32_e32 v148, v158, v150
	ds_read_b128 v[144:147], v144
	ds_read_b128 v[148:151], v148
	ds_read_b64_tr_b16 v[166:167], v130 offset:0
	ds_read_b64_tr_b16 v[168:169], v130 offset:0x800
	ds_read_b64_tr_b16 v[170:171], v130 offset:0x1000
	ds_read_b64_tr_b16 v[172:173], v130 offset:0x1800
	ds_read_b64_tr_b16 v[174:175], v130 offset:0x200
	ds_read_b64_tr_b16 v[176:177], v130 offset:0xa00
	ds_read_b64_tr_b16 v[178:179], v130 offset:0x1200
	ds_read_b64_tr_b16 v[180:181], v130 offset:0x1a00
	ds_read_b64_tr_b16 v[182:183], v130 offset:0x400
	ds_read_b64_tr_b16 v[184:185], v130 offset:0xc00
	ds_read_b64_tr_b16 v[186:187], v130 offset:0x1400
	ds_read_b64_tr_b16 v[188:189], v130 offset:0x1c00
	ds_read_b64_tr_b16 v[190:191], v130 offset:0x600
	ds_read_b64_tr_b16 v[192:193], v130 offset:0xe00
	ds_read_b64_tr_b16 v[194:195], v130 offset:0x1600
	ds_read_b64_tr_b16 v[196:197], v130 offset:0x1e00
	s_setprio 2
	v_exp_f32_e32 v64, v64
	v_exp_f32_e32 v65, v65
	v_exp_f32_e32 v66, v66
	v_exp_f32_e32 v67, v67
	v_exp_f32_e32 v68, v68
	v_exp_f32_e32 v69, v69
	v_exp_f32_e32 v70, v70
	v_exp_f32_e32 v71, v71
	v_exp_f32_e32 v72, v72
	v_exp_f32_e32 v73, v73
	v_exp_f32_e32 v74, v74
	v_exp_f32_e32 v75, v75
	v_exp_f32_e32 v76, v76
	v_exp_f32_e32 v77, v77
	v_exp_f32_e32 v78, v78
	v_exp_f32_e32 v79, v79
	v_add_f32_e32 v159, v65, v64
	v_add_f32_e32 v159, v66, v159
	v_add_f32_e32 v159, v67, v159
	v_add_f32_e32 v159, v68, v159
	v_add_f32_e32 v159, v69, v159
	v_add_f32_e32 v159, v70, v159
	v_add_f32_e32 v159, v71, v159
	v_add_f32_e32 v159, v72, v159
	v_add_f32_e32 v159, v73, v159
	v_add_f32_e32 v159, v74, v159
	v_add_f32_e32 v159, v75, v159
	v_add_f32_e32 v159, v76, v159
	v_add_f32_e32 v159, v77, v159
	v_add_f32_e32 v159, v78, v159
	v_add_f32_e32 v159, v79, v159
	v_add_f32_e32 v161, v161, v159
	v_cvt_pk_bf16_f32 v64, v64, v65
	v_cvt_pk_bf16_f32 v65, v66, v67
	v_cvt_pk_bf16_f32 v66, v68, v69
	v_cvt_pk_bf16_f32 v67, v70, v71
	v_cvt_pk_bf16_f32 v68, v72, v73
	v_cvt_pk_bf16_f32 v69, v74, v75
	v_cvt_pk_bf16_f32 v70, v76, v77
	v_cvt_pk_bf16_f32 v71, v78, v79
	s_nop 0
	v_permlane32_swap_b32_e32 v64, v66
	v_permlane32_swap_b32_e32 v65, v67
	v_permlane32_swap_b32_e32 v68, v70
	v_permlane32_swap_b32_e32 v69, v71
	s_waitcnt lgkmcnt(0)
	v_add_u32_e32 v72, v158, v152
	v_add_u32_e32 v73, v158, v153
	ds_read_b128 v[198:201], v72
	ds_read_b128 v[202:205], v73
	v_add_u32_e32 v72, v158, v154
	v_add_u32_e32 v73, v158, v155
	ds_read_b128 v[152:155], v72
	ds_read_b128 v[206:209], v73
	v_add_u32_e32 v72, v158, v156
	v_add_u32_e32 v73, v158, v157
	ds_read_b128 v[156:159], v72
	ds_read_b128 v[210:213], v73
	s_setprio 1
	v_mfma_f32_32x32x16_bf16 v[48:63], v[64:67], v[166:169], v[48:63]
	v_mfma_f32_32x32x16_bf16 v[32:47], v[64:67], v[174:177], v[32:47]
	v_mfma_f32_32x32x16_bf16 v[16:31], v[64:67], v[182:185], v[16:31]
	v_mfma_f32_32x32x16_bf16 v[0:15], v[64:67], v[190:193], v[0:15]
	v_mfma_f32_32x32x16_bf16 v[48:63], v[68:71], v[170:173], v[48:63]
	v_mfma_f32_32x32x16_bf16 v[32:47], v[68:71], v[178:181], v[32:47]
	v_mfma_f32_32x32x16_bf16 v[16:31], v[68:71], v[186:189], v[16:31]
	v_mfma_f32_32x32x16_bf16 v[0:15], v[68:71], v[194:197], v[0:15]
	s_waitcnt lgkmcnt(0)
; template <int TAG = 0> DI int fresh_tid(int wv) { int l; asm volatile("v_mbcnt_lo_u32_b32 %0, -1, 0\n\tv_mbcnt_hi_u32_b32 %0, -1, %0 ; site %1" : "=v"(l) : "n"(TAG)); return wv * 64 + l; }
; DI float swap_sum(float v) { auto rr = __builtin_amdgcn_permlane32_swap(__float_as_uint(v), __float_as_uint(v), false, false); return __uint_as_float(rr[0]) + __uint_as_float(rr[1]); }
; template <int DQK, int MODE, int LDQ, int LDK, int LDV> ...
;     ...
;     l_reg = swap_sum(l_reg);
;     { const int lane2 = fresh_tid<110 + MODE>(wv) & 63, r32 = lane2 & 31, hi = lane2 >> 5;
;     if (hi == 0) li_l[r32] = l_reg;
	v_mfma_f32_32x32x16_bf16 v[64:79], v[132:135], v[80:83], 0
	v_mfma_f32_32x32x16_bf16 v[64:79], v[136:139], v[84:87], v[64:79]
	v_mfma_f32_32x32x16_bf16 v[64:79], v[140:143], v[88:91], v[64:79]
	v_mfma_f32_32x32x16_bf16 v[64:79], v[162:165], v[92:95], v[64:79]
	v_mfma_f32_32x32x16_bf16 v[64:79], v[144:147], v[96:99], v[64:79]
	v_mfma_f32_32x32x16_bf16 v[64:79], v[148:151], v[100:103], v[64:79]
	s_waitcnt lgkmcnt(0)
	v_mfma_f32_32x32x16_bf16 v[64:79], v[198:201], v[104:107], v[64:79]
	v_mfma_f32_32x32x16_bf16 v[64:79], v[202:205], v[108:111], v[64:79]
	v_mfma_f32_32x32x16_bf16 v[64:79], v[152:155], v[112:115], v[64:79]
	v_mfma_f32_32x32x16_bf16 v[64:79], v[206:209], v[116:119], v[64:79]
	v_mfma_f32_32x32x16_bf16 v[64:79], v[156:159], v[120:123], v[64:79]
	v_mfma_f32_32x32x16_bf16 v[64:79], v[210:213], v[124:127], v[64:79]
	s_setprio 0
	ds_read_b64_tr_b16 v[80:81], v130 offset:0x2000
	ds_read_b64_tr_b16 v[82:83], v130 offset:0x2800
	ds_read_b64_tr_b16 v[84:85], v130 offset:0x3000
	ds_read_b64_tr_b16 v[86:87], v130 offset:0x3800
	ds_read_b64_tr_b16 v[88:89], v130 offset:0x2200
	ds_read_b64_tr_b16 v[90:91], v130 offset:0x2a00
	ds_read_b64_tr_b16 v[92:93], v130 offset:0x3200
	ds_read_b64_tr_b16 v[94:95], v130 offset:0x3a00
	ds_read_b64_tr_b16 v[96:97], v130 offset:0x2400
	ds_read_b64_tr_b16 v[98:99], v130 offset:0x2c00
	ds_read_b64_tr_b16 v[100:101], v130 offset:0x3400
	ds_read_b64_tr_b16 v[102:103], v130 offset:0x3c00
	ds_read_b64_tr_b16 v[104:105], v130 offset:0x2600
	ds_read_b64_tr_b16 v[106:107], v130 offset:0x2e00
	ds_read_b64_tr_b16 v[108:109], v130 offset:0x3600
	ds_read_b64_tr_b16 v[110:111], v130 offset:0x3e00
	s_nop 11
	s_setprio 2
	v_exp_f32_e32 v112, v64
	v_exp_f32_e32 v65, v65
	v_exp_f32_e32 v113, v66
	v_exp_f32_e32 v67, v67
	v_exp_f32_e32 v68, v68
	v_exp_f32_e32 v69, v69
	v_exp_f32_e32 v70, v70
	v_exp_f32_e32 v71, v71
	v_exp_f32_e32 v72, v72
	v_exp_f32_e32 v73, v73
	v_exp_f32_e32 v74, v74
	v_exp_f32_e32 v75, v75
	v_exp_f32_e32 v76, v76
	v_exp_f32_e32 v77, v77
	v_exp_f32_e32 v78, v78
	v_exp_f32_e32 v79, v79
	v_add_f32_e32 v64, v65, v112
	v_add_f32_e32 v64, v113, v64
	v_add_f32_e32 v64, v67, v64
	v_add_f32_e32 v64, v68, v64
	v_add_f32_e32 v64, v69, v64
	v_add_f32_e32 v64, v70, v64
	v_add_f32_e32 v64, v71, v64
	v_add_f32_e32 v64, v72, v64
	v_add_f32_e32 v64, v73, v64
	v_add_f32_e32 v64, v74, v64
	v_add_f32_e32 v64, v75, v64
	v_add_f32_e32 v64, v76, v64
	v_add_f32_e32 v64, v77, v64
	v_add_f32_e32 v64, v78, v64
	v_add_f32_e32 v64, v79, v64
	v_add_f32_e32 v64, v161, v64
	v_cvt_pk_bf16_f32 v66, v112, v65
	v_cvt_pk_bf16_f32 v67, v113, v67
	v_cvt_pk_bf16_f32 v68, v68, v69
	v_cvt_pk_bf16_f32 v69, v70, v71
	v_cvt_pk_bf16_f32 v70, v72, v73
	v_cvt_pk_bf16_f32 v71, v74, v75
	v_cvt_pk_bf16_f32 v72, v76, v77
	v_cvt_pk_bf16_f32 v73, v78, v79
	s_nop 0
	v_permlane32_swap_b32_e32 v66, v68
	v_permlane32_swap_b32_e32 v67, v69
	v_permlane32_swap_b32_e32 v70, v72
	v_permlane32_swap_b32_e32 v71, v73
	s_waitcnt lgkmcnt(0)
	s_setprio 1
	v_mfma_f32_32x32x16_bf16 v[48:63], v[66:69], v[80:83], v[48:63]
	v_mfma_f32_32x32x16_bf16 v[32:47], v[66:69], v[88:91], v[32:47]
	v_mfma_f32_32x32x16_bf16 v[16:31], v[66:69], v[96:99], v[16:31]
	v_mfma_f32_32x32x16_bf16 v[0:15], v[66:69], v[104:107], v[0:15]
	v_mfma_f32_32x32x16_bf16 v[48:63], v[70:73], v[84:87], v[48:63]
	v_mfma_f32_32x32x16_bf16 v[32:47], v[70:73], v[92:95], v[32:47]
	v_mfma_f32_32x32x16_bf16 v[16:31], v[70:73], v[100:103], v[16:31]
	v_mfma_f32_32x32x16_bf16 v[0:15], v[70:73], v[108:111], v[0:15]
	s_setprio 0
	v_mbcnt_lo_u32_b32 v66, -1, 0
	v_mbcnt_hi_u32_b32 v66, -1, v66
	v_mov_b32_e32 v67, v64
	v_and_b32_e32 v65, 31, v66
	v_bfe_u32 v66, v66, 5, 1
	v_permlane32_swap_b32_e32 v64, v67
	v_cmp_eq_u32_e32 vcc, 0, v66
	s_and_saveexec_b64 s[2:3], vcc
	s_cbranch_execz .LBB0_1910
	v_lshl_add_u32 v68, v65, 2, s4
	v_add_f32_e32 v64, v64, v67
	ds_write_b32 v68, v64
	s_branch .LBB0_1910
